# GEMM K-loops: per-phase setprio flips removed, one static s_setprio 1 for waves 4-7 (reset at phase end)
# speedup vs baseline: 1.0999x; 1.0057x over previous
; DI int otid() { int t = threadIdx.x; asm volatile("" : "+v"(t)); return t; }
; #define PG8_STAGE(bufoff, gbase, voff) do { _Pragma("unroll") for (int _i = 0; _i < 2; ++_i) \
;     __builtin_amdgcn_global_load_lds((const unsigned*)((const char*)(gbase) + (voff)[_i]), (PG8_LAS unsigned*)(lds + (bufoff) + ldsw + _i * 8192), 16, 0, 0); } while (0)
; #define PG8_WAIT_V(n) asm volatile("s_waitcnt vmcnt(" #n ")" ::: "memory")
; #define PG8_BAR __builtin_amdgcn_s_barrier()
; template <class Epi>
; DI void gemm_phase(PG8_LAS unsigned char* lds, const Gemm g, const StaticOrder& S, const Epi& E) {
;   const int tid = otid(), wid = __builtin_amdgcn_readfirstlane(tid >> 6), lane = tid & 63, wr = wid >> 2, wc = wid & 3, fr = lane & 15, fq = lane >> 4;
;   const int K = g.K, nt = K / BK;
;   unsigned voffA[2], voffB[2];
; #pragma unroll
;   for (int i = 0; i < 2; ++i) { int R, C; stage_rc(tid * 16 + i * 8192, R, C); const int Rb = Epi::PERM ? ((R & ~31) + perm32(R & 31)) : R;
;     voffA[i] = (unsigned)(R * g.lda + C) * 2u; voffB[i] = (unsigned)(Rb * K + C) * 2u; }
;   const size_t kstep = (size_t)(BK * 2);
;   const size_t hstepA = (size_t)HALF * g.lda * 2, hstepB = (size_t)HALF * K * 2;
;   const size_t tstepA = 2 * hstepA, tstepB = 2 * hstepB;
;   const unsigned ldsw = (unsigned)wid * 1024u;
;   const int aoff = lds_byte(wr * 64 + fr, fq * 8), boff = lds_byte(wc * 32 + fr, fq * 8);
;     ...
;   Unit cur, nxt; int ui = 0;
;   if (!S.next(0, cur)) return;
;   f32x4 acc[2][2][4][2];
; #pragma unroll
;   for (int a = 0; a < 2; ++a)
; #pragma unroll
;     for (int b = 0; b < 2; ++b)
; #pragma unroll
;       for (int m = 0; m < 4; ++m)
; #pragma unroll
;         for (int n = 0; n < 2; ++n) acc[a][b][m][n] = (f32x4){0.f, 0.f, 0.f, 0.f};
;   bf16x8 At[4][2], B0[2][2], B1[2][2];
;   const char* cA = (const char*)g.A + (size_t)cur.pm * tstepA; const char* cB = (const char*)g.Bt + (size_t)cur.pn * tstepB;
;   PG8_STAGE(PG8_SB(0, 0), cB, voffB); PG8_STAGE(PG8_SA(0, 0), cA, voffA); PG8_STAGE(PG8_SB(0, 1), cB + hstepB, voffB); PG8_STAGE(PG8_SA(0, 1), cA + hstepA, voffA);
;   if (wr == 1) PG8_BAR;
;   PG8_WAIT_V(4); PG8_BAR;
;   PG8_STAGE(PG8_SB(1, 0), cB + kstep, voffB); PG8_STAGE(PG8_SA(1, 0), cA + kstep, voffA); PG8_STAGE(PG8_SB(1, 1), cB + hstepB + kstep, voffB);
;   PG8_WAIT_V(6); PG8_BAR;
.LBB0_45:
	s_or_b64 exec, exec, s[30:31]
	v_readlane_b32 s30, v252, 6
	v_mov_b32_e32 v4, v200
	v_readlane_b32 s31, v252, 7
	s_waitcnt lgkmcnt(0)
	s_barrier
	s_andn2_b64 vcc, exec, s[30:31]
	v_readfirstlane_b32 s28, v4
	s_cbranch_vccnz .LBB0_57
	v_lshlrev_b32_e32 v0, 4, v4
	v_add_u32_e32 v3, 0x2000, v0
	v_ashrrev_i32_e32 v2, 31, v3
	v_lshrrev_b32_e32 v2, 22, v2
	v_add_u32_e32 v2, v3, v2
	v_ashrrev_i32_e32 v2, 10, v2
	v_lshlrev_b32_e32 v5, 5, v2
	v_and_b32_e32 v6, 32, v5
	v_mul_i32_i24_e32 v5, 0x400, v2
	v_sub_u32_e32 v3, v3, v5
	v_lshrrev_b32_e32 v5, 4, v3
	v_bitop3_b32 v5, v5, v3, 32 bitop3:0x6c
	v_ashrrev_i32_e32 v3, 31, v5
	v_lshrrev_b32_e32 v3, 26, v3
	v_add_u32_e32 v7, v5, v3
	v_ashrrev_i32_e32 v3, 6, v7
	v_and_b32_e32 v7, 0xc0, v7
	v_sub_u32_e32 v5, v5, v7
	v_ashrrev_i16_sdwa v5, v202, sext(v5) dst_sel:DWORD dst_unused:UNUSED_PAD src0_sel:DWORD src1_sel:BYTE_0
	v_lshlrev_b32_e32 v7, 3, v2
	v_bfe_i32 v5, v5, 0, 16
	v_and_b32_e32 v7, 0x1ffff0, v7
	v_add_u32_e32 v6, v6, v5
	v_add_lshl_u32 v7, v3, v7, 11
	v_lshl_add_u32 v130, v6, 1, v7
	v_ashrrev_i32_e32 v6, 31, v4
	v_lshrrev_b32_e32 v6, 26, v6
	v_add_u32_e32 v6, v4, v6
	v_ashrrev_i32_e32 v6, 6, v6
	v_lshlrev_b32_e32 v7, 5, v6
	v_and_b32_e32 v9, 32, v7
	v_bfe_i32 v7, v4, 27, 1
	v_lshrrev_b32_e32 v7, 22, v7
	v_add_u32_e32 v7, v0, v7
	v_and_b32_e32 v7, 0xfffffc00, v7
	v_sub_u32_e32 v0, v0, v7
	v_lshrrev_b32_e32 v7, 4, v0
	v_bitop3_b32 v8, v7, v0, 32 bitop3:0x6c
	v_ashrrev_i32_e32 v0, 31, v0
	v_lshrrev_b32_e32 v0, 26, v0
	v_add_u32_e32 v0, v8, v0
	v_ashrrev_i32_e32 v7, 6, v0
	v_mul_i32_i24_e32 v0, 64, v7
	v_sub_u32_e32 v0, v8, v0
	v_ashrrev_i16_sdwa v0, v202, sext(v0) dst_sel:DWORD dst_unused:UNUSED_PAD src0_sel:DWORD src1_sel:BYTE_0
	v_bfe_i32 v8, v0, 0, 16
	s_ashr_i32 s30, s28, 6
	v_add_u32_e32 v0, v9, v8
	v_lshlrev_b32_e32 v9, 3, v6
	s_lshl_b32 s34, s30, 10
	v_and_b32_e32 v9, 0x1ffff0, v9
	v_add_lshl_u32 v9, v7, v9, 11
	s_add_i32 s37, s34, 0
	v_readlane_b32 s40, v252, 19
	v_lshl_add_u32 v0, v0, 1, v9
	s_add_i32 m0, s37, 0x10000
	v_readlane_b32 s41, v252, 20
	s_add_i32 s62, s37, 0x2000
	s_add_i32 s63, s37, 0x4000
	s_add_i32 s64, s37, 0x6000
	s_ashr_i32 s31, s28, 8
	s_nop 0
	global_load_lds_dwordx4 v0, s[40:41]
	s_add_i32 m0, s37, 0x12000
	s_nop 0
	global_load_lds_dwordx4 v130, s[40:41]
	v_readlane_b32 s40, v252, 15
	s_mov_b32 m0, s37
	v_readlane_b32 s41, v252, 16
	s_nop 4
	global_load_lds_dwordx4 v0, s[40:41]
	s_mov_b32 m0, s62
	s_nop 0
	global_load_lds_dwordx4 v130, s[40:41]
	v_readlane_b32 s40, v252, 13
	s_add_i32 m0, s37, 0x14000
	v_readlane_b32 s41, v252, 14
	s_nop 4
	global_load_lds_dwordx4 v0, s[40:41]
	s_add_i32 m0, s37, 0x16000
	s_cmp_lg_u32 s31, 1
	global_load_lds_dwordx4 v130, s[40:41]
	v_readlane_b32 s40, v252, 17
	s_mov_b32 m0, s63
	v_readlane_b32 s41, v252, 18
	s_nop 4
	global_load_lds_dwordx4 v0, s[40:41]
	s_mov_b32 m0, s64
	s_nop 0
	global_load_lds_dwordx4 v130, s[40:41]
	s_cbranch_scc1 .LBB0_48
	s_barrier
	s_setprio 1

; #define PG8_STAGE(bufoff, gbase, voff) do { _Pragma("unroll") for (int _i = 0; _i < 2; ++_i) \
;     __builtin_amdgcn_global_load_lds((const unsigned*)((const char*)(gbase) + (voff)[_i]), (PG8_LAS unsigned*)(lds + (bufoff) + ldsw + _i * 8192), 16, 0, 0); } while (0)
; #define PG8_LDA(dst, b, h) do { _Pragma("unroll") for (int m = 0; m < 4; ++m) _Pragma("unroll") for (int k = 0; k < 2; ++k) dst[m][k] = *(const PG8_LAS bf16x8*)(lds + PG8_SA(b, h) + aoff + m * 2048 + k * 1024); } while (0)
; #define PG8_LDB(dst, b, h) do { _Pragma("unroll") for (int n = 0; n < 2; ++n) _Pragma("unroll") for (int k = 0; k < 2; ++k) dst[n][k] = *(const PG8_LAS bf16x8*)(lds + PG8_SB(b, h) + boff + n * 2048 + k * 1024); } while (0)
; #define PG8_MMA(ai, bj, At, Bt) do { __builtin_amdgcn_s_setprio(1); _Pragma("unroll") for (int m = 0; m < 4; ++m) _Pragma("unroll") for (int n = 0; n < 2; ++n) _Pragma("unroll") for (int k = 0; k < 2; ++k) \
;     acc[ai][bj][m][n] = __builtin_amdgcn_mfma_f32_16x16x32_bf16(Bt[n][k], At[m][k], acc[ai][bj][m][n], 0, 0, 0); __builtin_amdgcn_s_setprio(0); } while (0)
; #define PG8_WAIT_L(n) asm volatile("s_waitcnt lgkmcnt(" #n ")" ::: "memory")
; #define PG8_BAR __builtin_amdgcn_s_barrier()
; #define PG8_SCHED __builtin_amdgcn_sched_barrier(0)
; template <class Epi>
; DI void gemm_phase(PG8_LAS unsigned char* lds, const Gemm g, const StaticOrder& S, const Epi& E) {
;     ...
;     for (int t = 0; t < nt; t += 2) {
;       const bool last = (t == nt - 2);
;       const char* a1 = cA + (size_t)(t + 1) * kstep;
;       const char* a2 = last ? nA : cA + (size_t)(t + 2) * kstep; const char* b2 = last ? nB : cB + (size_t)(t + 2) * kstep;
;       const char* a3 = a2 + kstep; const char* b3 = b2 + kstep;
;       PG8_LDB(B0, 0, 0); PG8_SCHED; PG8_LDA(At, 0, 0); PG8_STAGE(PG8_SA(1, 1), a1 + hstepA, voffA);
;       PG8_WAIT_L(8); PG8_BAR; PG8_WAIT_L(0); PG8_MMA(0, 0, At, B0); PG8_BAR; PG8_SCHED;
;       PG8_LDB(B1, 0, 1); PG8_STAGE(PG8_SB(0, 0), b2, voffB);
;       PG8_BAR; PG8_WAIT_L(0); PG8_MMA(0, 1, At, B1); PG8_BAR;
;       PG8_LDA(At, 0, 1); PG8_STAGE(PG8_SA(0, 0), a2, voffA);
;       PG8_BAR; PG8_WAIT_L(0); PG8_MMA(1, 0, At, B0); PG8_BAR; PG8_SCHED;
.LBB0_52:
	s_add_u32 s58, s56, 0xfffc0080
	s_addc_u32 s59, s57, -1
	s_add_i32 s77, 0, 0x10000
	v_add_u32_e32 v153, s77, v149
	ds_read_b128 v[144:147], v153
	ds_read_b128 v[154:157], v153 offset:1024
	ds_read_b128 v[158:161], v153 offset:2048
	ds_read_b128 v[162:165], v153 offset:3072
	s_cmp_eq_u32 s76, 12
	s_cselect_b32 s61, s51, s59
	s_cselect_b32 s60, s72, s58
	s_cselect_b32 s59, s31, s75
	s_cselect_b32 s58, s73, s74
	v_lshl_add_u64 v[198:199], s[56:57], 0, v[132:133]
	s_add_i32 m0, s37, 0xc000
	ds_read_b128 v[166:169], v152
	ds_read_b128 v[170:173], v152 offset:1024
	ds_read_b128 v[174:177], v152 offset:2048
	ds_read_b128 v[178:181], v152 offset:3072
	ds_read_b128 v[182:185], v152 offset:4096
	ds_read_b128 v[186:189], v152 offset:5120
	ds_read_b128 v[190:193], v152 offset:6144
	ds_read_b128 v[194:197], v152 offset:7168
	global_load_lds_dwordx4 v[198:199], off
	v_lshl_add_u64 v[198:199], s[56:57], 0, v[142:143]
	s_add_i32 m0, s37, 0xe000
	s_nop 0
	global_load_lds_dwordx4 v[198:199], off
	s_waitcnt lgkmcnt(8)
	s_barrier
	s_waitcnt lgkmcnt(0)
	s_waitcnt lgkmcnt(0)
	v_mfma_f32_16x16x32_bf16 v[126:129], v[144:147], v[166:169], v[126:129]
	v_mfma_f32_16x16x32_bf16 v[122:125], v[158:161], v[166:169], v[122:125]
	v_mfma_f32_16x16x32_bf16 v[110:113], v[144:147], v[174:177], v[110:113]
	v_mfma_f32_16x16x32_bf16 v[106:109], v[158:161], v[174:177], v[106:109]
	v_mfma_f32_16x16x32_bf16 v[94:97], v[144:147], v[182:185], v[94:97]
	v_mfma_f32_16x16x32_bf16 v[90:93], v[158:161], v[182:185], v[90:93]
	v_mfma_f32_16x16x32_bf16 v[78:81], v[144:147], v[190:193], v[78:81]
	v_mfma_f32_16x16x32_bf16 v[74:77], v[158:161], v[190:193], v[74:77]
	v_mfma_f32_16x16x32_bf16 v[126:129], v[154:157], v[170:173], v[126:129]
	v_mfma_f32_16x16x32_bf16 v[122:125], v[162:165], v[170:173], v[122:125]
	v_mfma_f32_16x16x32_bf16 v[110:113], v[154:157], v[178:181], v[110:113]
	v_mfma_f32_16x16x32_bf16 v[106:109], v[162:165], v[178:181], v[106:109]
	v_mfma_f32_16x16x32_bf16 v[94:97], v[154:157], v[186:189], v[94:97]
	v_mfma_f32_16x16x32_bf16 v[90:93], v[162:165], v[186:189], v[90:93]
	v_mfma_f32_16x16x32_bf16 v[78:81], v[154:157], v[194:197], v[78:81]
	v_mfma_f32_16x16x32_bf16 v[74:77], v[162:165], v[194:197], v[74:77]
	s_barrier
	s_add_i32 s80, 0, 0x14000
	s_add_i32 s77, s77, s34
	v_add_u32_e32 v153, s80, v149
	v_lshl_add_u64 v[198:199], s[58:59], 0, v[0:1]
	s_mov_b32 m0, s77
	ds_read_b128 v[222:225], v153
	ds_read_b128 v[226:229], v153 offset:1024
	ds_read_b128 v[230:233], v153 offset:2048
	ds_read_b128 v[234:237], v153 offset:3072
	global_load_lds_dwordx4 v[198:199], off
	v_lshl_add_u64 v[238:239], s[58:59], 0, v[130:131]
	s_add_i32 m0, s77, 0x2000
	s_nop 0
	global_load_lds_dwordx4 v[238:239], off
	s_barrier
	s_waitcnt lgkmcnt(0)
	s_waitcnt lgkmcnt(0)
	v_mfma_f32_16x16x32_bf16 v[118:121], v[222:225], v[166:169], v[118:121]
	v_mfma_f32_16x16x32_bf16 v[114:117], v[230:233], v[166:169], v[114:117]
	v_mfma_f32_16x16x32_bf16 v[102:105], v[222:225], v[174:177], v[102:105]
	v_mfma_f32_16x16x32_bf16 v[98:101], v[230:233], v[174:177], v[98:101]
	v_mfma_f32_16x16x32_bf16 v[86:89], v[222:225], v[182:185], v[86:89]
	v_mfma_f32_16x16x32_bf16 v[82:85], v[230:233], v[182:185], v[82:85]
	v_mfma_f32_16x16x32_bf16 v[70:73], v[222:225], v[190:193], v[70:73]
	v_mfma_f32_16x16x32_bf16 v[66:69], v[230:233], v[190:193], v[66:69]
	v_mfma_f32_16x16x32_bf16 v[118:121], v[226:229], v[170:173], v[118:121]
	v_mfma_f32_16x16x32_bf16 v[114:117], v[234:237], v[170:173], v[114:117]
	v_mfma_f32_16x16x32_bf16 v[102:105], v[226:229], v[178:181], v[102:105]
	v_mfma_f32_16x16x32_bf16 v[98:101], v[234:237], v[178:181], v[98:101]
	v_mfma_f32_16x16x32_bf16 v[86:89], v[226:229], v[186:189], v[86:89]
	v_mfma_f32_16x16x32_bf16 v[82:85], v[234:237], v[186:189], v[82:85]
	v_mfma_f32_16x16x32_bf16 v[70:73], v[226:229], v[194:197], v[70:73]
	v_mfma_f32_16x16x32_bf16 v[66:69], v[234:237], v[194:197], v[66:69]
	s_mov_b32 m0, s37
	v_lshl_add_u64 v[240:241], s[60:61], 0, v[0:1]
	s_barrier
	ds_read_b128 v[166:169], v152 offset:16384
	ds_read_b128 v[170:173], v152 offset:17408
	ds_read_b128 v[174:177], v152 offset:18432
	ds_read_b128 v[178:181], v152 offset:19456
	ds_read_b128 v[182:185], v152 offset:20480
	ds_read_b128 v[186:189], v152 offset:21504
	ds_read_b128 v[190:193], v152 offset:22528
	ds_read_b128 v[194:197], v152 offset:23552
	global_load_lds_dwordx4 v[240:241], off
	v_lshl_add_u64 v[242:243], s[60:61], 0, v[130:131]
	s_mov_b32 m0, s62
	s_nop 0
	global_load_lds_dwordx4 v[242:243], off
	s_barrier
	s_waitcnt lgkmcnt(0)
	s_waitcnt lgkmcnt(0)
	v_mfma_f32_16x16x32_bf16 v[62:65], v[144:147], v[166:169], v[62:65]
	v_mfma_f32_16x16x32_bf16 v[58:61], v[158:161], v[166:169], v[58:61]
	v_mfma_f32_16x16x32_bf16 v[46:49], v[144:147], v[174:177], v[46:49]
	v_mfma_f32_16x16x32_bf16 v[42:45], v[158:161], v[174:177], v[42:45]
	v_mfma_f32_16x16x32_bf16 v[30:33], v[144:147], v[182:185], v[30:33]
	v_mfma_f32_16x16x32_bf16 v[26:29], v[158:161], v[182:185], v[26:29]
	v_mfma_f32_16x16x32_bf16 v[14:17], v[144:147], v[190:193], v[14:17]
	v_mfma_f32_16x16x32_bf16 v[10:13], v[158:161], v[190:193], v[10:13]
	v_mfma_f32_16x16x32_bf16 v[62:65], v[154:157], v[170:173], v[62:65]
	v_mfma_f32_16x16x32_bf16 v[58:61], v[162:165], v[170:173], v[58:61]
	v_mfma_f32_16x16x32_bf16 v[46:49], v[154:157], v[178:181], v[46:49]
	v_mfma_f32_16x16x32_bf16 v[42:45], v[162:165], v[178:181], v[42:45]
	v_mfma_f32_16x16x32_bf16 v[30:33], v[154:157], v[186:189], v[30:33]
	v_mfma_f32_16x16x32_bf16 v[26:29], v[162:165], v[186:189], v[26:29]
	v_mfma_f32_16x16x32_bf16 v[14:17], v[154:157], v[194:197], v[14:17]
	v_mfma_f32_16x16x32_bf16 v[10:13], v[162:165], v[194:197], v[10:13]
	s_barrier
; #define PG8_STAGE(bufoff, gbase, voff) do { _Pragma("unroll") for (int _i = 0; _i < 2; ++_i) \
;     __builtin_amdgcn_global_load_lds((const unsigned*)((const char*)(gbase) + (voff)[_i]), (PG8_LAS unsigned*)(lds + (bufoff) + ldsw + _i * 8192), 16, 0, 0); } while (0)
; #define PG8_LDA(dst, b, h) do { _Pragma("unroll") for (int m = 0; m < 4; ++m) _Pragma("unroll") for (int k = 0; k < 2; ++k) dst[m][k] = *(const PG8_LAS bf16x8*)(lds + PG8_SA(b, h) + aoff + m * 2048 + k * 1024); } while (0)
; #define PG8_LDB(dst, b, h) do { _Pragma("unroll") for (int n = 0; n < 2; ++n) _Pragma("unroll") for (int k = 0; k < 2; ++k) dst[n][k] = *(const PG8_LAS bf16x8*)(lds + PG8_SB(b, h) + boff + n * 2048 + k * 1024); } while (0)
; #define PG8_MMA(ai, bj, At, Bt) do { __builtin_amdgcn_s_setprio(1); _Pragma("unroll") for (int m = 0; m < 4; ++m) _Pragma("unroll") for (int n = 0; n < 2; ++n) _Pragma("unroll") for (int k = 0; k < 2; ++k) \
;     acc[ai][bj][m][n] = __builtin_amdgcn_mfma_f32_16x16x32_bf16(Bt[n][k], At[m][k], acc[ai][bj][m][n], 0, 0, 0); __builtin_amdgcn_s_setprio(0); } while (0)
; #define PG8_WAIT_V(n) asm volatile("s_waitcnt vmcnt(" #n ")" ::: "memory")
; #define PG8_WAIT_L(n) asm volatile("s_waitcnt lgkmcnt(" #n ")" ::: "memory")
; #define PG8_BAR __builtin_amdgcn_s_barrier()
; #define PG8_SCHED __builtin_amdgcn_sched_barrier(0)
; template <class Epi>
; DI void gemm_phase(PG8_LAS unsigned char* lds, const Gemm g, const StaticOrder& S, const Epi& E) {
;     ...
;       PG8_STAGE(PG8_SB(0, 1), b2 + hstepB, voffB);
;       PG8_WAIT_V(6); PG8_BAR; PG8_MMA(1, 1, At, B1); PG8_BAR;
;       PG8_LDB(B0, 1, 0); PG8_SCHED; PG8_LDA(At, 1, 0); PG8_STAGE(PG8_SA(0, 1), a2 + hstepA, voffA);
;       PG8_WAIT_L(8); PG8_BAR; PG8_WAIT_L(0); PG8_MMA(0, 0, At, B0); PG8_BAR; PG8_SCHED;
;       PG8_LDB(B1, 1, 1); PG8_STAGE(PG8_SB(1, 0), b3, voffB);
;       PG8_BAR; PG8_WAIT_L(0); PG8_MMA(0, 1, At, B1); PG8_BAR;
;       PG8_LDA(At, 1, 1); PG8_STAGE(PG8_SA(1, 0), a3, voffA);
;       PG8_BAR; PG8_WAIT_L(0); PG8_MMA(1, 0, At, B0); PG8_BAR; PG8_SCHED;
	s_add_u32 s78, s58, 0x40000
	s_addc_u32 s79, s59, 0
	s_add_i32 s77, s80, s34
	v_lshl_add_u64 v[144:145], s[78:79], 0, v[0:1]
	s_mov_b32 m0, s77
	s_nop 0
	global_load_lds_dwordx4 v[144:145], off
	v_lshl_add_u64 v[144:145], s[78:79], 0, v[130:131]
	s_add_i32 m0, s77, 0x2000
	s_nop 0
	global_load_lds_dwordx4 v[144:145], off
	s_waitcnt vmcnt(6)
	s_barrier
	v_mfma_f32_16x16x32_bf16 v[54:57], v[222:225], v[166:169], v[54:57]
	v_mfma_f32_16x16x32_bf16 v[50:53], v[230:233], v[166:169], v[50:53]
	v_mfma_f32_16x16x32_bf16 v[38:41], v[222:225], v[174:177], v[38:41]
	v_mfma_f32_16x16x32_bf16 v[34:37], v[230:233], v[174:177], v[34:37]
	v_mfma_f32_16x16x32_bf16 v[22:25], v[222:225], v[182:185], v[22:25]
	v_mfma_f32_16x16x32_bf16 v[18:21], v[230:233], v[182:185], v[18:21]
	v_mfma_f32_16x16x32_bf16 v[6:9], v[222:225], v[190:193], v[6:9]
	v_mfma_f32_16x16x32_bf16 v[2:5], v[230:233], v[190:193], v[2:5]
	v_mfma_f32_16x16x32_bf16 v[54:57], v[226:229], v[170:173], v[54:57]
	v_mfma_f32_16x16x32_bf16 v[50:53], v[234:237], v[170:173], v[50:53]
	v_mfma_f32_16x16x32_bf16 v[38:41], v[226:229], v[178:181], v[38:41]
	v_mfma_f32_16x16x32_bf16 v[34:37], v[234:237], v[178:181], v[34:37]
	v_mfma_f32_16x16x32_bf16 v[22:25], v[226:229], v[186:189], v[22:25]
	v_mfma_f32_16x16x32_bf16 v[18:21], v[234:237], v[186:189], v[18:21]
	v_mfma_f32_16x16x32_bf16 v[6:9], v[226:229], v[194:197], v[6:9]
	v_mfma_f32_16x16x32_bf16 v[2:5], v[234:237], v[194:197], v[2:5]
	s_add_i32 s77, 0, 0x18000
	v_add_u32_e32 v153, s77, v149
	s_barrier
	ds_read_b128 v[144:147], v153
	ds_read_b128 v[154:157], v153 offset:1024
	ds_read_b128 v[158:161], v153 offset:2048
	ds_read_b128 v[162:165], v153 offset:3072
	s_add_u32 s60, s60, 0x40000
	s_addc_u32 s61, s61, 0
	s_mov_b32 m0, s63
	v_lshl_add_u64 v[222:223], s[60:61], 0, v[0:1]
	ds_read_b128 v[166:169], v152 offset:32768
	ds_read_b128 v[170:173], v152 offset:33792
	ds_read_b128 v[174:177], v152 offset:34816
	ds_read_b128 v[178:181], v152 offset:35840
	ds_read_b128 v[182:185], v152 offset:36864
	ds_read_b128 v[186:189], v152 offset:37888
	ds_read_b128 v[190:193], v152 offset:38912
	ds_read_b128 v[194:197], v152 offset:39936
	global_load_lds_dwordx4 v[222:223], off
	v_lshl_add_u64 v[222:223], s[60:61], 0, v[130:131]
	s_mov_b32 m0, s64
	s_nop 0
	global_load_lds_dwordx4 v[222:223], off
	s_waitcnt lgkmcnt(8)
	s_barrier
	s_waitcnt lgkmcnt(0)
	s_waitcnt lgkmcnt(0)
	v_mfma_f32_16x16x32_bf16 v[126:129], v[144:147], v[166:169], v[126:129]
	v_mfma_f32_16x16x32_bf16 v[122:125], v[158:161], v[166:169], v[122:125]
	v_mfma_f32_16x16x32_bf16 v[110:113], v[144:147], v[174:177], v[110:113]
	v_mfma_f32_16x16x32_bf16 v[106:109], v[158:161], v[174:177], v[106:109]
	v_mfma_f32_16x16x32_bf16 v[94:97], v[144:147], v[182:185], v[94:97]
	v_mfma_f32_16x16x32_bf16 v[90:93], v[158:161], v[182:185], v[90:93]
	v_mfma_f32_16x16x32_bf16 v[78:81], v[144:147], v[190:193], v[78:81]
	v_mfma_f32_16x16x32_bf16 v[74:77], v[158:161], v[190:193], v[74:77]
	v_mfma_f32_16x16x32_bf16 v[126:129], v[154:157], v[170:173], v[126:129]
	v_mfma_f32_16x16x32_bf16 v[122:125], v[162:165], v[170:173], v[122:125]
	v_mfma_f32_16x16x32_bf16 v[110:113], v[154:157], v[178:181], v[110:113]
	v_mfma_f32_16x16x32_bf16 v[106:109], v[162:165], v[178:181], v[106:109]
	v_mfma_f32_16x16x32_bf16 v[94:97], v[154:157], v[186:189], v[94:97]
	v_mfma_f32_16x16x32_bf16 v[90:93], v[162:165], v[186:189], v[90:93]
	v_mfma_f32_16x16x32_bf16 v[78:81], v[154:157], v[194:197], v[78:81]
	v_mfma_f32_16x16x32_bf16 v[74:77], v[162:165], v[194:197], v[74:77]
	s_barrier
	s_add_i32 s60, 0, 0x1c000
	s_add_i32 s61, s77, s34
	v_add_u32_e32 v153, s60, v149
	v_lshl_add_u64 v[198:199], v[198:199], 0, s[86:87]
	s_mov_b32 m0, s61
	ds_read_b128 v[222:225], v153
	ds_read_b128 v[226:229], v153 offset:1024
	ds_read_b128 v[230:233], v153 offset:2048
	ds_read_b128 v[234:237], v153 offset:3072
	global_load_lds_dwordx4 v[198:199], off
	v_lshl_add_u64 v[198:199], v[238:239], 0, s[86:87]
	s_add_i32 m0, s61, 0x2000
	s_nop 0
	global_load_lds_dwordx4 v[198:199], off
	s_barrier
	s_waitcnt lgkmcnt(0)
	s_waitcnt lgkmcnt(0)
	v_mfma_f32_16x16x32_bf16 v[118:121], v[222:225], v[166:169], v[118:121]
	v_mfma_f32_16x16x32_bf16 v[114:117], v[230:233], v[166:169], v[114:117]
	v_mfma_f32_16x16x32_bf16 v[102:105], v[222:225], v[174:177], v[102:105]
	v_mfma_f32_16x16x32_bf16 v[98:101], v[230:233], v[174:177], v[98:101]
	v_mfma_f32_16x16x32_bf16 v[86:89], v[222:225], v[182:185], v[86:89]
	v_mfma_f32_16x16x32_bf16 v[82:85], v[230:233], v[182:185], v[82:85]
	v_mfma_f32_16x16x32_bf16 v[70:73], v[222:225], v[190:193], v[70:73]
	v_mfma_f32_16x16x32_bf16 v[66:69], v[230:233], v[190:193], v[66:69]
	v_mfma_f32_16x16x32_bf16 v[118:121], v[226:229], v[170:173], v[118:121]
	v_mfma_f32_16x16x32_bf16 v[114:117], v[234:237], v[170:173], v[114:117]
	v_mfma_f32_16x16x32_bf16 v[102:105], v[226:229], v[178:181], v[102:105]
	v_mfma_f32_16x16x32_bf16 v[98:101], v[234:237], v[178:181], v[98:101]
	v_mfma_f32_16x16x32_bf16 v[86:89], v[226:229], v[186:189], v[86:89]
	v_mfma_f32_16x16x32_bf16 v[82:85], v[234:237], v[186:189], v[82:85]
	v_mfma_f32_16x16x32_bf16 v[70:73], v[226:229], v[194:197], v[70:73]
	v_mfma_f32_16x16x32_bf16 v[66:69], v[234:237], v[194:197], v[66:69]
	s_mov_b32 m0, s65
	v_lshl_add_u64 v[198:199], v[240:241], 0, s[86:87]
	s_barrier
	ds_read_b128 v[166:169], v152 offset:49152
	ds_read_b128 v[170:173], v152 offset:50176
	ds_read_b128 v[174:177], v152 offset:51200
	ds_read_b128 v[178:181], v152 offset:52224
	ds_read_b128 v[182:185], v152 offset:53248
	ds_read_b128 v[186:189], v152 offset:54272
	ds_read_b128 v[190:193], v152 offset:55296
	ds_read_b128 v[194:197], v152 offset:56320
	global_load_lds_dwordx4 v[198:199], off
	v_lshl_add_u64 v[198:199], v[242:243], 0, s[86:87]
	s_mov_b32 m0, s66
	s_nop 0
	global_load_lds_dwordx4 v[198:199], off
	s_barrier
; DI unsigned pk2(float lo, float hi) { f32x2 v = {lo, hi}; bf2_t r = __builtin_convertvector(v, bf2_t); return __builtin_bit_cast(unsigned, r); }
; DI float silu(float x) { return x * __builtin_amdgcn_rcpf(1.f + __expf(-x)); }
; #define PG8_LAS __attribute__((address_space(3)))
; #define PG8_STAGE(bufoff, gbase, voff) do { _Pragma("unroll") for (int _i = 0; _i < 2; ++_i) \
;     __builtin_amdgcn_global_load_lds((const unsigned*)((const char*)(gbase) + (voff)[_i]), (PG8_LAS unsigned*)(lds + (bufoff) + ldsw + _i * 8192), 16, 0, 0); } while (0)
; #define PG8_MMA(ai, bj, At, Bt) do { __builtin_amdgcn_s_setprio(1); _Pragma("unroll") for (int m = 0; m < 4; ++m) _Pragma("unroll") for (int n = 0; n < 2; ++n) _Pragma("unroll") for (int k = 0; k < 2; ++k) \
;     acc[ai][bj][m][n] = __builtin_amdgcn_mfma_f32_16x16x32_bf16(Bt[n][k], At[m][k], acc[ai][bj][m][n], 0, 0, 0); __builtin_amdgcn_s_setprio(0); } while (0)
; #define PG8_WAIT_V(n) asm volatile("s_waitcnt vmcnt(" #n ")" ::: "memory")
; #define PG8_BAR __builtin_amdgcn_s_barrier()
;   DI void operator()(const f32x4 (&acc)[2][2][4][2], const Unit& u, int wr, int wc, int fr, int fq, const PG8_LAS float* sR) const {
;     const int row0 = u.pm * BM + wr * 64 + fr, j0 = (u.pn * BM + wc * 32) / 2 + 4 * fq;
; #pragma unroll
;     for (int ai = 0; ai < 2; ++ai)
; #pragma unroll
;       for (int m = 0; m < 4; ++m) {
;         bf16_t* rowp = Hd + (size_t)(row0 + ai * HALF + m * 16) * 2816 + j0;
;         const float rs = sR[ai * 128 + m * 16 + fr];
; #pragma unroll
;         for (int bj = 0; bj < 2; ++bj) {
;           const f32x4 g = acc[ai][bj][m][0] * rs, up = acc[ai][bj][m][1] * rs;
;           u32x2 o; o[0] = pk2(silu(g[0]) * up[0], silu(g[1]) * up[1]); o[1] = pk2(silu(g[2]) * up[2], silu(g[3]) * up[3]);
; template <class Epi>
; DI void gemm_phase(PG8_LAS unsigned char* lds, const Gemm g, const StaticOrder& S, const Epi& E) {
;     ...
;       PG8_STAGE(PG8_SB(1, 1), b3 + hstepB, voffB);
;       PG8_WAIT_V(6); PG8_BAR; PG8_MMA(1, 1, At, B1); PG8_BAR;
	s_waitcnt lgkmcnt(0)
	s_waitcnt lgkmcnt(0)
	v_mfma_f32_16x16x32_bf16 v[62:65], v[144:147], v[166:169], v[62:65]
	v_mfma_f32_16x16x32_bf16 v[58:61], v[158:161], v[166:169], v[58:61]
	v_mfma_f32_16x16x32_bf16 v[46:49], v[144:147], v[174:177], v[46:49]
	v_mfma_f32_16x16x32_bf16 v[42:45], v[158:161], v[174:177], v[42:45]
	v_mfma_f32_16x16x32_bf16 v[30:33], v[144:147], v[182:185], v[30:33]
	v_mfma_f32_16x16x32_bf16 v[26:29], v[158:161], v[182:185], v[26:29]
	v_mfma_f32_16x16x32_bf16 v[14:17], v[144:147], v[190:193], v[14:17]
	v_mfma_f32_16x16x32_bf16 v[10:13], v[158:161], v[190:193], v[10:13]
	v_mfma_f32_16x16x32_bf16 v[62:65], v[154:157], v[170:173], v[62:65]
	v_mfma_f32_16x16x32_bf16 v[58:61], v[162:165], v[170:173], v[58:61]
	v_mfma_f32_16x16x32_bf16 v[46:49], v[154:157], v[178:181], v[46:49]
	v_mfma_f32_16x16x32_bf16 v[42:45], v[162:165], v[178:181], v[42:45]
	v_mfma_f32_16x16x32_bf16 v[30:33], v[154:157], v[186:189], v[30:33]
	v_mfma_f32_16x16x32_bf16 v[26:29], v[162:165], v[186:189], v[26:29]
	v_mfma_f32_16x16x32_bf16 v[14:17], v[154:157], v[194:197], v[14:17]
	v_mfma_f32_16x16x32_bf16 v[10:13], v[162:165], v[194:197], v[10:13]
	s_barrier
	s_add_u32 s58, s58, 0x40080
	s_addc_u32 s59, s59, 0
	s_add_i32 s60, s60, s34
	v_lshl_add_u64 v[144:145], s[58:59], 0, v[0:1]
	s_mov_b32 m0, s60
	s_nop 0
	global_load_lds_dwordx4 v[144:145], off
	v_lshl_add_u64 v[144:145], s[58:59], 0, v[130:131]
	s_add_i32 m0, s60, 0x2000
	s_nop 0
	global_load_lds_dwordx4 v[144:145], off
	s_waitcnt vmcnt(6)
	s_barrier
	v_mfma_f32_16x16x32_bf16 v[54:57], v[222:225], v[166:169], v[54:57]
	v_mfma_f32_16x16x32_bf16 v[50:53], v[230:233], v[166:169], v[50:53]
	v_mfma_f32_16x16x32_bf16 v[38:41], v[222:225], v[174:177], v[38:41]
	v_mfma_f32_16x16x32_bf16 v[34:37], v[230:233], v[174:177], v[34:37]
	v_mfma_f32_16x16x32_bf16 v[22:25], v[222:225], v[182:185], v[22:25]
	v_mfma_f32_16x16x32_bf16 v[18:21], v[230:233], v[182:185], v[18:21]
	v_mfma_f32_16x16x32_bf16 v[6:9], v[222:225], v[190:193], v[6:9]
	v_mfma_f32_16x16x32_bf16 v[2:5], v[230:233], v[190:193], v[2:5]
	v_mfma_f32_16x16x32_bf16 v[54:57], v[226:229], v[170:173], v[54:57]
	v_mfma_f32_16x16x32_bf16 v[50:53], v[234:237], v[170:173], v[50:53]
	v_mfma_f32_16x16x32_bf16 v[38:41], v[226:229], v[178:181], v[38:41]
	v_mfma_f32_16x16x32_bf16 v[34:37], v[234:237], v[178:181], v[34:37]
	v_mfma_f32_16x16x32_bf16 v[22:25], v[226:229], v[186:189], v[22:25]
	v_mfma_f32_16x16x32_bf16 v[18:21], v[234:237], v[186:189], v[18:21]
	v_mfma_f32_16x16x32_bf16 v[6:9], v[226:229], v[194:197], v[6:9]
	v_mfma_f32_16x16x32_bf16 v[2:5], v[234:237], v[194:197], v[2:5]
	s_add_i32 s76, s76, 2
	s_add_u32 s56, s56, 0x100
	s_addc_u32 s57, s57, 0
	s_add_u32 s74, s74, 0x100
	s_addc_u32 s75, s75, 0
	s_cmp_gt_u32 s76, 13
	s_barrier
	s_cbranch_scc0 .LBB0_52
	v_lshl_add_u32 v154, s69, 10, v150
	ds_read2_b32 v[158:159], v154 offset1:16
	ds_read2_b32 v[160:161], v154 offset0:32 offset1:48
	s_lshl_b32 s31, s70, 8
	s_or_b32 s31, s31, s67
	s_ashr_i32 s31, s31, 1
	v_readlane_b32 s18, v253, 30
	v_readlane_b32 s19, v253, 31
	v_or_b32_e32 v146, s31, v151
	v_lshl_add_u32 v153, s71, 8, v148
	v_ashrrev_i32_e32 v147, 31, v146
	s_movk_i32 s4, 0x1600
	v_mov_b64_e32 v[144:145], s[18:19]
	v_lshlrev_b64 v[146:147], 1, v[146:147]
	v_mad_i64_i32 v[156:157], s[56:57], v153, s4, v[144:145]
	v_and_b32_e32 v144, 4, v151
	v_mul_u32_u24_e32 v144, 30, v144
	v_mov_b32_e32 v145, 0
	v_lshl_add_u64 v[156:157], v[156:157], 0, v[146:147]
	s_mov_b32 s70, s30
	s_mov_b32 s71, s50
	s_mov_b64 s[58:59], s[54:55]
	v_lshl_add_u64 v[156:157], v[156:157], 0, v[144:145]
	v_readlane_b32 s5, v253, 17
	v_readlane_b32 s6, v253, 18
	v_readlane_b32 s7, v253, 19
	v_readlane_b32 s8, v253, 20
	v_readlane_b32 s9, v253, 21
	v_readlane_b32 s10, v253, 22
	v_readlane_b32 s11, v253, 23
	v_readlane_b32 s12, v253, 24
	v_readlane_b32 s13, v253, 25
	v_readlane_b32 s14, v253, 26
	v_readlane_b32 s15, v253, 27
	v_readlane_b32 s16, v253, 28
	v_readlane_b32 s17, v253, 29
	s_mov_b32 s56, 0x16000
	s_mov_b32 s57, 0
	s_waitcnt lgkmcnt(0)
	v_pk_mul_f32 v[126:127], v[126:127], v[158:159] op_sel_hi:[1,0]
	v_pk_mul_f32 v[128:129], v[128:129], v[158:159] op_sel_hi:[1,0]
	v_pk_mul_f32 v[122:123], v[122:123], v[158:159] op_sel_hi:[1,0]
	v_pk_mul_f32 v[124:125], v[124:125], v[158:159] op_sel_hi:[1,0]
	v_mul_f32_e32 v144, 0xbfb8aa3b, v126
	v_mul_f32_e32 v145, 0xbfb8aa3b, v127
	v_mul_f32_e32 v146, 0xbfb8aa3b, v128
	v_mul_f32_e32 v147, 0xbfb8aa3b, v129
	v_exp_f32_e32 v144, v144
	v_exp_f32_e32 v145, v145
	v_exp_f32_e32 v146, v146
	v_exp_f32_e32 v147, v147
	v_add_f32_e32 v144, 1.0, v144
	v_add_f32_e32 v145, 1.0, v145
	v_add_f32_e32 v146, 1.0, v146
	v_add_f32_e32 v147, 1.0, v147
	v_rcp_f32_e32 v144, v144
	v_rcp_f32_e32 v145, v145
	v_rcp_f32_e32 v146, v146
	v_rcp_f32_e32 v147, v147
	v_pk_mul_f32 v[126:127], v[126:127], v[144:145]
	v_pk_mul_f32 v[128:129], v[128:129], v[146:147]
	v_pk_mul_f32 v[126:127], v[126:127], v[122:123]
	v_pk_mul_f32 v[128:129], v[128:129], v[124:125]
	v_cvt_pk_bf16_f32 v122, v126, v127
	v_cvt_pk_bf16_f32 v123, v128, v129
	v_pk_mul_f32 v[118:119], v[118:119], v[158:159] op_sel_hi:[1,0]
	v_pk_mul_f32 v[120:121], v[120:121], v[158:159] op_sel_hi:[1,0]
	v_pk_mul_f32 v[114:115], v[114:115], v[158:159] op_sel_hi:[1,0]
	v_pk_mul_f32 v[116:117], v[116:117], v[158:159] op_sel_hi:[1,0]
	v_pk_mul_f32 v[110:111], v[110:111], v[158:159] op_sel:[0,1]
	v_pk_mul_f32 v[112:113], v[112:113], v[158:159] op_sel:[0,1]
	v_pk_mul_f32 v[106:107], v[106:107], v[158:159] op_sel:[0,1]
	v_pk_mul_f32 v[108:109], v[108:109], v[158:159] op_sel:[0,1]
	v_mul_f32_e32 v144, 0xbfb8aa3b, v118
	v_mul_f32_e32 v145, 0xbfb8aa3b, v119
	v_mul_f32_e32 v146, 0xbfb8aa3b, v120
; DI unsigned pk2(float lo, float hi) { f32x2 v = {lo, hi}; bf2_t r = __builtin_convertvector(v, bf2_t); return __builtin_bit_cast(unsigned, r); }
; DI float silu(float x) { return x * __builtin_amdgcn_rcpf(1.f + __expf(-x)); }
;   DI void operator()(const f32x4 (&acc)[2][2][4][2], const Unit& u, int wr, int wc, int fr, int fq, const PG8_LAS float* sR) const {
;     ...
;     for (int ai = 0; ai < 2; ++ai)
; #pragma unroll
;       for (int m = 0; m < 4; ++m) {
;         bf16_t* rowp = Hd + (size_t)(row0 + ai * HALF + m * 16) * 2816 + j0;
;         const float rs = sR[ai * 128 + m * 16 + fr];
; #pragma unroll
;         for (int bj = 0; bj < 2; ++bj) {
;           const f32x4 g = acc[ai][bj][m][0] * rs, up = acc[ai][bj][m][1] * rs;
;           u32x2 o; o[0] = pk2(silu(g[0]) * up[0], silu(g[1]) * up[1]); o[1] = pk2(silu(g[2]) * up[2], silu(g[3]) * up[3]);
;           *(u32x2*)(rowp + bj * (HALF / 2)) = o;
;         }
	v_mul_f32_e32 v147, 0xbfb8aa3b, v121
	v_mul_f32_e32 v126, 0xbfb8aa3b, v110
	v_mul_f32_e32 v127, 0xbfb8aa3b, v111
	v_mul_f32_e32 v128, 0xbfb8aa3b, v112
	v_mul_f32_e32 v129, 0xbfb8aa3b, v113
	v_exp_f32_e32 v144, v144
	v_exp_f32_e32 v145, v145
	v_exp_f32_e32 v146, v146
	v_exp_f32_e32 v147, v147
	v_exp_f32_e32 v126, v126
	v_exp_f32_e32 v127, v127
	v_exp_f32_e32 v128, v128
	v_exp_f32_e32 v129, v129
	v_add_f32_e32 v144, 1.0, v144
	v_add_f32_e32 v145, 1.0, v145
	v_add_f32_e32 v146, 1.0, v146
	v_add_f32_e32 v147, 1.0, v147
	v_add_f32_e32 v126, 1.0, v126
	v_add_f32_e32 v127, 1.0, v127
	v_add_f32_e32 v128, 1.0, v128
	v_add_f32_e32 v129, 1.0, v129
	v_rcp_f32_e32 v144, v144
	v_rcp_f32_e32 v145, v145
	v_rcp_f32_e32 v146, v146
	v_rcp_f32_e32 v147, v147
	v_rcp_f32_e32 v126, v126
	v_rcp_f32_e32 v127, v127
	v_rcp_f32_e32 v128, v128
	v_rcp_f32_e32 v129, v129
	v_pk_mul_f32 v[118:119], v[118:119], v[144:145]
	v_pk_mul_f32 v[120:121], v[120:121], v[146:147]
	v_pk_mul_f32 v[110:111], v[110:111], v[126:127]
	v_pk_mul_f32 v[112:113], v[112:113], v[128:129]
	v_pk_mul_f32 v[118:119], v[118:119], v[114:115]
	v_pk_mul_f32 v[120:121], v[120:121], v[116:117]
	v_pk_mul_f32 v[110:111], v[110:111], v[106:107]
	v_pk_mul_f32 v[112:113], v[112:113], v[108:109]
	v_cvt_pk_bf16_f32 v124, v118, v119
	v_cvt_pk_bf16_f32 v125, v120, v121
	v_cvt_pk_bf16_f32 v106, v110, v111
	v_cvt_pk_bf16_f32 v107, v112, v113
	s_nop 1
	v_permlane16_swap_b32_e32 v122, v124
	v_permlane16_swap_b32_e32 v123, v125
	global_store_dwordx4 v[156:157], v[122:125], off
	v_lshl_add_u64 v[156:157], v[156:157], 0, s[56:57]
	ds_read2_b32 v[118:119], v154 offset0:128 offset1:144
	ds_read2_b32 v[120:121], v154 offset0:160 offset1:176
	v_pk_mul_f32 v[102:103], v[102:103], v[158:159] op_sel:[0,1]
	v_pk_mul_f32 v[104:105], v[104:105], v[158:159] op_sel:[0,1]
	v_pk_mul_f32 v[98:99], v[98:99], v[158:159] op_sel:[0,1]
	v_pk_mul_f32 v[100:101], v[100:101], v[158:159] op_sel:[0,1]
	v_pk_mul_f32 v[94:95], v[94:95], v[160:161] op_sel_hi:[1,0]
	v_pk_mul_f32 v[96:97], v[96:97], v[160:161] op_sel_hi:[1,0]
	v_pk_mul_f32 v[90:91], v[90:91], v[160:161] op_sel_hi:[1,0]
	v_pk_mul_f32 v[92:93], v[92:93], v[160:161] op_sel_hi:[1,0]
	v_mul_f32_e32 v144, 0xbfb8aa3b, v102
	v_mul_f32_e32 v145, 0xbfb8aa3b, v103
	v_mul_f32_e32 v146, 0xbfb8aa3b, v104
	v_mul_f32_e32 v147, 0xbfb8aa3b, v105
	v_mul_f32_e32 v126, 0xbfb8aa3b, v94
	v_mul_f32_e32 v127, 0xbfb8aa3b, v95
	v_mul_f32_e32 v128, 0xbfb8aa3b, v96
	v_mul_f32_e32 v129, 0xbfb8aa3b, v97
	v_exp_f32_e32 v144, v144
	v_exp_f32_e32 v145, v145
	v_exp_f32_e32 v146, v146
	v_exp_f32_e32 v147, v147
	v_exp_f32_e32 v126, v126
	v_exp_f32_e32 v127, v127
	v_exp_f32_e32 v128, v128
	v_exp_f32_e32 v129, v129
	v_add_f32_e32 v144, 1.0, v144
	v_add_f32_e32 v145, 1.0, v145
	v_add_f32_e32 v146, 1.0, v146
	v_add_f32_e32 v147, 1.0, v147
	v_add_f32_e32 v126, 1.0, v126
	v_add_f32_e32 v127, 1.0, v127
	v_add_f32_e32 v128, 1.0, v128
	v_add_f32_e32 v129, 1.0, v129
	v_rcp_f32_e32 v144, v144
	v_rcp_f32_e32 v145, v145
	v_rcp_f32_e32 v146, v146
	v_rcp_f32_e32 v147, v147
	v_rcp_f32_e32 v126, v126
	v_rcp_f32_e32 v127, v127
	v_rcp_f32_e32 v128, v128
	v_rcp_f32_e32 v129, v129
	v_pk_mul_f32 v[102:103], v[102:103], v[144:145]
	v_pk_mul_f32 v[104:105], v[104:105], v[146:147]
	v_pk_mul_f32 v[94:95], v[94:95], v[126:127]
	v_pk_mul_f32 v[96:97], v[96:97], v[128:129]
	v_pk_mul_f32 v[102:103], v[102:103], v[98:99]
	v_pk_mul_f32 v[104:105], v[104:105], v[100:101]
	v_pk_mul_f32 v[94:95], v[94:95], v[90:91]
	v_pk_mul_f32 v[96:97], v[96:97], v[92:93]
	v_cvt_pk_bf16_f32 v108, v102, v103
	v_cvt_pk_bf16_f32 v109, v104, v105
	v_cvt_pk_bf16_f32 v90, v94, v95
	v_cvt_pk_bf16_f32 v91, v96, v97
	s_nop 1
	v_permlane16_swap_b32_e32 v106, v108
	v_permlane16_swap_b32_e32 v107, v109
	global_store_dwordx4 v[156:157], v[106:109], off
	v_lshl_add_u64 v[156:157], v[156:157], 0, s[56:57]
	v_pk_mul_f32 v[86:87], v[86:87], v[160:161] op_sel_hi:[1,0]
	v_pk_mul_f32 v[88:89], v[88:89], v[160:161] op_sel_hi:[1,0]
	v_pk_mul_f32 v[82:83], v[82:83], v[160:161] op_sel_hi:[1,0]
	v_pk_mul_f32 v[84:85], v[84:85], v[160:161] op_sel_hi:[1,0]
	v_pk_mul_f32 v[78:79], v[78:79], v[160:161] op_sel:[0,1]
	v_pk_mul_f32 v[80:81], v[80:81], v[160:161] op_sel:[0,1]
	v_pk_mul_f32 v[74:75], v[74:75], v[160:161] op_sel:[0,1]
	v_pk_mul_f32 v[76:77], v[76:77], v[160:161] op_sel:[0,1]
	v_mul_f32_e32 v144, 0xbfb8aa3b, v86
	v_mul_f32_e32 v145, 0xbfb8aa3b, v87
	v_mul_f32_e32 v146, 0xbfb8aa3b, v88
	v_mul_f32_e32 v147, 0xbfb8aa3b, v89
	v_mul_f32_e32 v126, 0xbfb8aa3b, v78
	v_mul_f32_e32 v127, 0xbfb8aa3b, v79
	v_mul_f32_e32 v128, 0xbfb8aa3b, v80
	v_mul_f32_e32 v129, 0xbfb8aa3b, v81
	v_exp_f32_e32 v144, v144
	v_exp_f32_e32 v145, v145
	v_exp_f32_e32 v146, v146
	v_exp_f32_e32 v147, v147
	v_exp_f32_e32 v126, v126
	v_exp_f32_e32 v127, v127
	v_exp_f32_e32 v128, v128
	v_exp_f32_e32 v129, v129
	v_add_f32_e32 v144, 1.0, v144
	v_add_f32_e32 v145, 1.0, v145
	v_add_f32_e32 v146, 1.0, v146
	v_add_f32_e32 v147, 1.0, v147
	v_add_f32_e32 v126, 1.0, v126
	v_add_f32_e32 v127, 1.0, v127
	v_add_f32_e32 v128, 1.0, v128
	v_add_f32_e32 v129, 1.0, v129
	v_rcp_f32_e32 v144, v144
	v_rcp_f32_e32 v145, v145
	v_rcp_f32_e32 v146, v146
	v_rcp_f32_e32 v147, v147
	v_rcp_f32_e32 v126, v126
	v_rcp_f32_e32 v127, v127
	v_rcp_f32_e32 v128, v128
	v_rcp_f32_e32 v129, v129
	v_pk_mul_f32 v[86:87], v[86:87], v[144:145]
	v_pk_mul_f32 v[88:89], v[88:89], v[146:147]
	v_pk_mul_f32 v[78:79], v[78:79], v[126:127]
	v_pk_mul_f32 v[80:81], v[80:81], v[128:129]
	v_pk_mul_f32 v[86:87], v[86:87], v[82:83]
	v_pk_mul_f32 v[88:89], v[88:89], v[84:85]
	v_pk_mul_f32 v[78:79], v[78:79], v[74:75]
	v_pk_mul_f32 v[80:81], v[80:81], v[76:77]
	v_cvt_pk_bf16_f32 v92, v86, v87
	v_cvt_pk_bf16_f32 v93, v88, v89
	v_cvt_pk_bf16_f32 v74, v78, v79
	v_cvt_pk_bf16_f32 v75, v80, v81
	s_nop 1
	v_permlane16_swap_b32_e32 v90, v92
	v_permlane16_swap_b32_e32 v91, v93
	global_store_dwordx4 v[156:157], v[90:93], off
	v_lshl_add_u64 v[156:157], v[156:157], 0, s[56:57]
	s_waitcnt lgkmcnt(0)
; DI unsigned pk2(float lo, float hi) { f32x2 v = {lo, hi}; bf2_t r = __builtin_convertvector(v, bf2_t); return __builtin_bit_cast(unsigned, r); }
; DI float silu(float x) { return x * __builtin_amdgcn_rcpf(1.f + __expf(-x)); }
;   DI void operator()(const f32x4 (&acc)[2][2][4][2], const Unit& u, int wr, int wc, int fr, int fq, const PG8_LAS float* sR) const {
;     ...
;     for (int ai = 0; ai < 2; ++ai)
; #pragma unroll
;       for (int m = 0; m < 4; ++m) {
;         bf16_t* rowp = Hd + (size_t)(row0 + ai * HALF + m * 16) * 2816 + j0;
;         const float rs = sR[ai * 128 + m * 16 + fr];
; #pragma unroll
;         for (int bj = 0; bj < 2; ++bj) {
;           const f32x4 g = acc[ai][bj][m][0] * rs, up = acc[ai][bj][m][1] * rs;
;           u32x2 o; o[0] = pk2(silu(g[0]) * up[0], silu(g[1]) * up[1]); o[1] = pk2(silu(g[2]) * up[2], silu(g[3]) * up[3]);
;           *(u32x2*)(rowp + bj * (HALF / 2)) = o;
;         }
	v_pk_mul_f32 v[70:71], v[70:71], v[160:161] op_sel:[0,1]
	v_pk_mul_f32 v[72:73], v[72:73], v[160:161] op_sel:[0,1]
	v_pk_mul_f32 v[66:67], v[66:67], v[160:161] op_sel:[0,1]
	v_pk_mul_f32 v[68:69], v[68:69], v[160:161] op_sel:[0,1]
	v_pk_mul_f32 v[62:63], v[62:63], v[118:119] op_sel_hi:[1,0]
	v_pk_mul_f32 v[64:65], v[64:65], v[118:119] op_sel_hi:[1,0]
	v_pk_mul_f32 v[58:59], v[58:59], v[118:119] op_sel_hi:[1,0]
	v_pk_mul_f32 v[60:61], v[60:61], v[118:119] op_sel_hi:[1,0]
	v_mul_f32_e32 v144, 0xbfb8aa3b, v70
	v_mul_f32_e32 v145, 0xbfb8aa3b, v71
	v_mul_f32_e32 v146, 0xbfb8aa3b, v72
	v_mul_f32_e32 v147, 0xbfb8aa3b, v73
	v_mul_f32_e32 v126, 0xbfb8aa3b, v62
	v_mul_f32_e32 v127, 0xbfb8aa3b, v63
	v_mul_f32_e32 v128, 0xbfb8aa3b, v64
	v_mul_f32_e32 v129, 0xbfb8aa3b, v65
	v_exp_f32_e32 v144, v144
	v_exp_f32_e32 v145, v145
	v_exp_f32_e32 v146, v146
	v_exp_f32_e32 v147, v147
	v_exp_f32_e32 v126, v126
	v_exp_f32_e32 v127, v127
	v_exp_f32_e32 v128, v128
	v_exp_f32_e32 v129, v129
	v_add_f32_e32 v144, 1.0, v144
	v_add_f32_e32 v145, 1.0, v145
	v_add_f32_e32 v146, 1.0, v146
	v_add_f32_e32 v147, 1.0, v147
	v_add_f32_e32 v126, 1.0, v126
	v_add_f32_e32 v127, 1.0, v127
	v_add_f32_e32 v128, 1.0, v128
	v_add_f32_e32 v129, 1.0, v129
	v_rcp_f32_e32 v144, v144
	v_rcp_f32_e32 v145, v145
	v_rcp_f32_e32 v146, v146
	v_rcp_f32_e32 v147, v147
	v_rcp_f32_e32 v126, v126
	v_rcp_f32_e32 v127, v127
	v_rcp_f32_e32 v128, v128
	v_rcp_f32_e32 v129, v129
	v_pk_mul_f32 v[70:71], v[70:71], v[144:145]
	v_pk_mul_f32 v[72:73], v[72:73], v[146:147]
	v_pk_mul_f32 v[62:63], v[62:63], v[126:127]
	v_pk_mul_f32 v[64:65], v[64:65], v[128:129]
	v_pk_mul_f32 v[70:71], v[70:71], v[66:67]
	v_pk_mul_f32 v[72:73], v[72:73], v[68:69]
	v_pk_mul_f32 v[62:63], v[62:63], v[58:59]
	v_pk_mul_f32 v[64:65], v[64:65], v[60:61]
	v_cvt_pk_bf16_f32 v76, v70, v71
	v_cvt_pk_bf16_f32 v77, v72, v73
	v_cvt_pk_bf16_f32 v58, v62, v63
	v_cvt_pk_bf16_f32 v59, v64, v65
	s_nop 1
	v_permlane16_swap_b32_e32 v74, v76
	v_permlane16_swap_b32_e32 v75, v77
	global_store_dwordx4 v[156:157], v[74:77], off
	s_mov_b32 s56, 0x6e000
	v_lshl_add_u64 v[156:157], v[156:157], 0, s[56:57]
	s_mov_b32 s56, 0x16000
	v_pk_mul_f32 v[54:55], v[54:55], v[118:119] op_sel_hi:[1,0]
	v_pk_mul_f32 v[56:57], v[56:57], v[118:119] op_sel_hi:[1,0]
	v_pk_mul_f32 v[50:51], v[50:51], v[118:119] op_sel_hi:[1,0]
	v_pk_mul_f32 v[52:53], v[52:53], v[118:119] op_sel_hi:[1,0]
	v_pk_mul_f32 v[46:47], v[46:47], v[118:119] op_sel:[0,1]
	v_pk_mul_f32 v[48:49], v[48:49], v[118:119] op_sel:[0,1]
	v_pk_mul_f32 v[42:43], v[42:43], v[118:119] op_sel:[0,1]
	v_pk_mul_f32 v[44:45], v[44:45], v[118:119] op_sel:[0,1]
	v_mul_f32_e32 v144, 0xbfb8aa3b, v54
	v_mul_f32_e32 v145, 0xbfb8aa3b, v55
	v_mul_f32_e32 v146, 0xbfb8aa3b, v56
	v_mul_f32_e32 v147, 0xbfb8aa3b, v57
	v_mul_f32_e32 v126, 0xbfb8aa3b, v46
	v_mul_f32_e32 v127, 0xbfb8aa3b, v47
	v_mul_f32_e32 v128, 0xbfb8aa3b, v48
	v_mul_f32_e32 v129, 0xbfb8aa3b, v49
	v_exp_f32_e32 v144, v144
	v_exp_f32_e32 v145, v145
	v_exp_f32_e32 v146, v146
	v_exp_f32_e32 v147, v147
	v_exp_f32_e32 v126, v126
	v_exp_f32_e32 v127, v127
	v_exp_f32_e32 v128, v128
	v_exp_f32_e32 v129, v129
	v_add_f32_e32 v144, 1.0, v144
	v_add_f32_e32 v145, 1.0, v145
	v_add_f32_e32 v146, 1.0, v146
	v_add_f32_e32 v147, 1.0, v147
	v_add_f32_e32 v126, 1.0, v126
	v_add_f32_e32 v127, 1.0, v127
	v_add_f32_e32 v128, 1.0, v128
	v_add_f32_e32 v129, 1.0, v129
	v_rcp_f32_e32 v144, v144
	v_rcp_f32_e32 v145, v145
	v_rcp_f32_e32 v146, v146
	v_rcp_f32_e32 v147, v147
	v_rcp_f32_e32 v126, v126
	v_rcp_f32_e32 v127, v127
	v_rcp_f32_e32 v128, v128
	v_rcp_f32_e32 v129, v129
	v_pk_mul_f32 v[54:55], v[54:55], v[144:145]
	v_pk_mul_f32 v[56:57], v[56:57], v[146:147]
	v_pk_mul_f32 v[46:47], v[46:47], v[126:127]
	v_pk_mul_f32 v[48:49], v[48:49], v[128:129]
	v_pk_mul_f32 v[54:55], v[54:55], v[50:51]
	v_pk_mul_f32 v[56:57], v[56:57], v[52:53]
	v_pk_mul_f32 v[46:47], v[46:47], v[42:43]
	v_pk_mul_f32 v[48:49], v[48:49], v[44:45]
	v_cvt_pk_bf16_f32 v60, v54, v55
	v_cvt_pk_bf16_f32 v61, v56, v57
	v_cvt_pk_bf16_f32 v42, v46, v47
	v_cvt_pk_bf16_f32 v43, v48, v49
	s_nop 1
	v_permlane16_swap_b32_e32 v58, v60
	v_permlane16_swap_b32_e32 v59, v61
	global_store_dwordx4 v[156:157], v[58:61], off
	v_lshl_add_u64 v[156:157], v[156:157], 0, s[56:57]
	v_pk_mul_f32 v[38:39], v[38:39], v[118:119] op_sel:[0,1]
	v_pk_mul_f32 v[40:41], v[40:41], v[118:119] op_sel:[0,1]
	v_pk_mul_f32 v[34:35], v[34:35], v[118:119] op_sel:[0,1]
	v_pk_mul_f32 v[36:37], v[36:37], v[118:119] op_sel:[0,1]
	v_pk_mul_f32 v[30:31], v[30:31], v[120:121] op_sel_hi:[1,0]
	v_pk_mul_f32 v[32:33], v[32:33], v[120:121] op_sel_hi:[1,0]
	v_pk_mul_f32 v[26:27], v[26:27], v[120:121] op_sel_hi:[1,0]
	v_pk_mul_f32 v[28:29], v[28:29], v[120:121] op_sel_hi:[1,0]
	v_mul_f32_e32 v144, 0xbfb8aa3b, v38
	v_mul_f32_e32 v145, 0xbfb8aa3b, v39
	v_mul_f32_e32 v146, 0xbfb8aa3b, v40
	v_mul_f32_e32 v147, 0xbfb8aa3b, v41
; DI unsigned pk2(float lo, float hi) { f32x2 v = {lo, hi}; bf2_t r = __builtin_convertvector(v, bf2_t); return __builtin_bit_cast(unsigned, r); }
; DI float silu(float x) { return x * __builtin_amdgcn_rcpf(1.f + __expf(-x)); }
; #define PG8_WAIT_V(n) asm volatile("s_waitcnt vmcnt(" #n ")" ::: "memory")
; #define PG8_BAR __builtin_amdgcn_s_barrier()
;   DI void operator()(const f32x4 (&acc)[2][2][4][2], const Unit& u, int wr, int wc, int fr, int fq, const PG8_LAS float* sR) const {
;     ...
;     for (int ai = 0; ai < 2; ++ai)
; #pragma unroll
;       for (int m = 0; m < 4; ++m) {
;         bf16_t* rowp = Hd + (size_t)(row0 + ai * HALF + m * 16) * 2816 + j0;
;         const float rs = sR[ai * 128 + m * 16 + fr];
; #pragma unroll
;         for (int bj = 0; bj < 2; ++bj) {
;           const f32x4 g = acc[ai][bj][m][0] * rs, up = acc[ai][bj][m][1] * rs;
;           u32x2 o; o[0] = pk2(silu(g[0]) * up[0], silu(g[1]) * up[1]); o[1] = pk2(silu(g[2]) * up[2], silu(g[3]) * up[3]);
;           *(u32x2*)(rowp + bj * (HALF / 2)) = o;
;         }
; template <class Epi>
; DI void gemm_phase(PG8_LAS unsigned char* lds, const Gemm g, const StaticOrder& S, const Epi& E) {
;     ...
;   PG8_WAIT_V(0);
;   if (wr == 0) PG8_BAR;
;   PG8_BAR;
	v_mul_f32_e32 v126, 0xbfb8aa3b, v30
	v_mul_f32_e32 v127, 0xbfb8aa3b, v31
	v_mul_f32_e32 v128, 0xbfb8aa3b, v32
	v_mul_f32_e32 v129, 0xbfb8aa3b, v33
	v_exp_f32_e32 v144, v144
	v_exp_f32_e32 v145, v145
	v_exp_f32_e32 v146, v146
	v_exp_f32_e32 v147, v147
	v_exp_f32_e32 v126, v126
	v_exp_f32_e32 v127, v127
	v_exp_f32_e32 v128, v128
	v_exp_f32_e32 v129, v129
	v_add_f32_e32 v144, 1.0, v144
	v_add_f32_e32 v145, 1.0, v145
	v_add_f32_e32 v146, 1.0, v146
	v_add_f32_e32 v147, 1.0, v147
	v_add_f32_e32 v126, 1.0, v126
	v_add_f32_e32 v127, 1.0, v127
	v_add_f32_e32 v128, 1.0, v128
	v_add_f32_e32 v129, 1.0, v129
	v_rcp_f32_e32 v144, v144
	v_rcp_f32_e32 v145, v145
	v_rcp_f32_e32 v146, v146
	v_rcp_f32_e32 v147, v147
	v_rcp_f32_e32 v126, v126
	v_rcp_f32_e32 v127, v127
	v_rcp_f32_e32 v128, v128
	v_rcp_f32_e32 v129, v129
	v_pk_mul_f32 v[38:39], v[38:39], v[144:145]
	v_pk_mul_f32 v[40:41], v[40:41], v[146:147]
	v_pk_mul_f32 v[30:31], v[30:31], v[126:127]
	v_pk_mul_f32 v[32:33], v[32:33], v[128:129]
	v_pk_mul_f32 v[38:39], v[38:39], v[34:35]
	v_pk_mul_f32 v[40:41], v[40:41], v[36:37]
	v_pk_mul_f32 v[30:31], v[30:31], v[26:27]
	v_pk_mul_f32 v[32:33], v[32:33], v[28:29]
	v_cvt_pk_bf16_f32 v44, v38, v39
	v_cvt_pk_bf16_f32 v45, v40, v41
	v_cvt_pk_bf16_f32 v26, v30, v31
	v_cvt_pk_bf16_f32 v27, v32, v33
	s_nop 1
	v_permlane16_swap_b32_e32 v42, v44
	v_permlane16_swap_b32_e32 v43, v45
	global_store_dwordx4 v[156:157], v[42:45], off
	v_lshl_add_u64 v[156:157], v[156:157], 0, s[56:57]
	v_pk_mul_f32 v[22:23], v[22:23], v[120:121] op_sel_hi:[1,0]
	v_pk_mul_f32 v[24:25], v[24:25], v[120:121] op_sel_hi:[1,0]
	v_pk_mul_f32 v[18:19], v[18:19], v[120:121] op_sel_hi:[1,0]
	v_pk_mul_f32 v[20:21], v[20:21], v[120:121] op_sel_hi:[1,0]
	v_pk_mul_f32 v[14:15], v[14:15], v[120:121] op_sel:[0,1]
	v_pk_mul_f32 v[16:17], v[16:17], v[120:121] op_sel:[0,1]
	v_pk_mul_f32 v[10:11], v[10:11], v[120:121] op_sel:[0,1]
	v_pk_mul_f32 v[12:13], v[12:13], v[120:121] op_sel:[0,1]
	v_mul_f32_e32 v144, 0xbfb8aa3b, v22
	v_mul_f32_e32 v145, 0xbfb8aa3b, v23
	v_mul_f32_e32 v146, 0xbfb8aa3b, v24
	v_mul_f32_e32 v147, 0xbfb8aa3b, v25
	v_mul_f32_e32 v126, 0xbfb8aa3b, v14
	v_mul_f32_e32 v127, 0xbfb8aa3b, v15
	v_mul_f32_e32 v128, 0xbfb8aa3b, v16
	v_mul_f32_e32 v129, 0xbfb8aa3b, v17
	v_exp_f32_e32 v144, v144
	v_exp_f32_e32 v145, v145
	v_exp_f32_e32 v146, v146
	v_exp_f32_e32 v147, v147
	v_exp_f32_e32 v126, v126
	v_exp_f32_e32 v127, v127
	v_exp_f32_e32 v128, v128
	v_exp_f32_e32 v129, v129
	v_add_f32_e32 v144, 1.0, v144
	v_add_f32_e32 v145, 1.0, v145
	v_add_f32_e32 v146, 1.0, v146
	v_add_f32_e32 v147, 1.0, v147
	v_add_f32_e32 v126, 1.0, v126
	v_add_f32_e32 v127, 1.0, v127
	v_add_f32_e32 v128, 1.0, v128
	v_add_f32_e32 v129, 1.0, v129
	v_rcp_f32_e32 v144, v144
	v_rcp_f32_e32 v145, v145
	v_rcp_f32_e32 v146, v146
	v_rcp_f32_e32 v147, v147
	v_rcp_f32_e32 v126, v126
	v_rcp_f32_e32 v127, v127
	v_rcp_f32_e32 v128, v128
	v_rcp_f32_e32 v129, v129
	v_pk_mul_f32 v[22:23], v[22:23], v[144:145]
	v_pk_mul_f32 v[24:25], v[24:25], v[146:147]
	v_pk_mul_f32 v[14:15], v[14:15], v[126:127]
	v_pk_mul_f32 v[16:17], v[16:17], v[128:129]
	v_pk_mul_f32 v[22:23], v[22:23], v[18:19]
	v_pk_mul_f32 v[24:25], v[24:25], v[20:21]
	v_pk_mul_f32 v[14:15], v[14:15], v[10:11]
	v_pk_mul_f32 v[16:17], v[16:17], v[12:13]
	v_cvt_pk_bf16_f32 v28, v22, v23
	v_cvt_pk_bf16_f32 v29, v24, v25
	v_cvt_pk_bf16_f32 v10, v14, v15
	v_cvt_pk_bf16_f32 v11, v16, v17
	s_nop 1
	v_permlane16_swap_b32_e32 v26, v28
	v_permlane16_swap_b32_e32 v27, v29
	global_store_dwordx4 v[156:157], v[26:29], off
	v_lshl_add_u64 v[156:157], v[156:157], 0, s[56:57]
	v_pk_mul_f32 v[6:7], v[6:7], v[120:121] op_sel:[0,1]
	v_pk_mul_f32 v[8:9], v[8:9], v[120:121] op_sel:[0,1]
	v_pk_mul_f32 v[2:3], v[2:3], v[120:121] op_sel:[0,1]
	v_pk_mul_f32 v[4:5], v[4:5], v[120:121] op_sel:[0,1]
	v_mul_f32_e32 v144, 0xbfb8aa3b, v6
	v_mul_f32_e32 v145, 0xbfb8aa3b, v7
	v_mul_f32_e32 v146, 0xbfb8aa3b, v8
	v_mul_f32_e32 v147, 0xbfb8aa3b, v9
	v_exp_f32_e32 v144, v144
	v_exp_f32_e32 v145, v145
	v_exp_f32_e32 v146, v146
	v_exp_f32_e32 v147, v147
	v_add_f32_e32 v144, 1.0, v144
	v_add_f32_e32 v145, 1.0, v145
	v_add_f32_e32 v146, 1.0, v146
	v_add_f32_e32 v147, 1.0, v147
	v_rcp_f32_e32 v144, v144
	v_rcp_f32_e32 v145, v145
	v_rcp_f32_e32 v146, v146
	v_rcp_f32_e32 v147, v147
	v_pk_mul_f32 v[6:7], v[6:7], v[144:145]
	v_pk_mul_f32 v[8:9], v[8:9], v[146:147]
	v_pk_mul_f32 v[6:7], v[6:7], v[2:3]
	v_pk_mul_f32 v[8:9], v[8:9], v[4:5]
	v_cvt_pk_bf16_f32 v12, v6, v7
	v_cvt_pk_bf16_f32 v13, v8, v9
	s_nop 1
	v_permlane16_swap_b32_e32 v10, v12
	v_permlane16_swap_b32_e32 v11, v13
	global_store_dwordx4 v[156:157], v[10:13], off
	s_mov_b32 s69, s68
	s_mov_b64 s[56:57], s[52:53]
	s_and_b64 vcc, exec, s[40:41]
	s_cbranch_vccz .LBB0_49
	s_waitcnt vmcnt(0)
	s_cmpk_gt_u32 s28, 0xff
	s_cbranch_scc1 .LBB0_56
	s_barrier
.LBB0_56:
	s_barrier
	s_setprio 0

; DI int otid() { int t = threadIdx.x; asm volatile("" : "+v"(t)); return t; }
; #define PG8_STAGE(bufoff, gbase, voff) do { _Pragma("unroll") for (int _i = 0; _i < 2; ++_i) \
;     __builtin_amdgcn_global_load_lds((const unsigned*)((const char*)(gbase) + (voff)[_i]), (PG8_LAS unsigned*)(lds + (bufoff) + ldsw + _i * 8192), 16, 0, 0); } while (0)
; #define PG8_WAIT_V(n) asm volatile("s_waitcnt vmcnt(" #n ")" ::: "memory")
; #define PG8_BAR __builtin_amdgcn_s_barrier()
; template <class Epi>
; DI void gemm_phase(PG8_LAS unsigned char* lds, const Gemm g, const StaticOrder& S, const Epi& E) {
;   const int tid = otid(), wid = __builtin_amdgcn_readfirstlane(tid >> 6), lane = tid & 63, wr = wid >> 2, wc = wid & 3, fr = lane & 15, fq = lane >> 4;
;   const int K = g.K, nt = K / BK;
;   unsigned voffA[2], voffB[2];
; #pragma unroll
;   for (int i = 0; i < 2; ++i) { int R, C; stage_rc(tid * 16 + i * 8192, R, C); const int Rb = Epi::PERM ? ((R & ~31) + perm32(R & 31)) : R;
;     voffA[i] = (unsigned)(R * g.lda + C) * 2u; voffB[i] = (unsigned)(Rb * K + C) * 2u; }
;   const size_t kstep = (size_t)(BK * 2);
;   const size_t hstepA = (size_t)HALF * g.lda * 2, hstepB = (size_t)HALF * K * 2;
;   const size_t tstepA = 2 * hstepA, tstepB = 2 * hstepB;
;   const unsigned ldsw = (unsigned)wid * 1024u;
;   const int aoff = lds_byte(wr * 64 + fr, fq * 8), boff = lds_byte(wc * 32 + fr, fq * 8);
;     ...
;   Unit cur, nxt; int ui = 0;
;   if (!S.next(0, cur)) return;
;   f32x4 acc[2][2][4][2];
; #pragma unroll
;   for (int a = 0; a < 2; ++a)
; #pragma unroll
;     for (int b = 0; b < 2; ++b)
; #pragma unroll
;       for (int m = 0; m < 4; ++m)
; #pragma unroll
;         for (int n = 0; n < 2; ++n) acc[a][b][m][n] = (f32x4){0.f, 0.f, 0.f, 0.f};
;   bf16x8 At[4][2], B0[2][2], B1[2][2];
;   const char* cA = (const char*)g.A + (size_t)cur.pm * tstepA; const char* cB = (const char*)g.Bt + (size_t)cur.pn * tstepB;
;   PG8_STAGE(PG8_SB(0, 0), cB, voffB); PG8_STAGE(PG8_SA(0, 0), cA, voffA); PG8_STAGE(PG8_SB(0, 1), cB + hstepB, voffB); PG8_STAGE(PG8_SA(0, 1), cA + hstepA, voffA);
;   if (wr == 1) PG8_BAR;
;   PG8_WAIT_V(4); PG8_BAR;
;   PG8_STAGE(PG8_SB(1, 0), cB + kstep, voffB); PG8_STAGE(PG8_SA(1, 0), cA + kstep, voffA); PG8_STAGE(PG8_SB(1, 1), cB + hstepB + kstep, voffB);
;   PG8_WAIT_V(6); PG8_BAR;
.LBB0_819:
	v_readlane_b32 s4, v252, 37
	s_waitcnt vmcnt(7)
	v_mov_b32_e32 v14, v200
	v_readlane_b32 s5, v252, 38
	s_barrier
	s_andn2_b64 vcc, exec, s[4:5]
	v_readfirstlane_b32 s28, v14
	s_cbranch_vccnz .LBB0_991
	v_lshlrev_b32_e32 v0, 4, v14
	s_waitcnt vmcnt(0)
	v_add_u32_e32 v2, 0x2000, v0
	v_ashrrev_i32_e32 v3, 31, v2
	v_lshrrev_b32_e32 v3, 22, v3
	v_add_u32_e32 v3, v2, v3
	v_ashrrev_i32_e32 v3, 10, v3
	v_lshlrev_b32_e32 v4, 5, v3
	v_and_b32_e32 v15, 32, v4
	v_mul_i32_i24_e32 v4, 0x400, v3
	v_sub_u32_e32 v2, v2, v4
	v_lshrrev_b32_e32 v4, 4, v2
	v_bitop3_b32 v2, v4, v2, 32 bitop3:0x6c
	v_ashrrev_i32_e32 v4, 31, v2
	v_lshrrev_b32_e32 v4, 26, v4
	v_add_u32_e32 v4, v2, v4
	v_ashrrev_i32_e32 v5, 6, v4
	v_and_b32_e32 v4, 0xc0, v4
	v_sub_u32_e32 v2, v2, v4
	v_lshlrev_b32_e32 v3, 3, v3
	v_ashrrev_i16_sdwa v2, v202, sext(v2) dst_sel:DWORD dst_unused:UNUSED_PAD src0_sel:DWORD src1_sel:BYTE_0
	v_and_b32_e32 v3, -16, v3
	v_bfe_i32 v16, v2, 0, 16
	v_add_u32_e32 v3, v5, v3
	v_add_u32_e32 v2, v15, v16
	v_mul_lo_u32 v4, v3, s34
	v_mul_lo_u32 v17, v3, s40
	v_add_lshl_u32 v142, v2, v4, 1
	v_add_lshl_u32 v144, v2, v17, 1
	v_ashrrev_i32_e32 v2, 31, v14
	v_lshrrev_b32_e32 v2, 26, v2
	v_add_u32_e32 v2, v14, v2
	v_ashrrev_i32_e32 v2, 6, v2
	v_lshlrev_b32_e32 v3, 5, v2
	v_and_b32_e32 v18, 32, v3
	v_bfe_i32 v3, v14, 27, 1
	v_lshrrev_b32_e32 v3, 22, v3
	v_add_u32_e32 v3, v0, v3
	v_and_b32_e32 v3, 0xfffffc00, v3
	v_sub_u32_e32 v0, v0, v3
	v_lshrrev_b32_e32 v3, 4, v0
	v_readlane_b32 s4, v253, 16
	v_bitop3_b32 v3, v3, v0, 32 bitop3:0x6c
	v_ashrrev_i32_e32 v0, 31, v0
	v_readlane_b32 s14, v253, 26
	v_lshrrev_b32_e32 v0, 26, v0
	v_readlane_b32 s15, v253, 27
	s_add_u32 s37, s14, s0
	v_add_u32_e32 v0, v3, v0
	v_lshlrev_b32_e32 v2, 3, v2
	s_addc_u32 s60, s15, s1
	v_readlane_b32 s0, v252, 4
	v_ashrrev_i32_e32 v0, 6, v0
	v_and_b32_e32 v2, -16, v2
	v_readlane_b32 s5, v253, 17
	v_readlane_b32 s1, v252, 5
	s_lshl_b32 s63, s40, 9
	v_mul_i32_i24_e32 v4, 64, v0
	v_add_u32_e32 v2, v0, v2
	v_readlane_b32 s4, v255, 0
	s_load_dword s61, s[0:1], 0x0
	s_ashr_i32 s1, s28, 6
	s_lshl_b32 s50, s40, 8
	s_lshl_b32 s64, s34, 9
	v_sub_u32_e32 v3, v3, v4
	v_mul_lo_u32 v20, v2, s40
	s_mul_hi_i32 s40, s63, s4
	s_mul_i32 s41, s63, s4
	v_readlane_b32 s4, v255, 2
	s_ashr_i32 s0, s28, 8
	s_lshl_b32 s62, s34, 8
	s_lshl_b32 s65, s1, 10
	v_ashrrev_i16_sdwa v3, v202, sext(v3) dst_sel:DWORD dst_unused:UNUSED_PAD src0_sel:DWORD src1_sel:BYTE_0
	s_mul_i32 s43, s64, s4
	v_bfe_i32 v19, v3, 0, 16
	s_mul_hi_i32 s42, s64, s4
	s_add_u32 s56, s37, s43
	v_add_u32_e32 v3, v18, v19
	v_mul_lo_u32 v0, v2, s34
	s_addc_u32 s57, s60, s42
	s_add_i32 s66, s65, 0
	v_add_lshl_u32 v0, v3, v0, 1
	s_add_i32 m0, s66, 0x10000
	v_add_lshl_u32 v146, v3, v20, 1
	global_load_lds_dwordx4 v0, s[56:57]
	s_add_i32 m0, s66, 0x12000
	s_add_u32 s58, s30, s41
	global_load_lds_dwordx4 v142, s[56:57]
	s_addc_u32 s59, s31, s40
	s_mov_b32 m0, s66
	s_add_i32 s67, s66, 0x2000
	global_load_lds_dwordx4 v146, s[58:59]
	s_mov_b32 m0, s67
	s_add_u32 s40, s56, s62
	global_load_lds_dwordx4 v144, s[58:59]
	s_addc_u32 s41, s57, 0
	s_add_i32 m0, s66, 0x14000
	v_mov_b32_e32 v143, v1
	global_load_lds_dwordx4 v0, s[40:41]
	s_add_i32 m0, s66, 0x16000
	s_waitcnt lgkmcnt(0)
	v_lshl_add_u64 v[10:11], s[40:41], 0, v[0:1]
	v_lshl_add_u64 v[12:13], s[40:41], 0, v[142:143]
	global_load_lds_dwordx4 v142, s[40:41]
	s_add_u32 s40, s58, s50
	s_addc_u32 s41, s59, 0
	s_add_i32 s68, s66, 0x4000
	s_mov_b32 m0, s68
	s_add_i32 s69, s66, 0x6000
	global_load_lds_dwordx4 v146, s[40:41]
	s_mov_b32 m0, s69
	v_mov_b32_e32 v147, v1
	global_load_lds_dwordx4 v144, s[40:41]
	v_mov_b32_e32 v145, v1
	s_mov_b32 s51, s35
	v_lshl_add_u64 v[2:3], s[56:57], 0, v[0:1]
	v_lshl_add_u64 v[4:5], s[56:57], 0, v[142:143]
	v_lshl_add_u64 v[6:7], s[58:59], 0, v[146:147]
	v_lshl_add_u64 v[8:9], s[58:59], 0, v[144:145]
	s_cmp_lg_u32 s0, 1
	v_readlane_b32 s6, v253, 18
	v_readlane_b32 s7, v253, 19
	v_readlane_b32 s8, v253, 20
	v_readlane_b32 s9, v253, 21
	v_readlane_b32 s10, v253, 22
	v_readlane_b32 s11, v253, 23
	v_readlane_b32 s12, v253, 24
	v_readlane_b32 s13, v253, 25
	v_readlane_b32 s16, v253, 28
	v_readlane_b32 s17, v253, 29
	v_readlane_b32 s18, v253, 30
	v_readlane_b32 s19, v253, 31
	v_readlane_b32 s5, v255, 3
	s_cbranch_scc1 .LBB0_822
	s_barrier
	s_setprio 1

; #define PG8_STAGE(bufoff, gbase, voff) do { _Pragma("unroll") for (int _i = 0; _i < 2; ++_i) \
;     __builtin_amdgcn_global_load_lds((const unsigned*)((const char*)(gbase) + (voff)[_i]), (PG8_LAS unsigned*)(lds + (bufoff) + ldsw + _i * 8192), 16, 0, 0); } while (0)
; #define PG8_LDA(dst, b, h) do { _Pragma("unroll") for (int m = 0; m < 4; ++m) _Pragma("unroll") for (int k = 0; k < 2; ++k) dst[m][k] = *(const PG8_LAS bf16x8*)(lds + PG8_SA(b, h) + aoff + m * 2048 + k * 1024); } while (0)
; #define PG8_LDB(dst, b, h) do { _Pragma("unroll") for (int n = 0; n < 2; ++n) _Pragma("unroll") for (int k = 0; k < 2; ++k) dst[n][k] = *(const PG8_LAS bf16x8*)(lds + PG8_SB(b, h) + boff + n * 2048 + k * 1024); } while (0)
; #define PG8_MMA(ai, bj, At, Bt) do { __builtin_amdgcn_s_setprio(1); _Pragma("unroll") for (int m = 0; m < 4; ++m) _Pragma("unroll") for (int n = 0; n < 2; ++n) _Pragma("unroll") for (int k = 0; k < 2; ++k) \
;     acc[ai][bj][m][n] = __builtin_amdgcn_mfma_f32_16x16x32_bf16(Bt[n][k], At[m][k], acc[ai][bj][m][n], 0, 0, 0); __builtin_amdgcn_s_setprio(0); } while (0)
; #define PG8_WAIT_L(n) asm volatile("s_waitcnt lgkmcnt(" #n ")" ::: "memory")
; #define PG8_BAR __builtin_amdgcn_s_barrier()
; #define PG8_SCHED __builtin_amdgcn_sched_barrier(0)
; template <class Epi>
; DI void gemm_phase(PG8_LAS unsigned char* lds, const Gemm g, const StaticOrder& S, const Epi& E) {
;     ...
;     for (int t = 0; t < nt; t += 2) {
;       const bool last = (t == nt - 2);
;       const char* a1 = cA + (size_t)(t + 1) * kstep;
;       const char* a2 = last ? nA : cA + (size_t)(t + 2) * kstep; const char* b2 = last ? nB : cB + (size_t)(t + 2) * kstep;
;       const char* a3 = a2 + kstep; const char* b3 = b2 + kstep;
;       PG8_LDB(B0, 0, 0); PG8_SCHED; PG8_LDA(At, 0, 0); PG8_STAGE(PG8_SA(1, 1), a1 + hstepA, voffA);
;       PG8_WAIT_L(8); PG8_BAR; PG8_WAIT_L(0); PG8_MMA(0, 0, At, B0); PG8_BAR; PG8_SCHED;
;       PG8_LDB(B1, 0, 1); PG8_STAGE(PG8_SB(0, 0), b2, voffB);
;       PG8_BAR; PG8_WAIT_L(0); PG8_MMA(0, 1, At, B1); PG8_BAR;
;       PG8_LDA(At, 0, 1); PG8_STAGE(PG8_SA(0, 0), a2, voffA);
;       PG8_BAR; PG8_WAIT_L(0); PG8_MMA(1, 0, At, B0); PG8_BAR; PG8_SCHED;
.LBB0_835:
	s_add_i32 s81, s56, 2
	s_add_u32 s58, s44, 0x80
	s_addc_u32 s57, s45, 0
	s_add_i32 s82, 0, 0x10000
	v_add_u32_e32 v160, s82, v223
	ds_read_b128 v[130:133], v160
	ds_read_b128 v[152:155], v160 offset:1024
	ds_read_b128 v[156:159], v160 offset:2048
	ds_read_b128 v[160:163], v160 offset:3072
	s_cmp_eq_u32 s75, s56
	s_cselect_b32 s56, s0, s58
	s_cselect_b32 s57, s1, s57
	s_cselect_b32 s59, s55, s80
	s_cselect_b32 s58, s54, s79
	v_lshl_add_u64 v[196:197], s[44:45], 0, v[148:149]
	s_add_i32 m0, s66, 0xc000
	ds_read_b128 v[164:167], v225
	ds_read_b128 v[168:171], v225 offset:1024
	ds_read_b128 v[172:175], v225 offset:2048
	ds_read_b128 v[176:179], v225 offset:3072
	ds_read_b128 v[180:183], v225 offset:4096
	ds_read_b128 v[184:187], v225 offset:5120
	ds_read_b128 v[188:191], v225 offset:6144
	ds_read_b128 v[192:195], v225 offset:7168
	global_load_lds_dwordx4 v[196:197], off
	v_lshl_add_u64 v[196:197], s[44:45], 0, v[150:151]
	s_add_i32 m0, s66, 0xe000
	s_nop 0
	global_load_lds_dwordx4 v[196:197], off
	s_waitcnt lgkmcnt(8)
	s_barrier
	s_waitcnt lgkmcnt(0)
	s_waitcnt lgkmcnt(0)
	v_mfma_f32_16x16x32_bf16 v[126:129], v[130:133], v[164:167], v[126:129]
	v_mfma_f32_16x16x32_bf16 v[122:125], v[156:159], v[164:167], v[122:125]
	v_mfma_f32_16x16x32_bf16 v[110:113], v[130:133], v[172:175], v[110:113]
	v_mfma_f32_16x16x32_bf16 v[106:109], v[156:159], v[172:175], v[106:109]
	v_mfma_f32_16x16x32_bf16 v[94:97], v[130:133], v[180:183], v[94:97]
	v_mfma_f32_16x16x32_bf16 v[90:93], v[156:159], v[180:183], v[90:93]
	v_mfma_f32_16x16x32_bf16 v[78:81], v[130:133], v[188:191], v[78:81]
	v_mfma_f32_16x16x32_bf16 v[74:77], v[156:159], v[188:191], v[74:77]
	v_mfma_f32_16x16x32_bf16 v[126:129], v[152:155], v[168:171], v[126:129]
	v_mfma_f32_16x16x32_bf16 v[122:125], v[160:163], v[168:171], v[122:125]
	v_mfma_f32_16x16x32_bf16 v[110:113], v[152:155], v[176:179], v[110:113]
	v_mfma_f32_16x16x32_bf16 v[106:109], v[160:163], v[176:179], v[106:109]
	v_mfma_f32_16x16x32_bf16 v[94:97], v[152:155], v[184:187], v[94:97]
	v_mfma_f32_16x16x32_bf16 v[90:93], v[160:163], v[184:187], v[90:93]
	v_mfma_f32_16x16x32_bf16 v[78:81], v[152:155], v[192:195], v[78:81]
	v_mfma_f32_16x16x32_bf16 v[74:77], v[160:163], v[192:195], v[74:77]
	s_barrier
	s_add_i32 s83, 0, 0x14000
	s_add_i32 s82, s82, s65
	v_add_u32_e32 v234, s83, v223
	v_lshl_add_u64 v[238:239], s[58:59], 0, v[0:1]
	s_mov_b32 m0, s82
	ds_read_b128 v[196:199], v234
	ds_read_b128 v[226:229], v234 offset:1024
	ds_read_b128 v[230:233], v234 offset:2048
	ds_read_b128 v[234:237], v234 offset:3072
	global_load_lds_dwordx4 v[238:239], off
	v_lshl_add_u64 v[240:241], s[58:59], 0, v[142:143]
	s_add_i32 m0, s82, 0x2000
	s_nop 0
	global_load_lds_dwordx4 v[240:241], off
	s_barrier
	s_waitcnt lgkmcnt(0)
	s_waitcnt lgkmcnt(0)
	v_mfma_f32_16x16x32_bf16 v[118:121], v[196:199], v[164:167], v[118:121]
	v_mfma_f32_16x16x32_bf16 v[114:117], v[230:233], v[164:167], v[114:117]
	v_mfma_f32_16x16x32_bf16 v[102:105], v[196:199], v[172:175], v[102:105]
	v_mfma_f32_16x16x32_bf16 v[98:101], v[230:233], v[172:175], v[98:101]
	v_mfma_f32_16x16x32_bf16 v[86:89], v[196:199], v[180:183], v[86:89]
	v_mfma_f32_16x16x32_bf16 v[82:85], v[230:233], v[180:183], v[82:85]
	v_mfma_f32_16x16x32_bf16 v[70:73], v[196:199], v[188:191], v[70:73]
	v_mfma_f32_16x16x32_bf16 v[66:69], v[230:233], v[188:191], v[66:69]
	v_mfma_f32_16x16x32_bf16 v[118:121], v[226:229], v[168:171], v[118:121]
	v_mfma_f32_16x16x32_bf16 v[114:117], v[234:237], v[168:171], v[114:117]
	v_mfma_f32_16x16x32_bf16 v[102:105], v[226:229], v[176:179], v[102:105]
	v_mfma_f32_16x16x32_bf16 v[98:101], v[234:237], v[176:179], v[98:101]
	v_mfma_f32_16x16x32_bf16 v[86:89], v[226:229], v[184:187], v[86:89]
	v_mfma_f32_16x16x32_bf16 v[82:85], v[234:237], v[184:187], v[82:85]
	v_mfma_f32_16x16x32_bf16 v[70:73], v[226:229], v[192:195], v[70:73]
	v_mfma_f32_16x16x32_bf16 v[66:69], v[234:237], v[192:195], v[66:69]
	s_mov_b32 m0, s66
	v_lshl_add_u64 v[242:243], s[56:57], 0, v[146:147]
	s_barrier
	ds_read_b128 v[164:167], v225 offset:16384
	ds_read_b128 v[168:171], v225 offset:17408
	ds_read_b128 v[172:175], v225 offset:18432
	ds_read_b128 v[176:179], v225 offset:19456
	ds_read_b128 v[180:183], v225 offset:20480
	ds_read_b128 v[184:187], v225 offset:21504
	ds_read_b128 v[188:191], v225 offset:22528
	ds_read_b128 v[192:195], v225 offset:23552
	global_load_lds_dwordx4 v[242:243], off
	v_lshl_add_u64 v[244:245], s[56:57], 0, v[144:145]
	s_mov_b32 m0, s67
	s_nop 0
	global_load_lds_dwordx4 v[244:245], off
	s_barrier
	s_waitcnt lgkmcnt(0)
	s_waitcnt lgkmcnt(0)
	v_mfma_f32_16x16x32_bf16 v[62:65], v[130:133], v[164:167], v[62:65]
	v_mfma_f32_16x16x32_bf16 v[58:61], v[156:159], v[164:167], v[58:61]
	v_mfma_f32_16x16x32_bf16 v[46:49], v[130:133], v[172:175], v[46:49]
	v_mfma_f32_16x16x32_bf16 v[42:45], v[156:159], v[172:175], v[42:45]
	v_mfma_f32_16x16x32_bf16 v[30:33], v[130:133], v[180:183], v[30:33]
	v_mfma_f32_16x16x32_bf16 v[26:29], v[156:159], v[180:183], v[26:29]
	v_mfma_f32_16x16x32_bf16 v[14:17], v[130:133], v[188:191], v[14:17]
	v_mfma_f32_16x16x32_bf16 v[10:13], v[156:159], v[188:191], v[10:13]
	v_mfma_f32_16x16x32_bf16 v[62:65], v[152:155], v[168:171], v[62:65]
	v_mfma_f32_16x16x32_bf16 v[58:61], v[160:163], v[168:171], v[58:61]
	v_mfma_f32_16x16x32_bf16 v[46:49], v[152:155], v[176:179], v[46:49]
	v_mfma_f32_16x16x32_bf16 v[42:45], v[160:163], v[176:179], v[42:45]
	v_mfma_f32_16x16x32_bf16 v[30:33], v[152:155], v[184:187], v[30:33]
	v_mfma_f32_16x16x32_bf16 v[26:29], v[160:163], v[184:187], v[26:29]
	v_mfma_f32_16x16x32_bf16 v[14:17], v[152:155], v[192:195], v[14:17]
	v_mfma_f32_16x16x32_bf16 v[10:13], v[160:163], v[192:195], v[10:13]
	s_barrier
; #define PG8_STAGE(bufoff, gbase, voff) do { _Pragma("unroll") for (int _i = 0; _i < 2; ++_i) \
;     __builtin_amdgcn_global_load_lds((const unsigned*)((const char*)(gbase) + (voff)[_i]), (PG8_LAS unsigned*)(lds + (bufoff) + ldsw + _i * 8192), 16, 0, 0); } while (0)
; #define PG8_LDA(dst, b, h) do { _Pragma("unroll") for (int m = 0; m < 4; ++m) _Pragma("unroll") for (int k = 0; k < 2; ++k) dst[m][k] = *(const PG8_LAS bf16x8*)(lds + PG8_SA(b, h) + aoff + m * 2048 + k * 1024); } while (0)
; #define PG8_LDB(dst, b, h) do { _Pragma("unroll") for (int n = 0; n < 2; ++n) _Pragma("unroll") for (int k = 0; k < 2; ++k) dst[n][k] = *(const PG8_LAS bf16x8*)(lds + PG8_SB(b, h) + boff + n * 2048 + k * 1024); } while (0)
; #define PG8_MMA(ai, bj, At, Bt) do { __builtin_amdgcn_s_setprio(1); _Pragma("unroll") for (int m = 0; m < 4; ++m) _Pragma("unroll") for (int n = 0; n < 2; ++n) _Pragma("unroll") for (int k = 0; k < 2; ++k) \
;     acc[ai][bj][m][n] = __builtin_amdgcn_mfma_f32_16x16x32_bf16(Bt[n][k], At[m][k], acc[ai][bj][m][n], 0, 0, 0); __builtin_amdgcn_s_setprio(0); } while (0)
; #define PG8_WAIT_V(n) asm volatile("s_waitcnt vmcnt(" #n ")" ::: "memory")
; #define PG8_WAIT_L(n) asm volatile("s_waitcnt lgkmcnt(" #n ")" ::: "memory")
; #define PG8_BAR __builtin_amdgcn_s_barrier()
; #define PG8_SCHED __builtin_amdgcn_sched_barrier(0)
; template <class Epi>
; DI void gemm_phase(PG8_LAS unsigned char* lds, const Gemm g, const StaticOrder& S, const Epi& E) {
;     ...
;       PG8_STAGE(PG8_SB(0, 1), b2 + hstepB, voffB);
;       PG8_WAIT_V(6); PG8_BAR; PG8_MMA(1, 1, At, B1); PG8_BAR;
;       PG8_LDB(B0, 1, 0); PG8_SCHED; PG8_LDA(At, 1, 0); PG8_STAGE(PG8_SA(0, 1), a2 + hstepA, voffA);
;       PG8_WAIT_L(8); PG8_BAR; PG8_WAIT_L(0); PG8_MMA(0, 0, At, B0); PG8_BAR; PG8_SCHED;
;       PG8_LDB(B1, 1, 1); PG8_STAGE(PG8_SB(1, 0), b3, voffB);
;       PG8_BAR; PG8_WAIT_L(0); PG8_MMA(0, 1, At, B1); PG8_BAR;
;       PG8_LDA(At, 1, 1); PG8_STAGE(PG8_SA(1, 0), a3, voffA);
	s_add_u32 s58, s58, s62
	s_addc_u32 s59, s59, 0
	s_add_i32 s82, s83, s65
	v_lshl_add_u64 v[246:247], s[58:59], 0, v[0:1]
	s_mov_b32 m0, s82
	v_lshl_add_u64 v[248:249], s[58:59], 0, v[142:143]
	global_load_lds_dwordx4 v[246:247], off
	s_add_i32 m0, s82, 0x2000
	s_nop 0
	global_load_lds_dwordx4 v[248:249], off
	s_waitcnt vmcnt(6)
	s_barrier
	v_mfma_f32_16x16x32_bf16 v[54:57], v[196:199], v[164:167], v[54:57]
	v_mfma_f32_16x16x32_bf16 v[50:53], v[230:233], v[164:167], v[50:53]
	v_mfma_f32_16x16x32_bf16 v[38:41], v[196:199], v[172:175], v[38:41]
	v_mfma_f32_16x16x32_bf16 v[34:37], v[230:233], v[172:175], v[34:37]
	v_mfma_f32_16x16x32_bf16 v[22:25], v[196:199], v[180:183], v[22:25]
	v_mfma_f32_16x16x32_bf16 v[18:21], v[230:233], v[180:183], v[18:21]
	v_mfma_f32_16x16x32_bf16 v[6:9], v[196:199], v[188:191], v[6:9]
	v_mfma_f32_16x16x32_bf16 v[2:5], v[230:233], v[188:191], v[2:5]
	v_mfma_f32_16x16x32_bf16 v[54:57], v[226:229], v[168:171], v[54:57]
	v_mfma_f32_16x16x32_bf16 v[50:53], v[234:237], v[168:171], v[50:53]
	v_mfma_f32_16x16x32_bf16 v[38:41], v[226:229], v[176:179], v[38:41]
	v_mfma_f32_16x16x32_bf16 v[34:37], v[234:237], v[176:179], v[34:37]
	v_mfma_f32_16x16x32_bf16 v[22:25], v[226:229], v[184:187], v[22:25]
	v_mfma_f32_16x16x32_bf16 v[18:21], v[234:237], v[184:187], v[18:21]
	v_mfma_f32_16x16x32_bf16 v[6:9], v[226:229], v[192:195], v[6:9]
	v_mfma_f32_16x16x32_bf16 v[2:5], v[234:237], v[192:195], v[2:5]
	s_add_i32 s58, 0, 0x18000
	v_add_u32_e32 v160, s58, v223
	s_barrier
	ds_read_b128 v[130:133], v160
	ds_read_b128 v[152:155], v160 offset:1024
	ds_read_b128 v[156:159], v160 offset:2048
	ds_read_b128 v[160:163], v160 offset:3072
	s_add_u32 s56, s56, s50
	s_addc_u32 s57, s57, 0
	s_mov_b32 m0, s68
	v_lshl_add_u64 v[196:197], s[56:57], 0, v[146:147]
	ds_read_b128 v[164:167], v225 offset:32768
	ds_read_b128 v[168:171], v225 offset:33792
	ds_read_b128 v[172:175], v225 offset:34816
	ds_read_b128 v[176:179], v225 offset:35840
	ds_read_b128 v[180:183], v225 offset:36864
	ds_read_b128 v[184:187], v225 offset:37888
	ds_read_b128 v[188:191], v225 offset:38912
	ds_read_b128 v[192:195], v225 offset:39936
	global_load_lds_dwordx4 v[196:197], off
	v_lshl_add_u64 v[196:197], s[56:57], 0, v[144:145]
	s_mov_b32 m0, s69
	s_nop 0
	global_load_lds_dwordx4 v[196:197], off
	s_waitcnt lgkmcnt(8)
	s_barrier
	s_waitcnt lgkmcnt(0)
	s_waitcnt lgkmcnt(0)
	v_mfma_f32_16x16x32_bf16 v[126:129], v[130:133], v[164:167], v[126:129]
	v_mfma_f32_16x16x32_bf16 v[122:125], v[156:159], v[164:167], v[122:125]
	v_mfma_f32_16x16x32_bf16 v[110:113], v[130:133], v[172:175], v[110:113]
	v_mfma_f32_16x16x32_bf16 v[106:109], v[156:159], v[172:175], v[106:109]
	v_mfma_f32_16x16x32_bf16 v[94:97], v[130:133], v[180:183], v[94:97]
	v_mfma_f32_16x16x32_bf16 v[90:93], v[156:159], v[180:183], v[90:93]
	v_mfma_f32_16x16x32_bf16 v[78:81], v[130:133], v[188:191], v[78:81]
	v_mfma_f32_16x16x32_bf16 v[74:77], v[156:159], v[188:191], v[74:77]
	v_mfma_f32_16x16x32_bf16 v[126:129], v[152:155], v[168:171], v[126:129]
	v_mfma_f32_16x16x32_bf16 v[122:125], v[160:163], v[168:171], v[122:125]
	v_mfma_f32_16x16x32_bf16 v[110:113], v[152:155], v[176:179], v[110:113]
	v_mfma_f32_16x16x32_bf16 v[106:109], v[160:163], v[176:179], v[106:109]
	v_mfma_f32_16x16x32_bf16 v[94:97], v[152:155], v[184:187], v[94:97]
	v_mfma_f32_16x16x32_bf16 v[90:93], v[160:163], v[184:187], v[90:93]
	v_mfma_f32_16x16x32_bf16 v[78:81], v[152:155], v[192:195], v[78:81]
	v_mfma_f32_16x16x32_bf16 v[74:77], v[160:163], v[192:195], v[74:77]
	s_barrier
	s_add_i32 s56, 0, 0x1c000
	s_add_i32 s57, s58, s65
	v_add_u32_e32 v234, s56, v223
	v_lshl_add_u64 v[238:239], v[238:239], 0, s[86:87]
	s_mov_b32 m0, s57
	ds_read_b128 v[196:199], v234
	ds_read_b128 v[226:229], v234 offset:1024
	ds_read_b128 v[230:233], v234 offset:2048
	ds_read_b128 v[234:237], v234 offset:3072
	global_load_lds_dwordx4 v[238:239], off
	v_lshl_add_u64 v[238:239], v[240:241], 0, s[86:87]
	s_add_i32 m0, s57, 0x2000
	s_nop 0
	global_load_lds_dwordx4 v[238:239], off
	s_barrier
	s_waitcnt lgkmcnt(0)
	s_waitcnt lgkmcnt(0)
	v_mfma_f32_16x16x32_bf16 v[118:121], v[196:199], v[164:167], v[118:121]
	v_mfma_f32_16x16x32_bf16 v[114:117], v[230:233], v[164:167], v[114:117]
	v_mfma_f32_16x16x32_bf16 v[102:105], v[196:199], v[172:175], v[102:105]
	v_mfma_f32_16x16x32_bf16 v[98:101], v[230:233], v[172:175], v[98:101]
	v_mfma_f32_16x16x32_bf16 v[86:89], v[196:199], v[180:183], v[86:89]
	v_mfma_f32_16x16x32_bf16 v[82:85], v[230:233], v[180:183], v[82:85]
	v_mfma_f32_16x16x32_bf16 v[70:73], v[196:199], v[188:191], v[70:73]
	v_mfma_f32_16x16x32_bf16 v[66:69], v[230:233], v[188:191], v[66:69]
	v_mfma_f32_16x16x32_bf16 v[118:121], v[226:229], v[168:171], v[118:121]
	v_mfma_f32_16x16x32_bf16 v[114:117], v[234:237], v[168:171], v[114:117]
	v_mfma_f32_16x16x32_bf16 v[102:105], v[226:229], v[176:179], v[102:105]
	v_mfma_f32_16x16x32_bf16 v[98:101], v[234:237], v[176:179], v[98:101]
	v_mfma_f32_16x16x32_bf16 v[86:89], v[226:229], v[184:187], v[86:89]
	v_mfma_f32_16x16x32_bf16 v[82:85], v[234:237], v[184:187], v[82:85]
	v_mfma_f32_16x16x32_bf16 v[70:73], v[226:229], v[192:195], v[70:73]
	v_mfma_f32_16x16x32_bf16 v[66:69], v[234:237], v[192:195], v[66:69]
	s_mov_b32 m0, s72
	v_lshl_add_u64 v[238:239], v[242:243], 0, s[86:87]
	s_barrier
	ds_read_b128 v[164:167], v225 offset:49152
	ds_read_b128 v[168:171], v225 offset:50176
	ds_read_b128 v[172:175], v225 offset:51200
	ds_read_b128 v[176:179], v225 offset:52224
	ds_read_b128 v[180:183], v225 offset:53248
	ds_read_b128 v[184:187], v225 offset:54272
	ds_read_b128 v[188:191], v225 offset:55296
	ds_read_b128 v[192:195], v225 offset:56320
	global_load_lds_dwordx4 v[238:239], off
	v_lshl_add_u64 v[238:239], v[244:245], 0, s[86:87]
	s_mov_b32 m0, s73
	s_nop 0
	global_load_lds_dwordx4 v[238:239], off
	s_barrier
; #define PG8_LAS __attribute__((address_space(3)))
; #define PG8_STAGE(bufoff, gbase, voff) do { _Pragma("unroll") for (int _i = 0; _i < 2; ++_i) \
;     __builtin_amdgcn_global_load_lds((const unsigned*)((const char*)(gbase) + (voff)[_i]), (PG8_LAS unsigned*)(lds + (bufoff) + ldsw + _i * 8192), 16, 0, 0); } while (0)
; #define PG8_MMA(ai, bj, At, Bt) do { __builtin_amdgcn_s_setprio(1); _Pragma("unroll") for (int m = 0; m < 4; ++m) _Pragma("unroll") for (int n = 0; n < 2; ++n) _Pragma("unroll") for (int k = 0; k < 2; ++k) \
;     acc[ai][bj][m][n] = __builtin_amdgcn_mfma_f32_16x16x32_bf16(Bt[n][k], At[m][k], acc[ai][bj][m][n], 0, 0, 0); __builtin_amdgcn_s_setprio(0); } while (0)
; #define PG8_WAIT_V(n) asm volatile("s_waitcnt vmcnt(" #n ")" ::: "memory")
; #define PG8_WAIT_L(n) asm volatile("s_waitcnt lgkmcnt(" #n ")" ::: "memory")
; #define PG8_BAR __builtin_amdgcn_s_barrier()
; #define PG8_SCHED __builtin_amdgcn_sched_barrier(0)
;   DI void operator()(const f32x4 (&acc)[2][2][4][2], const Unit& u, int wr, int wc, int fr, int fq, const PG8_LAS float* sR) const {
;     const int row0 = u.pm * BM + wr * 64 + fr, col0 = u.pn * BM + wc * 32 + 4 * fq;
; #pragma unroll
;     for (int ai = 0; ai < 2; ++ai) {
;       u32x2 sv[4][2][2];
;       if (X0 == nullptr) {
; #pragma unroll
;         for (int m = 0; m < 4; ++m)
; #pragma unroll
;           for (int bj = 0; bj < 2; ++bj)
; #pragma unroll
;             for (int n = 0; n < 2; ++n) sv[m][bj][n] = *(const u32x2*)(S + (size_t)(row0 + ai * HALF + m * 16) * 1024 + col0 + bj * HALF + n * 16);
; template <class Epi>
; DI void gemm_phase(PG8_LAS unsigned char* lds, const Gemm g, const StaticOrder& S, const Epi& E) {
;     ...
;       PG8_BAR; PG8_WAIT_L(0); PG8_MMA(1, 0, At, B0); PG8_BAR; PG8_SCHED;
;       PG8_STAGE(PG8_SB(1, 1), b3 + hstepB, voffB);
;       PG8_WAIT_V(6); PG8_BAR; PG8_MMA(1, 1, At, B1); PG8_BAR;
	s_waitcnt lgkmcnt(0)
	s_waitcnt lgkmcnt(0)
	v_mfma_f32_16x16x32_bf16 v[62:65], v[130:133], v[164:167], v[62:65]
	v_mfma_f32_16x16x32_bf16 v[58:61], v[156:159], v[164:167], v[58:61]
	v_mfma_f32_16x16x32_bf16 v[46:49], v[130:133], v[172:175], v[46:49]
	v_mfma_f32_16x16x32_bf16 v[42:45], v[156:159], v[172:175], v[42:45]
	v_mfma_f32_16x16x32_bf16 v[30:33], v[130:133], v[180:183], v[30:33]
	v_mfma_f32_16x16x32_bf16 v[26:29], v[156:159], v[180:183], v[26:29]
	v_mfma_f32_16x16x32_bf16 v[14:17], v[130:133], v[188:191], v[14:17]
	v_mfma_f32_16x16x32_bf16 v[10:13], v[156:159], v[188:191], v[10:13]
	v_mfma_f32_16x16x32_bf16 v[62:65], v[152:155], v[168:171], v[62:65]
	v_mfma_f32_16x16x32_bf16 v[58:61], v[160:163], v[168:171], v[58:61]
	v_mfma_f32_16x16x32_bf16 v[46:49], v[152:155], v[176:179], v[46:49]
	v_mfma_f32_16x16x32_bf16 v[42:45], v[160:163], v[176:179], v[42:45]
	v_mfma_f32_16x16x32_bf16 v[30:33], v[152:155], v[184:187], v[30:33]
	v_mfma_f32_16x16x32_bf16 v[26:29], v[160:163], v[184:187], v[26:29]
	v_mfma_f32_16x16x32_bf16 v[14:17], v[152:155], v[192:195], v[14:17]
	v_mfma_f32_16x16x32_bf16 v[10:13], v[160:163], v[192:195], v[10:13]
	s_barrier
	s_add_i32 s56, s56, s65
	v_lshl_add_u64 v[130:131], v[246:247], 0, s[86:87]
	s_mov_b32 m0, s56
	s_nop 0
	global_load_lds_dwordx4 v[130:131], off
	v_lshl_add_u64 v[130:131], v[248:249], 0, s[86:87]
	s_add_i32 m0, s56, 0x2000
	s_nop 0
	global_load_lds_dwordx4 v[130:131], off
	s_waitcnt vmcnt(6)
	s_barrier
	v_mfma_f32_16x16x32_bf16 v[54:57], v[196:199], v[164:167], v[54:57]
	v_mfma_f32_16x16x32_bf16 v[50:53], v[230:233], v[164:167], v[50:53]
	v_mfma_f32_16x16x32_bf16 v[38:41], v[196:199], v[172:175], v[38:41]
	v_mfma_f32_16x16x32_bf16 v[34:37], v[230:233], v[172:175], v[34:37]
	v_mfma_f32_16x16x32_bf16 v[22:25], v[196:199], v[180:183], v[22:25]
	v_mfma_f32_16x16x32_bf16 v[18:21], v[230:233], v[180:183], v[18:21]
	v_mfma_f32_16x16x32_bf16 v[6:9], v[196:199], v[188:191], v[6:9]
	v_mfma_f32_16x16x32_bf16 v[2:5], v[230:233], v[188:191], v[2:5]
	v_mfma_f32_16x16x32_bf16 v[54:57], v[226:229], v[168:171], v[54:57]
	v_mfma_f32_16x16x32_bf16 v[50:53], v[234:237], v[168:171], v[50:53]
	v_mfma_f32_16x16x32_bf16 v[38:41], v[226:229], v[176:179], v[38:41]
	v_mfma_f32_16x16x32_bf16 v[34:37], v[234:237], v[176:179], v[34:37]
	v_mfma_f32_16x16x32_bf16 v[22:25], v[226:229], v[184:187], v[22:25]
	v_mfma_f32_16x16x32_bf16 v[18:21], v[234:237], v[184:187], v[18:21]
	v_mfma_f32_16x16x32_bf16 v[6:9], v[226:229], v[192:195], v[6:9]
	v_mfma_f32_16x16x32_bf16 v[2:5], v[234:237], v[192:195], v[2:5]
	s_add_u32 s44, s44, 0x100
	s_addc_u32 s45, s45, 0
	s_add_u32 s79, s79, 0x100
	s_addc_u32 s80, s80, 0
	s_cmp_ge_u32 s81, s71
	s_mov_b32 s56, s81
	s_barrier
	s_cbranch_scc0 .LBB0_835
	s_and_b64 vcc, exec, s[52:53]
	s_cbranch_vccnz .Lres_x0_path
	v_and_b32_e32 v248, 15, v204
	v_lshrrev_b32_e32 v249, 4, v204
	v_and_b32_e32 v246, 1, v249
	v_lshrrev_b32_e32 v247, 1, v249
	v_lshl_or_b32 v246, v246, 1, v247
	v_lshl_add_u32 v246, v248, 2, v246
	v_lshlrev_b32_e32 v246, 2, v246
	v_and_b32_e32 v248, 3, v204
	v_lshrrev_b32_e32 v249, 2, v204
	v_and_b32_e32 v247, 1, v248
	v_lshrrev_b32_e32 v152, 1, v248
	v_lshl_or_b32 v247, v247, 1, v152
	v_lshl_add_u32 v247, v247, 4, v249
	v_lshlrev_b32_e32 v247, 2, v247
	v_and_b32_e32 v152, 64, v222
	v_add_u32_e32 v152, v152, v249
	v_lshl_add_u32 v152, s78, 8, v152
	v_and_b32_e32 v153, 0x60, v224
	v_lshl_or_b32 v153, v248, 3, v153
	v_lshl_or_b32 v154, s34, 8, v153
	v_lshlrev_b32_e32 v153, 10, v152
	v_add_u32_e32 v154, v154, v153
	v_mov_b32_e32 v155, 0
	v_lshl_add_u64 v[132:133], v[154:155], 1, s[22:23]
	v_mov_b64_e32 v[130:131], v[132:133]
	v_lshl_add_u32 v152, s78, 8, v222
	v_lshlrev_b32_e32 v154, 6, v152
	s_lshl_b32 s56, s34, 4
	s_lshl_b32 s57, s70, 2
	s_add_i32 s56, s56, s57
	v_add_u32_e32 v154, s56, v154
	v_lshl_add_u64 v[250:251], v[154:155], 0, s[92:93]
	s_mov_b32 s57, 0
	global_load_dwordx4 v[152:155], v[130:131], off
	global_load_dwordx4 v[156:159], v[130:131], off offset:256
	s_mov_b32 s56, 0x8000
	v_lshl_add_u64 v[130:131], v[130:131], 0, s[56:57]
	global_load_dwordx4 v[160:163], v[130:131], off
	global_load_dwordx4 v[164:167], v[130:131], off offset:256
	s_mov_b32 s56, 0x8000
	v_lshl_add_u64 v[130:131], v[130:131], 0, s[56:57]
	global_load_dwordx4 v[168:171], v[130:131], off
	global_load_dwordx4 v[172:175], v[130:131], off offset:256
	s_mov_b32 s56, 0x8000
	v_lshl_add_u64 v[130:131], v[130:131], 0, s[56:57]
	global_load_dwordx4 v[176:179], v[130:131], off
	global_load_dwordx4 v[180:183], v[130:131], off offset:256
	s_mov_b32 s56, 0x28000
	v_lshl_add_u64 v[130:131], v[130:131], 0, s[56:57]
	global_load_dwordx4 v[184:187], v[130:131], off
	global_load_dwordx4 v[188:191], v[130:131], off offset:256
	s_mov_b32 s56, 0x8000
	v_lshl_add_u64 v[130:131], v[130:131], 0, s[56:57]
	global_load_dwordx4 v[192:195], v[130:131], off
	global_load_dwordx4 v[196:199], v[130:131], off offset:256
	s_mov_b32 s56, 0x8000
	v_lshl_add_u64 v[130:131], v[130:131], 0, s[56:57]
	global_load_dwordx4 v[226:229], v[130:131], off
	global_load_dwordx4 v[230:233], v[130:131], off offset:256
	s_mov_b32 s56, 0x8000
	v_lshl_add_u64 v[130:131], v[130:131], 0, s[56:57]
	global_load_dwordx4 v[234:237], v[130:131], off
	global_load_dwordx4 v[238:241], v[130:131], off offset:256
	v_permlane16_swap_b32_e32 v126, v122
	v_permlane16_swap_b32_e32 v127, v123
	v_permlane16_swap_b32_e32 v128, v124
	v_permlane16_swap_b32_e32 v129, v125
	v_permlane16_swap_b32_e32 v118, v114
	v_permlane16_swap_b32_e32 v119, v115
	v_permlane16_swap_b32_e32 v120, v116
	v_permlane16_swap_b32_e32 v121, v117
	v_permlane16_swap_b32_e32 v110, v106
	v_permlane16_swap_b32_e32 v111, v107
; DI unsigned pk2(float lo, float hi) { f32x2 v = {lo, hi}; bf2_t r = __builtin_convertvector(v, bf2_t); return __builtin_bit_cast(unsigned, r); }
; DI float bflo(unsigned u) { return __uint_as_float(u << 16); }
; DI float bfhi(unsigned u) { return __uint_as_float(u & 0xffff0000u); }
;   DI void operator()(const f32x4 (&acc)[2][2][4][2], const Unit& u, int wr, int wc, int fr, int fq, const PG8_LAS float* sR) const {
;     ...
; #pragma unroll
;       for (int m = 0; m < 4; ++m) {
;         const int row = row0 + ai * HALF + m * 16;
;         const size_t ro = (size_t)row * 1024 + col0;
;         float ss = 0.f;
; #pragma unroll
;         for (int bj = 0; bj < 2; ++bj)
; #pragma unroll
;           for (int n = 0; n < 2; ++n) {
;             f32x4 v;
;             if (X0 != nullptr) v = *(const f32x4*)(X0 + ro + bj * HALF + n * 16);
;             else { const u32x2 q = sv[m][bj][n]; v[0] = bflo(q[0]); v[1] = bfhi(q[0]); v[2] = bflo(q[1]); v[3] = bfhi(q[1]); }
;             v += acc[ai][bj][m][n];
;             ss += v[0] * v[0] + v[1] * v[1] + v[2] * v[2] + v[3] * v[3];
;             if (!dry) { u32x2 q; q[0] = pk2(v[0], v[1]); q[1] = pk2(v[2], v[3]); *(u32x2*)(S + ro + bj * HALF + n * 16) = q; }
;           }
;         ss += __shfl_xor(ss, 16); ss += __shfl_xor(ss, 32);
;         if (!dry && fq == 0) ssq[(size_t)row * 16 + u.pn * 4 + wc] = ss;
	v_permlane16_swap_b32_e32 v112, v108
	v_permlane16_swap_b32_e32 v113, v109
	v_permlane16_swap_b32_e32 v102, v98
	v_permlane16_swap_b32_e32 v103, v99
	v_permlane16_swap_b32_e32 v104, v100
	v_permlane16_swap_b32_e32 v105, v101
	v_permlane16_swap_b32_e32 v94, v90
	v_permlane16_swap_b32_e32 v95, v91
	v_permlane16_swap_b32_e32 v96, v92
	v_permlane16_swap_b32_e32 v97, v93
	v_permlane16_swap_b32_e32 v86, v82
	v_permlane16_swap_b32_e32 v87, v83
	v_permlane16_swap_b32_e32 v88, v84
	v_permlane16_swap_b32_e32 v89, v85
	v_permlane16_swap_b32_e32 v78, v74
	v_permlane16_swap_b32_e32 v79, v75
	v_permlane16_swap_b32_e32 v80, v76
	v_permlane16_swap_b32_e32 v81, v77
	v_permlane16_swap_b32_e32 v70, v66
	v_permlane16_swap_b32_e32 v71, v67
	v_permlane16_swap_b32_e32 v72, v68
	v_permlane16_swap_b32_e32 v73, v69
	v_permlane16_swap_b32_e32 v62, v58
	v_permlane16_swap_b32_e32 v63, v59
	v_permlane16_swap_b32_e32 v64, v60
	v_permlane16_swap_b32_e32 v65, v61
	v_permlane16_swap_b32_e32 v54, v50
	v_permlane16_swap_b32_e32 v55, v51
	v_permlane16_swap_b32_e32 v56, v52
	v_permlane16_swap_b32_e32 v57, v53
	v_permlane16_swap_b32_e32 v46, v42
	v_permlane16_swap_b32_e32 v47, v43
	v_permlane16_swap_b32_e32 v48, v44
	v_permlane16_swap_b32_e32 v49, v45
	v_permlane16_swap_b32_e32 v38, v34
	v_permlane16_swap_b32_e32 v39, v35
	v_permlane16_swap_b32_e32 v40, v36
	v_permlane16_swap_b32_e32 v41, v37
	v_permlane16_swap_b32_e32 v30, v26
	v_permlane16_swap_b32_e32 v31, v27
	v_permlane16_swap_b32_e32 v32, v28
	v_permlane16_swap_b32_e32 v33, v29
	v_permlane16_swap_b32_e32 v22, v18
	v_permlane16_swap_b32_e32 v23, v19
	v_permlane16_swap_b32_e32 v24, v20
	v_permlane16_swap_b32_e32 v25, v21
	v_permlane16_swap_b32_e32 v14, v10
	v_permlane16_swap_b32_e32 v15, v11
	v_permlane16_swap_b32_e32 v16, v12
	v_permlane16_swap_b32_e32 v17, v13
	v_permlane16_swap_b32_e32 v6, v2
	v_permlane16_swap_b32_e32 v7, v3
	v_permlane16_swap_b32_e32 v8, v4
	v_permlane16_swap_b32_e32 v9, v5
	s_waitcnt vmcnt(15)
	ds_bpermute_b32 v152, v246, v152
	ds_bpermute_b32 v153, v246, v153
	ds_bpermute_b32 v154, v246, v154
	ds_bpermute_b32 v155, v246, v155
	s_waitcnt vmcnt(14)
	ds_bpermute_b32 v156, v246, v156
	ds_bpermute_b32 v157, v246, v157
	ds_bpermute_b32 v158, v246, v158
	ds_bpermute_b32 v159, v246, v159
	s_waitcnt lgkmcnt(4)
	v_lshlrev_b32_e32 v242, 16, v152
	v_and_b32_e32 v243, 0xffff0000, v152
	v_lshlrev_b32_e32 v244, 16, v153
	v_and_b32_e32 v245, 0xffff0000, v153
	v_pk_add_f32 v[126:127], v[126:127], v[242:243]
	v_pk_add_f32 v[128:129], v[128:129], v[244:245]
	v_lshlrev_b32_e32 v242, 16, v154
	v_and_b32_e32 v243, 0xffff0000, v154
	v_lshlrev_b32_e32 v244, 16, v155
	v_and_b32_e32 v245, 0xffff0000, v155
	v_pk_add_f32 v[122:123], v[122:123], v[242:243]
	v_pk_add_f32 v[124:125], v[124:125], v[244:245]
	v_mul_f32_e32 v130, v126, v126
	v_mul_f32_e32 v131, v127, v127
	v_fmac_f32_e32 v130, v128, v128
	v_fmac_f32_e32 v131, v129, v129
	v_fmac_f32_e32 v130, v122, v122
	v_fmac_f32_e32 v131, v123, v123
	v_fmac_f32_e32 v130, v124, v124
	v_fmac_f32_e32 v131, v125, v125
	v_cvt_pk_bf16_f32 v126, v126, v127
	v_cvt_pk_bf16_f32 v127, v128, v129
	v_cvt_pk_bf16_f32 v128, v122, v123
	v_cvt_pk_bf16_f32 v129, v124, v125
	ds_bpermute_b32 v126, v247, v126
	ds_bpermute_b32 v127, v247, v127
	ds_bpermute_b32 v128, v247, v128
	ds_bpermute_b32 v129, v247, v129
	s_waitcnt vmcnt(13)
	ds_bpermute_b32 v160, v246, v160
	ds_bpermute_b32 v161, v246, v161
	ds_bpermute_b32 v162, v246, v162
	ds_bpermute_b32 v163, v246, v163
	s_waitcnt lgkmcnt(8)
	v_lshlrev_b32_e32 v242, 16, v156
	v_and_b32_e32 v243, 0xffff0000, v156
	v_lshlrev_b32_e32 v244, 16, v157
	v_and_b32_e32 v245, 0xffff0000, v157
	v_pk_add_f32 v[118:119], v[118:119], v[242:243]
	v_pk_add_f32 v[120:121], v[120:121], v[244:245]
	v_lshlrev_b32_e32 v242, 16, v158
	v_and_b32_e32 v243, 0xffff0000, v158
	v_lshlrev_b32_e32 v244, 16, v159
	v_and_b32_e32 v245, 0xffff0000, v159
	v_pk_add_f32 v[114:115], v[114:115], v[242:243]
	v_pk_add_f32 v[116:117], v[116:117], v[244:245]
	v_fmac_f32_e32 v130, v118, v118
	v_fmac_f32_e32 v131, v119, v119
	v_fmac_f32_e32 v130, v120, v120
	v_fmac_f32_e32 v131, v121, v121
	v_fmac_f32_e32 v130, v114, v114
	v_fmac_f32_e32 v131, v115, v115
	v_fmac_f32_e32 v130, v116, v116
	v_fmac_f32_e32 v131, v117, v117
	v_cvt_pk_bf16_f32 v118, v118, v119
	v_cvt_pk_bf16_f32 v119, v120, v121
	v_cvt_pk_bf16_f32 v120, v114, v115
	v_cvt_pk_bf16_f32 v121, v116, v117
	ds_bpermute_b32 v118, v247, v118
	ds_bpermute_b32 v119, v247, v119
	ds_bpermute_b32 v120, v247, v120
	ds_bpermute_b32 v121, v247, v121
	v_add_f32_e32 v130, v130, v131
	v_mov_b32_e32 v131, v130
	s_nop 1
	v_permlane16_swap_b32_e32 v130, v131
	s_nop 1
	v_add_f32_e32 v130, v130, v131
	v_mov_b32_e32 v131, v130
	s_nop 1
	v_permlane32_swap_b32_e32 v130, v131
	s_nop 1
	v_add_f32_e32 v130, v130, v131
	s_and_saveexec_b64 s[58:59], s[40:41]
	global_store_dword v[250:251], v130, off
	s_or_b64 exec, exec, s[58:59]
	s_mov_b32 s56, 0x400
	v_lshl_add_u64 v[250:251], v[250:251], 0, s[56:57]
	s_waitcnt vmcnt(13)
	ds_bpermute_b32 v164, v246, v164
	ds_bpermute_b32 v165, v246, v165
	ds_bpermute_b32 v166, v246, v166
	ds_bpermute_b32 v167, v246, v167
	s_waitcnt lgkmcnt(12)
	global_store_dwordx4 v[132:133], v[126:129], off
	s_waitcnt lgkmcnt(8)
; DI unsigned pk2(float lo, float hi) { f32x2 v = {lo, hi}; bf2_t r = __builtin_convertvector(v, bf2_t); return __builtin_bit_cast(unsigned, r); }
; DI float bflo(unsigned u) { return __uint_as_float(u << 16); }
; DI float bfhi(unsigned u) { return __uint_as_float(u & 0xffff0000u); }
;   DI void operator()(const f32x4 (&acc)[2][2][4][2], const Unit& u, int wr, int wc, int fr, int fq, const PG8_LAS float* sR) const {
;     ...
; #pragma unroll
;       for (int m = 0; m < 4; ++m) {
;         const int row = row0 + ai * HALF + m * 16;
;         const size_t ro = (size_t)row * 1024 + col0;
;         float ss = 0.f;
; #pragma unroll
;         for (int bj = 0; bj < 2; ++bj)
; #pragma unroll
;           for (int n = 0; n < 2; ++n) {
;             f32x4 v;
;             if (X0 != nullptr) v = *(const f32x4*)(X0 + ro + bj * HALF + n * 16);
;             else { const u32x2 q = sv[m][bj][n]; v[0] = bflo(q[0]); v[1] = bfhi(q[0]); v[2] = bflo(q[1]); v[3] = bfhi(q[1]); }
;             v += acc[ai][bj][m][n];
;             ss += v[0] * v[0] + v[1] * v[1] + v[2] * v[2] + v[3] * v[3];
;             if (!dry) { u32x2 q; q[0] = pk2(v[0], v[1]); q[1] = pk2(v[2], v[3]); *(u32x2*)(S + ro + bj * HALF + n * 16) = q; }
;           }
;         ss += __shfl_xor(ss, 16); ss += __shfl_xor(ss, 32);
;         if (!dry && fq == 0) ssq[(size_t)row * 16 + u.pn * 4 + wc] = ss;
	v_lshlrev_b32_e32 v242, 16, v160
	v_and_b32_e32 v243, 0xffff0000, v160
	v_lshlrev_b32_e32 v244, 16, v161
	v_and_b32_e32 v245, 0xffff0000, v161
	v_pk_add_f32 v[110:111], v[110:111], v[242:243]
	v_pk_add_f32 v[112:113], v[112:113], v[244:245]
	v_lshlrev_b32_e32 v242, 16, v162
	v_and_b32_e32 v243, 0xffff0000, v162
	v_lshlrev_b32_e32 v244, 16, v163
	v_and_b32_e32 v245, 0xffff0000, v163
	v_pk_add_f32 v[106:107], v[106:107], v[242:243]
	v_pk_add_f32 v[108:109], v[108:109], v[244:245]
	v_mul_f32_e32 v130, v110, v110
	v_mul_f32_e32 v131, v111, v111
	v_fmac_f32_e32 v130, v112, v112
	v_fmac_f32_e32 v131, v113, v113
	v_fmac_f32_e32 v130, v106, v106
	v_fmac_f32_e32 v131, v107, v107
	v_fmac_f32_e32 v130, v108, v108
	v_fmac_f32_e32 v131, v109, v109
	v_cvt_pk_bf16_f32 v110, v110, v111
	v_cvt_pk_bf16_f32 v111, v112, v113
	v_cvt_pk_bf16_f32 v112, v106, v107
	v_cvt_pk_bf16_f32 v113, v108, v109
	ds_bpermute_b32 v110, v247, v110
	ds_bpermute_b32 v111, v247, v111
	ds_bpermute_b32 v112, v247, v112
	ds_bpermute_b32 v113, v247, v113
	s_waitcnt vmcnt(13)
	ds_bpermute_b32 v168, v246, v168
	ds_bpermute_b32 v169, v246, v169
	ds_bpermute_b32 v170, v246, v170
	ds_bpermute_b32 v171, v246, v171
	s_waitcnt lgkmcnt(12)
	global_store_dwordx4 v[132:133], v[118:121], off offset:256
	s_mov_b32 s56, 0x8000
	v_lshl_add_u64 v[132:133], v[132:133], 0, s[56:57]
	s_waitcnt lgkmcnt(8)
	v_lshlrev_b32_e32 v242, 16, v164
	v_and_b32_e32 v243, 0xffff0000, v164
	v_lshlrev_b32_e32 v244, 16, v165
	v_and_b32_e32 v245, 0xffff0000, v165
	v_pk_add_f32 v[102:103], v[102:103], v[242:243]
	v_pk_add_f32 v[104:105], v[104:105], v[244:245]
	v_lshlrev_b32_e32 v242, 16, v166
	v_and_b32_e32 v243, 0xffff0000, v166
	v_lshlrev_b32_e32 v244, 16, v167
	v_and_b32_e32 v245, 0xffff0000, v167
	v_pk_add_f32 v[98:99], v[98:99], v[242:243]
	v_pk_add_f32 v[100:101], v[100:101], v[244:245]
	v_fmac_f32_e32 v130, v102, v102
	v_fmac_f32_e32 v131, v103, v103
	v_fmac_f32_e32 v130, v104, v104
	v_fmac_f32_e32 v131, v105, v105
	v_fmac_f32_e32 v130, v98, v98
	v_fmac_f32_e32 v131, v99, v99
	v_fmac_f32_e32 v130, v100, v100
	v_fmac_f32_e32 v131, v101, v101
	v_cvt_pk_bf16_f32 v102, v102, v103
	v_cvt_pk_bf16_f32 v103, v104, v105
	v_cvt_pk_bf16_f32 v104, v98, v99
	v_cvt_pk_bf16_f32 v105, v100, v101
	ds_bpermute_b32 v102, v247, v102
	ds_bpermute_b32 v103, v247, v103
	ds_bpermute_b32 v104, v247, v104
	ds_bpermute_b32 v105, v247, v105
	v_add_f32_e32 v130, v130, v131
	v_mov_b32_e32 v131, v130
	s_nop 1
	v_permlane16_swap_b32_e32 v130, v131
	s_nop 1
	v_add_f32_e32 v130, v130, v131
	v_mov_b32_e32 v131, v130
	s_nop 1
	v_permlane32_swap_b32_e32 v130, v131
	s_nop 1
	v_add_f32_e32 v130, v130, v131
	s_and_saveexec_b64 s[58:59], s[40:41]
	global_store_dword v[250:251], v130, off
	s_or_b64 exec, exec, s[58:59]
	s_mov_b32 s56, 0x400
	v_lshl_add_u64 v[250:251], v[250:251], 0, s[56:57]
	s_waitcnt vmcnt(14)
	ds_bpermute_b32 v172, v246, v172
	ds_bpermute_b32 v173, v246, v173
	ds_bpermute_b32 v174, v246, v174
	ds_bpermute_b32 v175, v246, v175
	s_waitcnt lgkmcnt(12)
	global_store_dwordx4 v[132:133], v[110:113], off
	s_waitcnt lgkmcnt(8)
	v_lshlrev_b32_e32 v242, 16, v168
	v_and_b32_e32 v243, 0xffff0000, v168
	v_lshlrev_b32_e32 v244, 16, v169
	v_and_b32_e32 v245, 0xffff0000, v169
	v_pk_add_f32 v[94:95], v[94:95], v[242:243]
	v_pk_add_f32 v[96:97], v[96:97], v[244:245]
	v_lshlrev_b32_e32 v242, 16, v170
	v_and_b32_e32 v243, 0xffff0000, v170
	v_lshlrev_b32_e32 v244, 16, v171
	v_and_b32_e32 v245, 0xffff0000, v171
	v_pk_add_f32 v[90:91], v[90:91], v[242:243]
	v_pk_add_f32 v[92:93], v[92:93], v[244:245]
	v_mul_f32_e32 v130, v94, v94
	v_mul_f32_e32 v131, v95, v95
	v_fmac_f32_e32 v130, v96, v96
	v_fmac_f32_e32 v131, v97, v97
	v_fmac_f32_e32 v130, v90, v90
	v_fmac_f32_e32 v131, v91, v91
	v_fmac_f32_e32 v130, v92, v92
	v_fmac_f32_e32 v131, v93, v93
	v_cvt_pk_bf16_f32 v94, v94, v95
	v_cvt_pk_bf16_f32 v95, v96, v97
	v_cvt_pk_bf16_f32 v96, v90, v91
	v_cvt_pk_bf16_f32 v97, v92, v93
	ds_bpermute_b32 v94, v247, v94
	ds_bpermute_b32 v95, v247, v95
	ds_bpermute_b32 v96, v247, v96
	ds_bpermute_b32 v97, v247, v97
	s_waitcnt vmcnt(14)
	ds_bpermute_b32 v176, v246, v176
	ds_bpermute_b32 v177, v246, v177
	ds_bpermute_b32 v178, v246, v178
	ds_bpermute_b32 v179, v246, v179
	s_waitcnt lgkmcnt(12)
	global_store_dwordx4 v[132:133], v[102:105], off offset:256
	s_mov_b32 s56, 0x8000
	v_lshl_add_u64 v[132:133], v[132:133], 0, s[56:57]
	s_waitcnt lgkmcnt(8)
	v_lshlrev_b32_e32 v242, 16, v172
	v_and_b32_e32 v243, 0xffff0000, v172
	v_lshlrev_b32_e32 v244, 16, v173
	v_and_b32_e32 v245, 0xffff0000, v173
	v_pk_add_f32 v[86:87], v[86:87], v[242:243]
	v_pk_add_f32 v[88:89], v[88:89], v[244:245]
	v_lshlrev_b32_e32 v242, 16, v174
	v_and_b32_e32 v243, 0xffff0000, v174
	v_lshlrev_b32_e32 v244, 16, v175
	v_and_b32_e32 v245, 0xffff0000, v175
	v_pk_add_f32 v[82:83], v[82:83], v[242:243]
	v_pk_add_f32 v[84:85], v[84:85], v[244:245]
	v_fmac_f32_e32 v130, v86, v86
	v_fmac_f32_e32 v131, v87, v87
	v_fmac_f32_e32 v130, v88, v88
	v_fmac_f32_e32 v131, v89, v89
	v_fmac_f32_e32 v130, v82, v82
	v_fmac_f32_e32 v131, v83, v83
	v_fmac_f32_e32 v130, v84, v84
	v_fmac_f32_e32 v131, v85, v85
	v_cvt_pk_bf16_f32 v86, v86, v87
	v_cvt_pk_bf16_f32 v87, v88, v89
	v_cvt_pk_bf16_f32 v88, v82, v83
	v_cvt_pk_bf16_f32 v89, v84, v85
	ds_bpermute_b32 v86, v247, v86
	ds_bpermute_b32 v87, v247, v87
	ds_bpermute_b32 v88, v247, v88
	ds_bpermute_b32 v89, v247, v89
	v_add_f32_e32 v130, v130, v131
	v_mov_b32_e32 v131, v130
	s_nop 1
	v_permlane16_swap_b32_e32 v130, v131
	s_nop 1
	v_add_f32_e32 v130, v130, v131
	v_mov_b32_e32 v131, v130
	s_nop 1
	v_permlane32_swap_b32_e32 v130, v131
	s_nop 1
	v_add_f32_e32 v130, v130, v131
	s_and_saveexec_b64 s[58:59], s[40:41]
	global_store_dword v[250:251], v130, off
	s_or_b64 exec, exec, s[58:59]
	s_mov_b32 s56, 0x400
	v_lshl_add_u64 v[250:251], v[250:251], 0, s[56:57]
	s_waitcnt vmcnt(15)
; DI unsigned pk2(float lo, float hi) { f32x2 v = {lo, hi}; bf2_t r = __builtin_convertvector(v, bf2_t); return __builtin_bit_cast(unsigned, r); }
; DI float bflo(unsigned u) { return __uint_as_float(u << 16); }
; DI float bfhi(unsigned u) { return __uint_as_float(u & 0xffff0000u); }
;   DI void operator()(const f32x4 (&acc)[2][2][4][2], const Unit& u, int wr, int wc, int fr, int fq, const PG8_LAS float* sR) const {
;     ...
; #pragma unroll
;       for (int m = 0; m < 4; ++m) {
;         const int row = row0 + ai * HALF + m * 16;
;         const size_t ro = (size_t)row * 1024 + col0;
;         float ss = 0.f;
; #pragma unroll
;         for (int bj = 0; bj < 2; ++bj)
; #pragma unroll
;           for (int n = 0; n < 2; ++n) {
;             f32x4 v;
;             if (X0 != nullptr) v = *(const f32x4*)(X0 + ro + bj * HALF + n * 16);
;             else { const u32x2 q = sv[m][bj][n]; v[0] = bflo(q[0]); v[1] = bfhi(q[0]); v[2] = bflo(q[1]); v[3] = bfhi(q[1]); }
;             v += acc[ai][bj][m][n];
;             ss += v[0] * v[0] + v[1] * v[1] + v[2] * v[2] + v[3] * v[3];
;             if (!dry) { u32x2 q; q[0] = pk2(v[0], v[1]); q[1] = pk2(v[2], v[3]); *(u32x2*)(S + ro + bj * HALF + n * 16) = q; }
;           }
;         ss += __shfl_xor(ss, 16); ss += __shfl_xor(ss, 32);
;         if (!dry && fq == 0) ssq[(size_t)row * 16 + u.pn * 4 + wc] = ss;
	ds_bpermute_b32 v180, v246, v180
	ds_bpermute_b32 v181, v246, v181
	ds_bpermute_b32 v182, v246, v182
	ds_bpermute_b32 v183, v246, v183
	s_waitcnt lgkmcnt(12)
	global_store_dwordx4 v[132:133], v[94:97], off
	s_waitcnt lgkmcnt(8)
	v_lshlrev_b32_e32 v242, 16, v176
	v_and_b32_e32 v243, 0xffff0000, v176
	v_lshlrev_b32_e32 v244, 16, v177
	v_and_b32_e32 v245, 0xffff0000, v177
	v_pk_add_f32 v[78:79], v[78:79], v[242:243]
	v_pk_add_f32 v[80:81], v[80:81], v[244:245]
	v_lshlrev_b32_e32 v242, 16, v178
	v_and_b32_e32 v243, 0xffff0000, v178
	v_lshlrev_b32_e32 v244, 16, v179
	v_and_b32_e32 v245, 0xffff0000, v179
	v_pk_add_f32 v[74:75], v[74:75], v[242:243]
	v_pk_add_f32 v[76:77], v[76:77], v[244:245]
	v_mul_f32_e32 v130, v78, v78
	v_mul_f32_e32 v131, v79, v79
	v_fmac_f32_e32 v130, v80, v80
	v_fmac_f32_e32 v131, v81, v81
	v_fmac_f32_e32 v130, v74, v74
	v_fmac_f32_e32 v131, v75, v75
	v_fmac_f32_e32 v130, v76, v76
	v_fmac_f32_e32 v131, v77, v77
	v_cvt_pk_bf16_f32 v78, v78, v79
	v_cvt_pk_bf16_f32 v79, v80, v81
	v_cvt_pk_bf16_f32 v80, v74, v75
	v_cvt_pk_bf16_f32 v81, v76, v77
	ds_bpermute_b32 v78, v247, v78
	ds_bpermute_b32 v79, v247, v79
	ds_bpermute_b32 v80, v247, v80
	ds_bpermute_b32 v81, v247, v81
	s_waitcnt vmcnt(15)
	ds_bpermute_b32 v184, v246, v184
	ds_bpermute_b32 v185, v246, v185
	ds_bpermute_b32 v186, v246, v186
	ds_bpermute_b32 v187, v246, v187
	s_waitcnt lgkmcnt(12)
	global_store_dwordx4 v[132:133], v[86:89], off offset:256
	s_mov_b32 s56, 0x8000
	v_lshl_add_u64 v[132:133], v[132:133], 0, s[56:57]
	s_waitcnt lgkmcnt(8)
	v_lshlrev_b32_e32 v242, 16, v180
	v_and_b32_e32 v243, 0xffff0000, v180
	v_lshlrev_b32_e32 v244, 16, v181
	v_and_b32_e32 v245, 0xffff0000, v181
	v_pk_add_f32 v[70:71], v[70:71], v[242:243]
	v_pk_add_f32 v[72:73], v[72:73], v[244:245]
	v_lshlrev_b32_e32 v242, 16, v182
	v_and_b32_e32 v243, 0xffff0000, v182
	v_lshlrev_b32_e32 v244, 16, v183
	v_and_b32_e32 v245, 0xffff0000, v183
	v_pk_add_f32 v[66:67], v[66:67], v[242:243]
	v_pk_add_f32 v[68:69], v[68:69], v[244:245]
	v_fmac_f32_e32 v130, v70, v70
	v_fmac_f32_e32 v131, v71, v71
	v_fmac_f32_e32 v130, v72, v72
	v_fmac_f32_e32 v131, v73, v73
	v_fmac_f32_e32 v130, v66, v66
	v_fmac_f32_e32 v131, v67, v67
	v_fmac_f32_e32 v130, v68, v68
	v_fmac_f32_e32 v131, v69, v69
	v_cvt_pk_bf16_f32 v70, v70, v71
	v_cvt_pk_bf16_f32 v71, v72, v73
	v_cvt_pk_bf16_f32 v72, v66, v67
	v_cvt_pk_bf16_f32 v73, v68, v69
	ds_bpermute_b32 v70, v247, v70
	ds_bpermute_b32 v71, v247, v71
	ds_bpermute_b32 v72, v247, v72
	ds_bpermute_b32 v73, v247, v73
	v_add_f32_e32 v130, v130, v131
	v_mov_b32_e32 v131, v130
	s_nop 1
	v_permlane16_swap_b32_e32 v130, v131
	s_nop 1
	v_add_f32_e32 v130, v130, v131
	v_mov_b32_e32 v131, v130
	s_nop 1
	v_permlane32_swap_b32_e32 v130, v131
	s_nop 1
	v_add_f32_e32 v130, v130, v131
	s_and_saveexec_b64 s[58:59], s[40:41]
	global_store_dword v[250:251], v130, off
	s_or_b64 exec, exec, s[58:59]
	s_mov_b32 s56, 0x1400
	v_lshl_add_u64 v[250:251], v[250:251], 0, s[56:57]
	s_waitcnt vmcnt(16)
	ds_bpermute_b32 v188, v246, v188
	ds_bpermute_b32 v189, v246, v189
	ds_bpermute_b32 v190, v246, v190
	ds_bpermute_b32 v191, v246, v191
	s_waitcnt lgkmcnt(12)
	global_store_dwordx4 v[132:133], v[78:81], off
	s_waitcnt lgkmcnt(8)
	v_lshlrev_b32_e32 v242, 16, v184
	v_and_b32_e32 v243, 0xffff0000, v184
	v_lshlrev_b32_e32 v244, 16, v185
	v_and_b32_e32 v245, 0xffff0000, v185
	v_pk_add_f32 v[62:63], v[62:63], v[242:243]
	v_pk_add_f32 v[64:65], v[64:65], v[244:245]
	v_lshlrev_b32_e32 v242, 16, v186
	v_and_b32_e32 v243, 0xffff0000, v186
	v_lshlrev_b32_e32 v244, 16, v187
	v_and_b32_e32 v245, 0xffff0000, v187
	v_pk_add_f32 v[58:59], v[58:59], v[242:243]
	v_pk_add_f32 v[60:61], v[60:61], v[244:245]
	v_mul_f32_e32 v130, v62, v62
	v_mul_f32_e32 v131, v63, v63
	v_fmac_f32_e32 v130, v64, v64
	v_fmac_f32_e32 v131, v65, v65
	v_fmac_f32_e32 v130, v58, v58
	v_fmac_f32_e32 v131, v59, v59
	v_fmac_f32_e32 v130, v60, v60
	v_fmac_f32_e32 v131, v61, v61
	v_cvt_pk_bf16_f32 v62, v62, v63
	v_cvt_pk_bf16_f32 v63, v64, v65
	v_cvt_pk_bf16_f32 v64, v58, v59
	v_cvt_pk_bf16_f32 v65, v60, v61
	ds_bpermute_b32 v62, v247, v62
	ds_bpermute_b32 v63, v247, v63
	ds_bpermute_b32 v64, v247, v64
	ds_bpermute_b32 v65, v247, v65
	s_waitcnt vmcnt(16)
	ds_bpermute_b32 v192, v246, v192
	ds_bpermute_b32 v193, v246, v193
	ds_bpermute_b32 v194, v246, v194
	ds_bpermute_b32 v195, v246, v195
	s_waitcnt lgkmcnt(12)
	global_store_dwordx4 v[132:133], v[70:73], off offset:256
	s_mov_b32 s56, 0x28000
	v_lshl_add_u64 v[132:133], v[132:133], 0, s[56:57]
	s_waitcnt lgkmcnt(8)
	v_lshlrev_b32_e32 v242, 16, v188
	v_and_b32_e32 v243, 0xffff0000, v188
	v_lshlrev_b32_e32 v244, 16, v189
	v_and_b32_e32 v245, 0xffff0000, v189
	v_pk_add_f32 v[54:55], v[54:55], v[242:243]
	v_pk_add_f32 v[56:57], v[56:57], v[244:245]
	v_lshlrev_b32_e32 v242, 16, v190
	v_and_b32_e32 v243, 0xffff0000, v190
	v_lshlrev_b32_e32 v244, 16, v191
	v_and_b32_e32 v245, 0xffff0000, v191
	v_pk_add_f32 v[50:51], v[50:51], v[242:243]
	v_pk_add_f32 v[52:53], v[52:53], v[244:245]
	v_fmac_f32_e32 v130, v54, v54
	v_fmac_f32_e32 v131, v55, v55
	v_fmac_f32_e32 v130, v56, v56
	v_fmac_f32_e32 v131, v57, v57
	v_fmac_f32_e32 v130, v50, v50
	v_fmac_f32_e32 v131, v51, v51
	v_fmac_f32_e32 v130, v52, v52
	v_fmac_f32_e32 v131, v53, v53
	v_cvt_pk_bf16_f32 v54, v54, v55
	v_cvt_pk_bf16_f32 v55, v56, v57
	v_cvt_pk_bf16_f32 v56, v50, v51
	v_cvt_pk_bf16_f32 v57, v52, v53
	ds_bpermute_b32 v54, v247, v54
	ds_bpermute_b32 v55, v247, v55
	ds_bpermute_b32 v56, v247, v56
	ds_bpermute_b32 v57, v247, v57
	v_add_f32_e32 v130, v130, v131
	v_mov_b32_e32 v131, v130
	s_nop 1
	v_permlane16_swap_b32_e32 v130, v131
	s_nop 1
	v_add_f32_e32 v130, v130, v131
	v_mov_b32_e32 v131, v130
	s_nop 1
	v_permlane32_swap_b32_e32 v130, v131
	s_nop 1
	v_add_f32_e32 v130, v130, v131
	s_and_saveexec_b64 s[58:59], s[40:41]
	global_store_dword v[250:251], v130, off
	s_or_b64 exec, exec, s[58:59]
	s_mov_b32 s56, 0x400
	v_lshl_add_u64 v[250:251], v[250:251], 0, s[56:57]
	s_waitcnt vmcnt(17)
; DI unsigned pk2(float lo, float hi) { f32x2 v = {lo, hi}; bf2_t r = __builtin_convertvector(v, bf2_t); return __builtin_bit_cast(unsigned, r); }
; DI float bflo(unsigned u) { return __uint_as_float(u << 16); }
; DI float bfhi(unsigned u) { return __uint_as_float(u & 0xffff0000u); }
;   DI void operator()(const f32x4 (&acc)[2][2][4][2], const Unit& u, int wr, int wc, int fr, int fq, const PG8_LAS float* sR) const {
;     ...
; #pragma unroll
;       for (int m = 0; m < 4; ++m) {
;         const int row = row0 + ai * HALF + m * 16;
;         const size_t ro = (size_t)row * 1024 + col0;
;         float ss = 0.f;
; #pragma unroll
;         for (int bj = 0; bj < 2; ++bj)
; #pragma unroll
;           for (int n = 0; n < 2; ++n) {
;             f32x4 v;
;             if (X0 != nullptr) v = *(const f32x4*)(X0 + ro + bj * HALF + n * 16);
;             else { const u32x2 q = sv[m][bj][n]; v[0] = bflo(q[0]); v[1] = bfhi(q[0]); v[2] = bflo(q[1]); v[3] = bfhi(q[1]); }
;             v += acc[ai][bj][m][n];
;             ss += v[0] * v[0] + v[1] * v[1] + v[2] * v[2] + v[3] * v[3];
;             if (!dry) { u32x2 q; q[0] = pk2(v[0], v[1]); q[1] = pk2(v[2], v[3]); *(u32x2*)(S + ro + bj * HALF + n * 16) = q; }
;           }
;         ss += __shfl_xor(ss, 16); ss += __shfl_xor(ss, 32);
;         if (!dry && fq == 0) ssq[(size_t)row * 16 + u.pn * 4 + wc] = ss;
	ds_bpermute_b32 v196, v246, v196
	ds_bpermute_b32 v197, v246, v197
	ds_bpermute_b32 v198, v246, v198
	ds_bpermute_b32 v199, v246, v199
	s_waitcnt lgkmcnt(12)
	global_store_dwordx4 v[132:133], v[62:65], off
	s_waitcnt lgkmcnt(8)
	v_lshlrev_b32_e32 v242, 16, v192
	v_and_b32_e32 v243, 0xffff0000, v192
	v_lshlrev_b32_e32 v244, 16, v193
	v_and_b32_e32 v245, 0xffff0000, v193
	v_pk_add_f32 v[46:47], v[46:47], v[242:243]
	v_pk_add_f32 v[48:49], v[48:49], v[244:245]
	v_lshlrev_b32_e32 v242, 16, v194
	v_and_b32_e32 v243, 0xffff0000, v194
	v_lshlrev_b32_e32 v244, 16, v195
	v_and_b32_e32 v245, 0xffff0000, v195
	v_pk_add_f32 v[42:43], v[42:43], v[242:243]
	v_pk_add_f32 v[44:45], v[44:45], v[244:245]
	v_mul_f32_e32 v130, v46, v46
	v_mul_f32_e32 v131, v47, v47
	v_fmac_f32_e32 v130, v48, v48
	v_fmac_f32_e32 v131, v49, v49
	v_fmac_f32_e32 v130, v42, v42
	v_fmac_f32_e32 v131, v43, v43
	v_fmac_f32_e32 v130, v44, v44
	v_fmac_f32_e32 v131, v45, v45
	v_cvt_pk_bf16_f32 v46, v46, v47
	v_cvt_pk_bf16_f32 v47, v48, v49
	v_cvt_pk_bf16_f32 v48, v42, v43
	v_cvt_pk_bf16_f32 v49, v44, v45
	ds_bpermute_b32 v46, v247, v46
	ds_bpermute_b32 v47, v247, v47
	ds_bpermute_b32 v48, v247, v48
	ds_bpermute_b32 v49, v247, v49
	s_waitcnt vmcnt(17)
	ds_bpermute_b32 v226, v246, v226
	ds_bpermute_b32 v227, v246, v227
	ds_bpermute_b32 v228, v246, v228
	ds_bpermute_b32 v229, v246, v229
	s_waitcnt lgkmcnt(12)
	global_store_dwordx4 v[132:133], v[54:57], off offset:256
	s_mov_b32 s56, 0x8000
	v_lshl_add_u64 v[132:133], v[132:133], 0, s[56:57]
	s_waitcnt lgkmcnt(8)
	v_lshlrev_b32_e32 v242, 16, v196
	v_and_b32_e32 v243, 0xffff0000, v196
	v_lshlrev_b32_e32 v244, 16, v197
	v_and_b32_e32 v245, 0xffff0000, v197
	v_pk_add_f32 v[38:39], v[38:39], v[242:243]
	v_pk_add_f32 v[40:41], v[40:41], v[244:245]
	v_lshlrev_b32_e32 v242, 16, v198
	v_and_b32_e32 v243, 0xffff0000, v198
	v_lshlrev_b32_e32 v244, 16, v199
	v_and_b32_e32 v245, 0xffff0000, v199
	v_pk_add_f32 v[34:35], v[34:35], v[242:243]
	v_pk_add_f32 v[36:37], v[36:37], v[244:245]
	v_fmac_f32_e32 v130, v38, v38
	v_fmac_f32_e32 v131, v39, v39
	v_fmac_f32_e32 v130, v40, v40
	v_fmac_f32_e32 v131, v41, v41
	v_fmac_f32_e32 v130, v34, v34
	v_fmac_f32_e32 v131, v35, v35
	v_fmac_f32_e32 v130, v36, v36
	v_fmac_f32_e32 v131, v37, v37
	v_cvt_pk_bf16_f32 v38, v38, v39
	v_cvt_pk_bf16_f32 v39, v40, v41
	v_cvt_pk_bf16_f32 v40, v34, v35
	v_cvt_pk_bf16_f32 v41, v36, v37
	ds_bpermute_b32 v38, v247, v38
	ds_bpermute_b32 v39, v247, v39
	ds_bpermute_b32 v40, v247, v40
	ds_bpermute_b32 v41, v247, v41
	v_add_f32_e32 v130, v130, v131
	v_mov_b32_e32 v131, v130
	s_nop 1
	v_permlane16_swap_b32_e32 v130, v131
	s_nop 1
	v_add_f32_e32 v130, v130, v131
	v_mov_b32_e32 v131, v130
	s_nop 1
	v_permlane32_swap_b32_e32 v130, v131
	s_nop 1
	v_add_f32_e32 v130, v130, v131
	s_and_saveexec_b64 s[58:59], s[40:41]
	global_store_dword v[250:251], v130, off
	s_or_b64 exec, exec, s[58:59]
	s_mov_b32 s56, 0x400
	v_lshl_add_u64 v[250:251], v[250:251], 0, s[56:57]
	s_waitcnt vmcnt(18)
	ds_bpermute_b32 v230, v246, v230
	ds_bpermute_b32 v231, v246, v231
	ds_bpermute_b32 v232, v246, v232
	ds_bpermute_b32 v233, v246, v233
	s_waitcnt lgkmcnt(12)
	global_store_dwordx4 v[132:133], v[46:49], off
	s_waitcnt lgkmcnt(8)
	v_lshlrev_b32_e32 v242, 16, v226
	v_and_b32_e32 v243, 0xffff0000, v226
	v_lshlrev_b32_e32 v244, 16, v227
	v_and_b32_e32 v245, 0xffff0000, v227
	v_pk_add_f32 v[30:31], v[30:31], v[242:243]
	v_pk_add_f32 v[32:33], v[32:33], v[244:245]
	v_lshlrev_b32_e32 v242, 16, v228
	v_and_b32_e32 v243, 0xffff0000, v228
	v_lshlrev_b32_e32 v244, 16, v229
	v_and_b32_e32 v245, 0xffff0000, v229
	v_pk_add_f32 v[26:27], v[26:27], v[242:243]
	v_pk_add_f32 v[28:29], v[28:29], v[244:245]
	v_mul_f32_e32 v130, v30, v30
	v_mul_f32_e32 v131, v31, v31
	v_fmac_f32_e32 v130, v32, v32
	v_fmac_f32_e32 v131, v33, v33
	v_fmac_f32_e32 v130, v26, v26
	v_fmac_f32_e32 v131, v27, v27
	v_fmac_f32_e32 v130, v28, v28
	v_fmac_f32_e32 v131, v29, v29
	v_cvt_pk_bf16_f32 v30, v30, v31
	v_cvt_pk_bf16_f32 v31, v32, v33
	v_cvt_pk_bf16_f32 v32, v26, v27
	v_cvt_pk_bf16_f32 v33, v28, v29
	ds_bpermute_b32 v30, v247, v30
	ds_bpermute_b32 v31, v247, v31
	ds_bpermute_b32 v32, v247, v32
	ds_bpermute_b32 v33, v247, v33
	s_waitcnt vmcnt(18)
	ds_bpermute_b32 v234, v246, v234
	ds_bpermute_b32 v235, v246, v235
	ds_bpermute_b32 v236, v246, v236
	ds_bpermute_b32 v237, v246, v237
	s_waitcnt lgkmcnt(12)
	global_store_dwordx4 v[132:133], v[38:41], off offset:256
	s_mov_b32 s56, 0x8000
	v_lshl_add_u64 v[132:133], v[132:133], 0, s[56:57]
	s_waitcnt lgkmcnt(8)
; DI unsigned pk2(float lo, float hi) { f32x2 v = {lo, hi}; bf2_t r = __builtin_convertvector(v, bf2_t); return __builtin_bit_cast(unsigned, r); }
; DI float bflo(unsigned u) { return __uint_as_float(u << 16); }
; DI float bfhi(unsigned u) { return __uint_as_float(u & 0xffff0000u); }
;   DI void operator()(const f32x4 (&acc)[2][2][4][2], const Unit& u, int wr, int wc, int fr, int fq, const PG8_LAS float* sR) const {
;     ...
; #pragma unroll
;       for (int m = 0; m < 4; ++m) {
;         const int row = row0 + ai * HALF + m * 16;
;         const size_t ro = (size_t)row * 1024 + col0;
;         float ss = 0.f;
; #pragma unroll
;         for (int bj = 0; bj < 2; ++bj)
; #pragma unroll
;           for (int n = 0; n < 2; ++n) {
;             f32x4 v;
;             if (X0 != nullptr) v = *(const f32x4*)(X0 + ro + bj * HALF + n * 16);
;             else { const u32x2 q = sv[m][bj][n]; v[0] = bflo(q[0]); v[1] = bfhi(q[0]); v[2] = bflo(q[1]); v[3] = bfhi(q[1]); }
;             v += acc[ai][bj][m][n];
;             ss += v[0] * v[0] + v[1] * v[1] + v[2] * v[2] + v[3] * v[3];
;             if (!dry) { u32x2 q; q[0] = pk2(v[0], v[1]); q[1] = pk2(v[2], v[3]); *(u32x2*)(S + ro + bj * HALF + n * 16) = q; }
;           }
;         ss += __shfl_xor(ss, 16); ss += __shfl_xor(ss, 32);
;         if (!dry && fq == 0) ssq[(size_t)row * 16 + u.pn * 4 + wc] = ss;
;       }
; template <class Epi>
; DI void gemm_phase(PG8_LAS unsigned char* lds, const Gemm g, const StaticOrder& S, const Epi& E) {
;     ...
;     if (!has_next) break;
; #pragma unroll
;     for (int a = 0; a < 2; ++a)
; #pragma unroll
;       for (int b = 0; b < 2; ++b)
; #pragma unroll
;         for (int m = 0; m < 4; ++m)
; #pragma unroll
;           for (int n = 0; n < 2; ++n) acc[a][b][m][n] = (f32x4){0.f, 0.f, 0.f, 0.f};
;     cur = nxt; cA = nA; cB = nB; ++ui;
	v_lshlrev_b32_e32 v242, 16, v230
	v_and_b32_e32 v243, 0xffff0000, v230
	v_lshlrev_b32_e32 v244, 16, v231
	v_and_b32_e32 v245, 0xffff0000, v231
	v_pk_add_f32 v[22:23], v[22:23], v[242:243]
	v_pk_add_f32 v[24:25], v[24:25], v[244:245]
	v_lshlrev_b32_e32 v242, 16, v232
	v_and_b32_e32 v243, 0xffff0000, v232
	v_lshlrev_b32_e32 v244, 16, v233
	v_and_b32_e32 v245, 0xffff0000, v233
	v_pk_add_f32 v[18:19], v[18:19], v[242:243]
	v_pk_add_f32 v[20:21], v[20:21], v[244:245]
	v_fmac_f32_e32 v130, v22, v22
	v_fmac_f32_e32 v131, v23, v23
	v_fmac_f32_e32 v130, v24, v24
	v_fmac_f32_e32 v131, v25, v25
	v_fmac_f32_e32 v130, v18, v18
	v_fmac_f32_e32 v131, v19, v19
	v_fmac_f32_e32 v130, v20, v20
	v_fmac_f32_e32 v131, v21, v21
	v_cvt_pk_bf16_f32 v22, v22, v23
	v_cvt_pk_bf16_f32 v23, v24, v25
	v_cvt_pk_bf16_f32 v24, v18, v19
	v_cvt_pk_bf16_f32 v25, v20, v21
	ds_bpermute_b32 v22, v247, v22
	ds_bpermute_b32 v23, v247, v23
	ds_bpermute_b32 v24, v247, v24
	ds_bpermute_b32 v25, v247, v25
	v_add_f32_e32 v130, v130, v131
	v_mov_b32_e32 v131, v130
	s_nop 1
	v_permlane16_swap_b32_e32 v130, v131
	s_nop 1
	v_add_f32_e32 v130, v130, v131
	v_mov_b32_e32 v131, v130
	s_nop 1
	v_permlane32_swap_b32_e32 v130, v131
	s_nop 1
	v_add_f32_e32 v130, v130, v131
	s_and_saveexec_b64 s[58:59], s[40:41]
	global_store_dword v[250:251], v130, off
	s_or_b64 exec, exec, s[58:59]
	s_mov_b32 s56, 0x400
	v_lshl_add_u64 v[250:251], v[250:251], 0, s[56:57]
	s_waitcnt vmcnt(19)
	ds_bpermute_b32 v238, v246, v238
	ds_bpermute_b32 v239, v246, v239
	ds_bpermute_b32 v240, v246, v240
	ds_bpermute_b32 v241, v246, v241
	s_waitcnt lgkmcnt(12)
	global_store_dwordx4 v[132:133], v[30:33], off
	s_waitcnt lgkmcnt(8)
	v_lshlrev_b32_e32 v242, 16, v234
	v_and_b32_e32 v243, 0xffff0000, v234
	v_lshlrev_b32_e32 v244, 16, v235
	v_and_b32_e32 v245, 0xffff0000, v235
	v_pk_add_f32 v[14:15], v[14:15], v[242:243]
	v_pk_add_f32 v[16:17], v[16:17], v[244:245]
	v_lshlrev_b32_e32 v242, 16, v236
	v_and_b32_e32 v243, 0xffff0000, v236
	v_lshlrev_b32_e32 v244, 16, v237
	v_and_b32_e32 v245, 0xffff0000, v237
	v_pk_add_f32 v[10:11], v[10:11], v[242:243]
	v_pk_add_f32 v[12:13], v[12:13], v[244:245]
	v_mul_f32_e32 v130, v14, v14
	v_mul_f32_e32 v131, v15, v15
	v_fmac_f32_e32 v130, v16, v16
	v_fmac_f32_e32 v131, v17, v17
	v_fmac_f32_e32 v130, v10, v10
	v_fmac_f32_e32 v131, v11, v11
	v_fmac_f32_e32 v130, v12, v12
	v_fmac_f32_e32 v131, v13, v13
	v_cvt_pk_bf16_f32 v14, v14, v15
	v_cvt_pk_bf16_f32 v15, v16, v17
	v_cvt_pk_bf16_f32 v16, v10, v11
	v_cvt_pk_bf16_f32 v17, v12, v13
	ds_bpermute_b32 v14, v247, v14
	ds_bpermute_b32 v15, v247, v15
	ds_bpermute_b32 v16, v247, v16
	ds_bpermute_b32 v17, v247, v17
	s_waitcnt lgkmcnt(8)
	global_store_dwordx4 v[132:133], v[22:25], off offset:256
	s_mov_b32 s56, 0x8000
	v_lshl_add_u64 v[132:133], v[132:133], 0, s[56:57]
	s_waitcnt lgkmcnt(4)
	v_lshlrev_b32_e32 v242, 16, v238
	v_and_b32_e32 v243, 0xffff0000, v238
	v_lshlrev_b32_e32 v244, 16, v239
	v_and_b32_e32 v245, 0xffff0000, v239
	v_pk_add_f32 v[6:7], v[6:7], v[242:243]
	v_pk_add_f32 v[8:9], v[8:9], v[244:245]
	v_lshlrev_b32_e32 v242, 16, v240
	v_and_b32_e32 v243, 0xffff0000, v240
	v_lshlrev_b32_e32 v244, 16, v241
	v_and_b32_e32 v245, 0xffff0000, v241
	v_pk_add_f32 v[2:3], v[2:3], v[242:243]
	v_pk_add_f32 v[4:5], v[4:5], v[244:245]
	v_fmac_f32_e32 v130, v6, v6
	v_fmac_f32_e32 v131, v7, v7
	v_fmac_f32_e32 v130, v8, v8
	v_fmac_f32_e32 v131, v9, v9
	v_fmac_f32_e32 v130, v2, v2
	v_fmac_f32_e32 v131, v3, v3
	v_fmac_f32_e32 v130, v4, v4
	v_fmac_f32_e32 v131, v5, v5
	v_cvt_pk_bf16_f32 v6, v6, v7
	v_cvt_pk_bf16_f32 v7, v8, v9
	v_cvt_pk_bf16_f32 v8, v2, v3
	v_cvt_pk_bf16_f32 v9, v4, v5
	ds_bpermute_b32 v6, v247, v6
	ds_bpermute_b32 v7, v247, v7
	ds_bpermute_b32 v8, v247, v8
	ds_bpermute_b32 v9, v247, v9
	v_add_f32_e32 v130, v130, v131
	v_mov_b32_e32 v131, v130
	s_nop 1
	v_permlane16_swap_b32_e32 v130, v131
	s_nop 1
	v_add_f32_e32 v130, v130, v131
	v_mov_b32_e32 v131, v130
	s_nop 1
	v_permlane32_swap_b32_e32 v130, v131
	s_nop 1
	v_add_f32_e32 v130, v130, v131
	s_and_saveexec_b64 s[58:59], s[40:41]
	global_store_dword v[250:251], v130, off
	s_or_b64 exec, exec, s[58:59]
	s_waitcnt lgkmcnt(4)
	global_store_dwordx4 v[132:133], v[14:17], off
	s_waitcnt lgkmcnt(0)
	global_store_dwordx4 v[132:133], v[6:9], off offset:256
	v_readlane_b32 s4, v253, 56
	v_readlane_b32 s5, v253, 57
	v_readlane_b32 s6, v253, 58
	v_readlane_b32 s7, v253, 59
	v_readlane_b32 s8, v253, 60
	v_readlane_b32 s9, v253, 61
	v_readlane_b32 s10, v253, 62
	v_readlane_b32 s11, v253, 63
	v_readlane_b32 s12, v254, 0
	v_readlane_b32 s13, v254, 1
	v_readlane_b32 s14, v254, 2
	v_readlane_b32 s15, v254, 3
	v_readlane_b32 s16, v254, 4
	v_readlane_b32 s17, v254, 5
	v_readlane_b32 s18, v254, 6
	v_readlane_b32 s19, v254, 7
	s_mov_b64 s[44:45], exec
	s_branch .LBB0_823

; DI int otid() { int t = threadIdx.x; asm volatile("" : "+v"(t)); return t; }
; #define PG8_STAGE(bufoff, gbase, voff) do { _Pragma("unroll") for (int _i = 0; _i < 2; ++_i) \
;     __builtin_amdgcn_global_load_lds((const unsigned*)((const char*)(gbase) + (voff)[_i]), (PG8_LAS unsigned*)(lds + (bufoff) + ldsw + _i * 8192), 16, 0, 0); } while (0)
; #define PG8_WAIT_V(n) asm volatile("s_waitcnt vmcnt(" #n ")" ::: "memory")
; #define PG8_BAR __builtin_amdgcn_s_barrier()
; template <class Epi>
; DI void gemm_phase(PG8_LAS unsigned char* lds, const Gemm g, const StaticOrder& S, const Epi& E) {
;   const int tid = otid(), wid = __builtin_amdgcn_readfirstlane(tid >> 6), lane = tid & 63, wr = wid >> 2, wc = wid & 3, fr = lane & 15, fq = lane >> 4;
;   const int K = g.K, nt = K / BK;
;   unsigned voffA[2], voffB[2];
; #pragma unroll
;   for (int i = 0; i < 2; ++i) { int R, C; stage_rc(tid * 16 + i * 8192, R, C); const int Rb = Epi::PERM ? ((R & ~31) + perm32(R & 31)) : R;
;     voffA[i] = (unsigned)(R * g.lda + C) * 2u; voffB[i] = (unsigned)(Rb * K + C) * 2u; }
;   const size_t kstep = (size_t)(BK * 2);
;   const size_t hstepA = (size_t)HALF * g.lda * 2, hstepB = (size_t)HALF * K * 2;
;   const size_t tstepA = 2 * hstepA, tstepB = 2 * hstepB;
;   const unsigned ldsw = (unsigned)wid * 1024u;
;   const int aoff = lds_byte(wr * 64 + fr, fq * 8), boff = lds_byte(wc * 32 + fr, fq * 8);
;     ...
;   Unit cur, nxt; int ui = 0;
;   if (!S.next(0, cur)) return;
;   f32x4 acc[2][2][4][2];
; #pragma unroll
;   for (int a = 0; a < 2; ++a)
; #pragma unroll
;     for (int b = 0; b < 2; ++b)
; #pragma unroll
;       for (int m = 0; m < 4; ++m)
; #pragma unroll
;         for (int n = 0; n < 2; ++n) acc[a][b][m][n] = (f32x4){0.f, 0.f, 0.f, 0.f};
;   bf16x8 At[4][2], B0[2][2], B1[2][2];
;   const char* cA = (const char*)g.A + (size_t)cur.pm * tstepA; const char* cB = (const char*)g.Bt + (size_t)cur.pn * tstepB;
;   PG8_STAGE(PG8_SB(0, 0), cB, voffB); PG8_STAGE(PG8_SA(0, 0), cA, voffA); PG8_STAGE(PG8_SB(0, 1), cB + hstepB, voffB); PG8_STAGE(PG8_SA(0, 1), cA + hstepA, voffA);
;   if (wr == 1) PG8_BAR;
;   PG8_WAIT_V(4); PG8_BAR;
;   PG8_STAGE(PG8_SB(1, 0), cB + kstep, voffB); PG8_STAGE(PG8_SA(1, 0), cA + kstep, voffA); PG8_STAGE(PG8_SB(1, 1), cB + hstepB + kstep, voffB);
;   PG8_WAIT_V(6); PG8_BAR;
.LBB0_1167:
	s_or_b64 exec, exec, s[30:31]
	v_readlane_b32 s4, v252, 48
	v_mov_b32_e32 v4, v200
	v_readlane_b32 s5, v252, 49
	s_waitcnt lgkmcnt(0)
	s_barrier
	s_andn2_b64 vcc, exec, s[4:5]
	v_readfirstlane_b32 s56, v4
	s_cbranch_vccnz .LBB0_1184
	v_lshlrev_b32_e32 v0, 4, v4
	v_add_u32_e32 v3, 0x2000, v0
	v_ashrrev_i32_e32 v2, 31, v3
	v_lshrrev_b32_e32 v2, 22, v2
	v_add_u32_e32 v2, v3, v2
	v_ashrrev_i32_e32 v2, 10, v2
	v_mul_i32_i24_e32 v5, 0x400, v2
	v_sub_u32_e32 v3, v3, v5
	v_lshrrev_b32_e32 v5, 4, v3
	v_bitop3_b32 v5, v5, v3, 32 bitop3:0x6c
	v_ashrrev_i32_e32 v3, 31, v5
	v_lshrrev_b32_e32 v3, 26, v3
	v_add_u32_e32 v6, v5, v3
	v_lshlrev_b32_e32 v7, 3, v2
	v_ashrrev_i32_e32 v3, 6, v6
	v_and_b32_e32 v7, -16, v7
	v_add_u32_e32 v7, v3, v7
	v_and_b32_e32 v8, 3, v3
	s_mov_b32 s4, 0x1fffe0
	v_lshrrev_b32_e32 v9, 2, v7
	v_lshlrev_b32_e32 v10, 1, v7
	v_and_b32_e32 v6, 0xc0, v6
	v_and_or_b32 v8, v7, s4, v8
	v_and_b32_e32 v9, 4, v9
	v_and_b32_e32 v10, 24, v10
	v_sub_u32_e32 v5, v5, v6
	v_or3_b32 v8, v8, v9, v10
	v_lshlrev_b32_e32 v9, 5, v2
	v_ashrrev_i16_sdwa v5, v202, sext(v5) dst_sel:DWORD dst_unused:UNUSED_PAD src0_sel:DWORD src1_sel:BYTE_0
	v_and_b32_e32 v9, 32, v9
	v_bfe_i32 v5, v5, 0, 16
	v_add_lshl_u32 v6, v9, v5, 1
	v_lshl_add_u32 v130, v8, 11, v6
	v_lshl_add_u32 v132, v7, 11, v6
	v_bfe_i32 v6, v4, 27, 1
	v_lshrrev_b32_e32 v6, 22, v6
	v_add_u32_e32 v6, v0, v6
	v_and_b32_e32 v6, 0xfffffc00, v6
	v_sub_u32_e32 v0, v0, v6
	v_lshrrev_b32_e32 v6, 4, v0
	v_bitop3_b32 v8, v6, v0, 32 bitop3:0x6c
	v_ashrrev_i32_e32 v0, 31, v0
	v_lshrrev_b32_e32 v0, 26, v0
	v_add_u32_e32 v0, v8, v0
	v_ashrrev_i32_e32 v6, 6, v0
	v_ashrrev_i32_e32 v0, 31, v4
	v_lshrrev_b32_e32 v0, 26, v0
	v_add_u32_e32 v0, v4, v0
	v_ashrrev_i32_e32 v7, 6, v0
	v_lshlrev_b32_e32 v0, 3, v7
	v_and_b32_e32 v0, -16, v0
	v_add_u32_e32 v9, v6, v0
	v_and_b32_e32 v0, 3, v6
	v_lshrrev_b32_e32 v10, 2, v9
	v_lshlrev_b32_e32 v11, 1, v9
	v_and_or_b32 v0, v9, s4, v0
	v_and_b32_e32 v10, 4, v10
	v_and_b32_e32 v11, 24, v11
	v_or3_b32 v0, v0, v10, v11
	v_mul_i32_i24_e32 v11, 64, v6
	v_sub_u32_e32 v8, v8, v11
	s_ashr_i32 s28, s56, 6
	v_lshlrev_b32_e32 v10, 5, v7
	v_ashrrev_i16_sdwa v8, v202, sext(v8) dst_sel:DWORD dst_unused:UNUSED_PAD src0_sel:DWORD src1_sel:BYTE_0
	s_lshl_b32 s57, s28, 10
	v_and_b32_e32 v10, 32, v10
	v_bfe_i32 v8, v8, 0, 16
	v_add_lshl_u32 v10, v10, v8, 1
	s_add_i32 s58, s57, 0
	v_readlane_b32 s4, v252, 59
	v_lshl_add_u32 v0, v0, 11, v10
	s_add_i32 m0, s58, 0x10000
	v_readlane_b32 s5, v252, 60
	v_lshl_add_u32 v142, v9, 11, v10
	s_add_i32 s59, s58, 0x2000
	s_add_i32 s60, s58, 0x4000
	s_add_i32 s61, s58, 0x6000
	s_ashr_i32 s30, s56, 8
	global_load_lds_dwordx4 v0, s[4:5]
	s_add_i32 m0, s58, 0x12000
	s_nop 0
	global_load_lds_dwordx4 v130, s[4:5]
	v_readlane_b32 s4, v252, 55
	s_mov_b32 m0, s58
	v_readlane_b32 s5, v252, 56
	s_nop 4
	global_load_lds_dwordx4 v142, s[4:5]
	s_mov_b32 m0, s59
	s_nop 0
	global_load_lds_dwordx4 v132, s[4:5]
	v_readlane_b32 s4, v252, 53
	s_add_i32 m0, s58, 0x14000
	v_readlane_b32 s5, v252, 54
	s_nop 4
	global_load_lds_dwordx4 v0, s[4:5]
	s_add_i32 m0, s58, 0x16000
	s_cmp_lg_u32 s30, 1
	global_load_lds_dwordx4 v130, s[4:5]
	v_readlane_b32 s4, v252, 57
	s_mov_b32 m0, s60
	v_readlane_b32 s5, v252, 58
	s_nop 4
	global_load_lds_dwordx4 v142, s[4:5]
	s_mov_b32 m0, s61
	s_nop 0
	global_load_lds_dwordx4 v132, s[4:5]
	s_cbranch_scc1 .LBB0_1170
	s_barrier
	s_setprio 1

; #define PG8_STAGE(bufoff, gbase, voff) do { _Pragma("unroll") for (int _i = 0; _i < 2; ++_i) \
;     __builtin_amdgcn_global_load_lds((const unsigned*)((const char*)(gbase) + (voff)[_i]), (PG8_LAS unsigned*)(lds + (bufoff) + ldsw + _i * 8192), 16, 0, 0); } while (0)
; #define PG8_LDA(dst, b, h) do { _Pragma("unroll") for (int m = 0; m < 4; ++m) _Pragma("unroll") for (int k = 0; k < 2; ++k) dst[m][k] = *(const PG8_LAS bf16x8*)(lds + PG8_SA(b, h) + aoff + m * 2048 + k * 1024); } while (0)
; #define PG8_LDB(dst, b, h) do { _Pragma("unroll") for (int n = 0; n < 2; ++n) _Pragma("unroll") for (int k = 0; k < 2; ++k) dst[n][k] = *(const PG8_LAS bf16x8*)(lds + PG8_SB(b, h) + boff + n * 2048 + k * 1024); } while (0)
; #define PG8_MMA(ai, bj, At, Bt) do { __builtin_amdgcn_s_setprio(1); _Pragma("unroll") for (int m = 0; m < 4; ++m) _Pragma("unroll") for (int n = 0; n < 2; ++n) _Pragma("unroll") for (int k = 0; k < 2; ++k) \
;     acc[ai][bj][m][n] = __builtin_amdgcn_mfma_f32_16x16x32_bf16(Bt[n][k], At[m][k], acc[ai][bj][m][n], 0, 0, 0); __builtin_amdgcn_s_setprio(0); } while (0)
; #define PG8_WAIT_L(n) asm volatile("s_waitcnt lgkmcnt(" #n ")" ::: "memory")
; #define PG8_BAR __builtin_amdgcn_s_barrier()
; #define PG8_SCHED __builtin_amdgcn_sched_barrier(0)
; template <class Epi>
; DI void gemm_phase(PG8_LAS unsigned char* lds, const Gemm g, const StaticOrder& S, const Epi& E) {
;     ...
;     for (int t = 0; t < nt; t += 2) {
;       const bool last = (t == nt - 2);
;       const char* a1 = cA + (size_t)(t + 1) * kstep;
;       const char* a2 = last ? nA : cA + (size_t)(t + 2) * kstep; const char* b2 = last ? nB : cB + (size_t)(t + 2) * kstep;
;       const char* a3 = a2 + kstep; const char* b3 = b2 + kstep;
;       PG8_LDB(B0, 0, 0); PG8_SCHED; PG8_LDA(At, 0, 0); PG8_STAGE(PG8_SA(1, 1), a1 + hstepA, voffA);
;       PG8_WAIT_L(8); PG8_BAR; PG8_WAIT_L(0); PG8_MMA(0, 0, At, B0); PG8_BAR; PG8_SCHED;
;       PG8_LDB(B1, 0, 1); PG8_STAGE(PG8_SB(0, 0), b2, voffB);
;       PG8_BAR; PG8_WAIT_L(0); PG8_MMA(0, 1, At, B1); PG8_BAR;
;       PG8_LDA(At, 0, 1); PG8_STAGE(PG8_SA(0, 0), a2, voffA);
;       PG8_BAR; PG8_WAIT_L(0); PG8_MMA(1, 0, At, B0); PG8_BAR; PG8_SCHED;
.LBB0_1175:
	s_add_u32 s52, s30, 0xfffc0080
	s_addc_u32 s53, s31, -1
	s_add_i32 s71, 0, 0x10000
	v_add_u32_e32 v156, s71, v160
	ds_read_b128 v[152:155], v156
	ds_read_b128 v[164:167], v156 offset:1024
	ds_read_b128 v[168:171], v156 offset:2048
	ds_read_b128 v[172:175], v156 offset:3072
	s_cmp_eq_u32 s70, 12
	s_cselect_b32 s55, s47, s53
	s_cselect_b32 s54, s66, s52
	s_cselect_b32 s53, s45, s69
	s_cselect_b32 s52, s67, s68
	v_lshl_add_u64 v[156:157], s[30:31], 0, v[148:149]
	s_add_i32 m0, s58, 0xc000
	ds_read_b128 v[176:179], v162
	ds_read_b128 v[180:183], v162 offset:1024
	ds_read_b128 v[184:187], v162 offset:2048
	ds_read_b128 v[188:191], v162 offset:3072
	ds_read_b128 v[192:195], v162 offset:4096
	ds_read_b128 v[196:199], v162 offset:5120
	ds_read_b128 v[222:225], v162 offset:6144
	ds_read_b128 v[226:229], v162 offset:7168
	global_load_lds_dwordx4 v[156:157], off
	v_lshl_add_u64 v[156:157], s[30:31], 0, v[150:151]
	s_add_i32 m0, s58, 0xe000
	s_nop 0
	global_load_lds_dwordx4 v[156:157], off
	s_waitcnt lgkmcnt(8)
	s_barrier
	s_waitcnt lgkmcnt(0)
	s_waitcnt lgkmcnt(0)
	v_mfma_f32_16x16x32_bf16 v[70:73], v[152:155], v[176:179], v[70:73]
	v_mfma_f32_16x16x32_bf16 v[66:69], v[168:171], v[176:179], v[66:69]
	v_mfma_f32_16x16x32_bf16 v[62:65], v[152:155], v[184:187], v[62:65]
	v_mfma_f32_16x16x32_bf16 v[58:61], v[168:171], v[184:187], v[58:61]
	v_mfma_f32_16x16x32_bf16 v[54:57], v[152:155], v[192:195], v[54:57]
	v_mfma_f32_16x16x32_bf16 v[50:53], v[168:171], v[192:195], v[50:53]
	v_mfma_f32_16x16x32_bf16 v[46:49], v[152:155], v[222:225], v[46:49]
	v_mfma_f32_16x16x32_bf16 v[42:45], v[168:171], v[222:225], v[42:45]
	v_mfma_f32_16x16x32_bf16 v[70:73], v[164:167], v[180:183], v[70:73]
	v_mfma_f32_16x16x32_bf16 v[66:69], v[172:175], v[180:183], v[66:69]
	v_mfma_f32_16x16x32_bf16 v[62:65], v[164:167], v[188:191], v[62:65]
	v_mfma_f32_16x16x32_bf16 v[58:61], v[172:175], v[188:191], v[58:61]
	v_mfma_f32_16x16x32_bf16 v[54:57], v[164:167], v[196:199], v[54:57]
	v_mfma_f32_16x16x32_bf16 v[50:53], v[172:175], v[196:199], v[50:53]
	v_mfma_f32_16x16x32_bf16 v[46:49], v[164:167], v[226:229], v[46:49]
	v_mfma_f32_16x16x32_bf16 v[42:45], v[172:175], v[226:229], v[42:45]
	s_barrier
	s_add_i32 s74, 0, 0x14000
	v_add_u32_e32 v156, s74, v160
	s_add_i32 s71, s71, s57
	ds_read_b128 v[230:233], v156
	ds_read_b128 v[234:237], v156 offset:1024
	ds_read_b128 v[238:241], v156 offset:2048
	ds_read_b128 v[242:245], v156 offset:3072
	v_lshl_add_u64 v[156:157], s[52:53], 0, v[0:1]
	s_mov_b32 m0, s71
	v_lshl_add_u64 v[246:247], s[52:53], 0, v[130:131]
	global_load_lds_dwordx4 v[156:157], off
	s_add_i32 m0, s71, 0x2000
	s_nop 0
	global_load_lds_dwordx4 v[246:247], off
	s_barrier
	s_waitcnt lgkmcnt(0)
	s_waitcnt lgkmcnt(0)
	v_mfma_f32_16x16x32_bf16 v[126:129], v[230:233], v[176:179], v[126:129]
	v_mfma_f32_16x16x32_bf16 v[122:125], v[238:241], v[176:179], v[122:125]
	v_mfma_f32_16x16x32_bf16 v[118:121], v[230:233], v[184:187], v[118:121]
	v_mfma_f32_16x16x32_bf16 v[114:117], v[238:241], v[184:187], v[114:117]
	v_mfma_f32_16x16x32_bf16 v[110:113], v[230:233], v[192:195], v[110:113]
	v_mfma_f32_16x16x32_bf16 v[106:109], v[238:241], v[192:195], v[106:109]
	v_mfma_f32_16x16x32_bf16 v[102:105], v[230:233], v[222:225], v[102:105]
	v_mfma_f32_16x16x32_bf16 v[98:101], v[238:241], v[222:225], v[98:101]
	v_mfma_f32_16x16x32_bf16 v[126:129], v[234:237], v[180:183], v[126:129]
	v_mfma_f32_16x16x32_bf16 v[122:125], v[242:245], v[180:183], v[122:125]
	v_mfma_f32_16x16x32_bf16 v[118:121], v[234:237], v[188:191], v[118:121]
	v_mfma_f32_16x16x32_bf16 v[114:117], v[242:245], v[188:191], v[114:117]
	v_mfma_f32_16x16x32_bf16 v[110:113], v[234:237], v[196:199], v[110:113]
	v_mfma_f32_16x16x32_bf16 v[106:109], v[242:245], v[196:199], v[106:109]
	v_mfma_f32_16x16x32_bf16 v[102:105], v[234:237], v[226:229], v[102:105]
	v_mfma_f32_16x16x32_bf16 v[98:101], v[242:245], v[226:229], v[98:101]
	s_mov_b32 m0, s58
	v_lshl_add_u64 v[248:249], s[54:55], 0, v[142:143]
	s_barrier
	ds_read_b128 v[176:179], v162 offset:16384
	ds_read_b128 v[180:183], v162 offset:17408
	ds_read_b128 v[184:187], v162 offset:18432
	ds_read_b128 v[188:191], v162 offset:19456
	ds_read_b128 v[192:195], v162 offset:20480
	ds_read_b128 v[196:199], v162 offset:21504
	ds_read_b128 v[222:225], v162 offset:22528
	ds_read_b128 v[226:229], v162 offset:23552
	global_load_lds_dwordx4 v[248:249], off
	v_lshl_add_u64 v[250:251], s[54:55], 0, v[132:133]
	s_mov_b32 m0, s59
	s_nop 0
	global_load_lds_dwordx4 v[250:251], off
	s_barrier
	s_waitcnt lgkmcnt(0)
	s_waitcnt lgkmcnt(0)
	v_mfma_f32_16x16x32_bf16 v[38:41], v[152:155], v[176:179], v[38:41]
	v_mfma_f32_16x16x32_bf16 v[34:37], v[168:171], v[176:179], v[34:37]
	v_mfma_f32_16x16x32_bf16 v[30:33], v[152:155], v[184:187], v[30:33]
	v_mfma_f32_16x16x32_bf16 v[26:29], v[168:171], v[184:187], v[26:29]
	v_mfma_f32_16x16x32_bf16 v[14:17], v[152:155], v[192:195], v[14:17]
	v_mfma_f32_16x16x32_bf16 v[10:13], v[168:171], v[192:195], v[10:13]
	v_mfma_f32_16x16x32_bf16 v[6:9], v[152:155], v[222:225], v[6:9]
	v_mfma_f32_16x16x32_bf16 v[2:5], v[168:171], v[222:225], v[2:5]
	v_mfma_f32_16x16x32_bf16 v[38:41], v[164:167], v[180:183], v[38:41]
	v_mfma_f32_16x16x32_bf16 v[34:37], v[172:175], v[180:183], v[34:37]
	v_mfma_f32_16x16x32_bf16 v[30:33], v[164:167], v[188:191], v[30:33]
	v_mfma_f32_16x16x32_bf16 v[26:29], v[172:175], v[188:191], v[26:29]
	v_mfma_f32_16x16x32_bf16 v[14:17], v[164:167], v[196:199], v[14:17]
	v_mfma_f32_16x16x32_bf16 v[10:13], v[172:175], v[196:199], v[10:13]
	v_mfma_f32_16x16x32_bf16 v[6:9], v[164:167], v[226:229], v[6:9]
	v_mfma_f32_16x16x32_bf16 v[2:5], v[172:175], v[226:229], v[2:5]
	s_barrier
; #define PG8_STAGE(bufoff, gbase, voff) do { _Pragma("unroll") for (int _i = 0; _i < 2; ++_i) \
;     __builtin_amdgcn_global_load_lds((const unsigned*)((const char*)(gbase) + (voff)[_i]), (PG8_LAS unsigned*)(lds + (bufoff) + ldsw + _i * 8192), 16, 0, 0); } while (0)
; #define PG8_LDA(dst, b, h) do { _Pragma("unroll") for (int m = 0; m < 4; ++m) _Pragma("unroll") for (int k = 0; k < 2; ++k) dst[m][k] = *(const PG8_LAS bf16x8*)(lds + PG8_SA(b, h) + aoff + m * 2048 + k * 1024); } while (0)
; #define PG8_LDB(dst, b, h) do { _Pragma("unroll") for (int n = 0; n < 2; ++n) _Pragma("unroll") for (int k = 0; k < 2; ++k) dst[n][k] = *(const PG8_LAS bf16x8*)(lds + PG8_SB(b, h) + boff + n * 2048 + k * 1024); } while (0)
; #define PG8_MMA(ai, bj, At, Bt) do { __builtin_amdgcn_s_setprio(1); _Pragma("unroll") for (int m = 0; m < 4; ++m) _Pragma("unroll") for (int n = 0; n < 2; ++n) _Pragma("unroll") for (int k = 0; k < 2; ++k) \
;     acc[ai][bj][m][n] = __builtin_amdgcn_mfma_f32_16x16x32_bf16(Bt[n][k], At[m][k], acc[ai][bj][m][n], 0, 0, 0); __builtin_amdgcn_s_setprio(0); } while (0)
; #define PG8_WAIT_V(n) asm volatile("s_waitcnt vmcnt(" #n ")" ::: "memory")
; #define PG8_WAIT_L(n) asm volatile("s_waitcnt lgkmcnt(" #n ")" ::: "memory")
; #define PG8_BAR __builtin_amdgcn_s_barrier()
; #define PG8_SCHED __builtin_amdgcn_sched_barrier(0)
; template <class Epi>
; DI void gemm_phase(PG8_LAS unsigned char* lds, const Gemm g, const StaticOrder& S, const Epi& E) {
;     ...
;       PG8_STAGE(PG8_SB(0, 1), b2 + hstepB, voffB);
;       PG8_WAIT_V(6); PG8_BAR; PG8_MMA(1, 1, At, B1); PG8_BAR;
;       PG8_LDB(B0, 1, 0); PG8_SCHED; PG8_LDA(At, 1, 0); PG8_STAGE(PG8_SA(0, 1), a2 + hstepA, voffA);
;       PG8_WAIT_L(8); PG8_BAR; PG8_WAIT_L(0); PG8_MMA(0, 0, At, B0); PG8_BAR; PG8_SCHED;
;       PG8_LDB(B1, 1, 1); PG8_STAGE(PG8_SB(1, 0), b3, voffB);
;       PG8_BAR; PG8_WAIT_L(0); PG8_MMA(0, 1, At, B1); PG8_BAR;
;       PG8_LDA(At, 1, 1); PG8_STAGE(PG8_SA(1, 0), a3, voffA);
	s_add_u32 s72, s52, 0x40000
	s_addc_u32 s73, s53, 0
	s_add_i32 s71, s74, s57
	v_lshl_add_u64 v[152:153], s[72:73], 0, v[0:1]
	s_mov_b32 m0, s71
	s_nop 0
	global_load_lds_dwordx4 v[152:153], off
	v_lshl_add_u64 v[152:153], s[72:73], 0, v[130:131]
	s_add_i32 m0, s71, 0x2000
	s_nop 0
	global_load_lds_dwordx4 v[152:153], off
	s_waitcnt vmcnt(6)
	s_barrier
	v_mfma_f32_16x16x32_bf16 v[94:97], v[230:233], v[176:179], v[94:97]
	v_mfma_f32_16x16x32_bf16 v[90:93], v[238:241], v[176:179], v[90:93]
	v_mfma_f32_16x16x32_bf16 v[86:89], v[230:233], v[184:187], v[86:89]
	v_mfma_f32_16x16x32_bf16 v[82:85], v[238:241], v[184:187], v[82:85]
	v_mfma_f32_16x16x32_bf16 v[78:81], v[230:233], v[192:195], v[78:81]
	v_mfma_f32_16x16x32_bf16 v[74:77], v[238:241], v[192:195], v[74:77]
	v_mfma_f32_16x16x32_bf16 v[22:25], v[230:233], v[222:225], v[22:25]
	v_mfma_f32_16x16x32_bf16 v[18:21], v[238:241], v[222:225], v[18:21]
	v_mfma_f32_16x16x32_bf16 v[94:97], v[234:237], v[180:183], v[94:97]
	v_mfma_f32_16x16x32_bf16 v[90:93], v[242:245], v[180:183], v[90:93]
	v_mfma_f32_16x16x32_bf16 v[86:89], v[234:237], v[188:191], v[86:89]
	v_mfma_f32_16x16x32_bf16 v[82:85], v[242:245], v[188:191], v[82:85]
	v_mfma_f32_16x16x32_bf16 v[78:81], v[234:237], v[196:199], v[78:81]
	v_mfma_f32_16x16x32_bf16 v[74:77], v[242:245], v[196:199], v[74:77]
	v_mfma_f32_16x16x32_bf16 v[22:25], v[234:237], v[226:229], v[22:25]
	v_mfma_f32_16x16x32_bf16 v[18:21], v[242:245], v[226:229], v[18:21]
	s_add_i32 s71, 0, 0x18000
	v_add_u32_e32 v163, s71, v160
	s_barrier
	ds_read_b128 v[152:155], v163
	ds_read_b128 v[164:167], v163 offset:1024
	ds_read_b128 v[168:171], v163 offset:2048
	ds_read_b128 v[172:175], v163 offset:3072
	s_add_u32 s54, s54, 0x40000
	s_addc_u32 s55, s55, 0
	s_mov_b32 m0, s60
	v_lshl_add_u64 v[230:231], s[54:55], 0, v[142:143]
	ds_read_b128 v[176:179], v162 offset:32768
	ds_read_b128 v[180:183], v162 offset:33792
	ds_read_b128 v[184:187], v162 offset:34816
	ds_read_b128 v[188:191], v162 offset:35840
	ds_read_b128 v[192:195], v162 offset:36864
	ds_read_b128 v[196:199], v162 offset:37888
	ds_read_b128 v[222:225], v162 offset:38912
	ds_read_b128 v[226:229], v162 offset:39936
	global_load_lds_dwordx4 v[230:231], off
	v_lshl_add_u64 v[230:231], s[54:55], 0, v[132:133]
	s_mov_b32 m0, s61
	s_nop 0
	global_load_lds_dwordx4 v[230:231], off
	s_waitcnt lgkmcnt(8)
	s_barrier
	s_waitcnt lgkmcnt(0)
	s_waitcnt lgkmcnt(0)
	v_mfma_f32_16x16x32_bf16 v[70:73], v[152:155], v[176:179], v[70:73]
	v_mfma_f32_16x16x32_bf16 v[66:69], v[168:171], v[176:179], v[66:69]
	v_mfma_f32_16x16x32_bf16 v[62:65], v[152:155], v[184:187], v[62:65]
	v_mfma_f32_16x16x32_bf16 v[58:61], v[168:171], v[184:187], v[58:61]
	v_mfma_f32_16x16x32_bf16 v[54:57], v[152:155], v[192:195], v[54:57]
	v_mfma_f32_16x16x32_bf16 v[50:53], v[168:171], v[192:195], v[50:53]
	v_mfma_f32_16x16x32_bf16 v[46:49], v[152:155], v[222:225], v[46:49]
	v_mfma_f32_16x16x32_bf16 v[42:45], v[168:171], v[222:225], v[42:45]
	v_mfma_f32_16x16x32_bf16 v[70:73], v[164:167], v[180:183], v[70:73]
	v_mfma_f32_16x16x32_bf16 v[66:69], v[172:175], v[180:183], v[66:69]
	v_mfma_f32_16x16x32_bf16 v[62:65], v[164:167], v[188:191], v[62:65]
	v_mfma_f32_16x16x32_bf16 v[58:61], v[172:175], v[188:191], v[58:61]
	v_mfma_f32_16x16x32_bf16 v[54:57], v[164:167], v[196:199], v[54:57]
	v_mfma_f32_16x16x32_bf16 v[50:53], v[172:175], v[196:199], v[50:53]
	v_mfma_f32_16x16x32_bf16 v[46:49], v[164:167], v[226:229], v[46:49]
	v_mfma_f32_16x16x32_bf16 v[42:45], v[172:175], v[226:229], v[42:45]
	s_barrier
	s_add_i32 s54, 0, 0x1c000
	s_add_i32 s55, s71, s57
	v_add_u32_e32 v163, s54, v160
	v_lshl_add_u64 v[156:157], v[156:157], 0, s[86:87]
	s_mov_b32 m0, s55
	ds_read_b128 v[230:233], v163
	ds_read_b128 v[234:237], v163 offset:1024
	ds_read_b128 v[238:241], v163 offset:2048
	ds_read_b128 v[242:245], v163 offset:3072
	global_load_lds_dwordx4 v[156:157], off
	v_lshl_add_u64 v[156:157], v[246:247], 0, s[86:87]
	s_add_i32 m0, s55, 0x2000
	s_nop 0
	global_load_lds_dwordx4 v[156:157], off
	s_barrier
	s_waitcnt lgkmcnt(0)
	s_waitcnt lgkmcnt(0)
	v_mfma_f32_16x16x32_bf16 v[126:129], v[230:233], v[176:179], v[126:129]
	v_mfma_f32_16x16x32_bf16 v[122:125], v[238:241], v[176:179], v[122:125]
	v_mfma_f32_16x16x32_bf16 v[118:121], v[230:233], v[184:187], v[118:121]
	v_mfma_f32_16x16x32_bf16 v[114:117], v[238:241], v[184:187], v[114:117]
	v_mfma_f32_16x16x32_bf16 v[110:113], v[230:233], v[192:195], v[110:113]
	v_mfma_f32_16x16x32_bf16 v[106:109], v[238:241], v[192:195], v[106:109]
	v_mfma_f32_16x16x32_bf16 v[102:105], v[230:233], v[222:225], v[102:105]
	v_mfma_f32_16x16x32_bf16 v[98:101], v[238:241], v[222:225], v[98:101]
	v_mfma_f32_16x16x32_bf16 v[126:129], v[234:237], v[180:183], v[126:129]
	v_mfma_f32_16x16x32_bf16 v[122:125], v[242:245], v[180:183], v[122:125]
	v_mfma_f32_16x16x32_bf16 v[118:121], v[234:237], v[188:191], v[118:121]
	v_mfma_f32_16x16x32_bf16 v[114:117], v[242:245], v[188:191], v[114:117]
	v_mfma_f32_16x16x32_bf16 v[110:113], v[234:237], v[196:199], v[110:113]
	v_mfma_f32_16x16x32_bf16 v[106:109], v[242:245], v[196:199], v[106:109]
	v_mfma_f32_16x16x32_bf16 v[102:105], v[234:237], v[226:229], v[102:105]
	v_mfma_f32_16x16x32_bf16 v[98:101], v[242:245], v[226:229], v[98:101]
	s_mov_b32 m0, s34
	v_lshl_add_u64 v[156:157], v[248:249], 0, s[86:87]
	s_barrier
	ds_read_b128 v[176:179], v162 offset:49152
	ds_read_b128 v[180:183], v162 offset:50176
	ds_read_b128 v[184:187], v162 offset:51200
	ds_read_b128 v[188:191], v162 offset:52224
	ds_read_b128 v[192:195], v162 offset:53248
	ds_read_b128 v[196:199], v162 offset:54272
	ds_read_b128 v[222:225], v162 offset:55296
	ds_read_b128 v[226:229], v162 offset:56320
	global_load_lds_dwordx4 v[156:157], off
	v_lshl_add_u64 v[156:157], v[250:251], 0, s[86:87]
	s_mov_b32 m0, s62
	s_nop 0
	global_load_lds_dwordx4 v[156:157], off
	s_barrier
; DI unsigned pk2(float lo, float hi) { f32x2 v = {lo, hi}; bf2_t r = __builtin_convertvector(v, bf2_t); return __builtin_bit_cast(unsigned, r); }
; #define PG8_STAGE(bufoff, gbase, voff) do { _Pragma("unroll") for (int _i = 0; _i < 2; ++_i) \
;     __builtin_amdgcn_global_load_lds((const unsigned*)((const char*)(gbase) + (voff)[_i]), (PG8_LAS unsigned*)(lds + (bufoff) + ldsw + _i * 8192), 16, 0, 0); } while (0)
; #define PG8_MMA(ai, bj, At, Bt) do { __builtin_amdgcn_s_setprio(1); _Pragma("unroll") for (int m = 0; m < 4; ++m) _Pragma("unroll") for (int n = 0; n < 2; ++n) _Pragma("unroll") for (int k = 0; k < 2; ++k) \
;     acc[ai][bj][m][n] = __builtin_amdgcn_mfma_f32_16x16x32_bf16(Bt[n][k], At[m][k], acc[ai][bj][m][n], 0, 0, 0); __builtin_amdgcn_s_setprio(0); } while (0)
; #define PG8_WAIT_V(n) asm volatile("s_waitcnt vmcnt(" #n ")" ::: "memory")
; #define PG8_WAIT_L(n) asm volatile("s_waitcnt lgkmcnt(" #n ")" ::: "memory")
; #define PG8_BAR __builtin_amdgcn_s_barrier()
; #define PG8_SCHED __builtin_amdgcn_sched_barrier(0)
;   DI void operator()(const f32x4 (&acc)[2][2][4][2], const Unit& u, int wr, int wc, int fr, int fq, const PG8_LAS float* sR) const {
;     ...
;     const int col0 = u.pn * BM + wc * 32 + 8 * fq;
; #pragma unroll
;     for (int ai = 0; ai < 2; ++ai)
; #pragma unroll
;       for (int m = 0; m < 4; ++m) {
;         bf16_t* rowp = C + (size_t)(row0 + ai * HALF + m * 16) * ldc + col0;
;         const float rs = sR[ai * 128 + m * 16 + fr];
; #pragma unroll
;         for (int bj = 0; bj < 2; ++bj) {
;           const f32x4 v0 = acc[ai][bj][m][0] * rs, v1 = acc[ai][bj][m][1] * rs;
;           u32x4 w; w[0] = pk2(v0[0], v0[1]); w[1] = pk2(v0[2], v0[3]); w[2] = pk2(v1[0], v1[1]); w[3] = pk2(v1[2], v1[3]);
;           *(u32x4*)(rowp + bj * HALF) = w;
; template <class Epi>
; DI void gemm_phase(PG8_LAS unsigned char* lds, const Gemm g, const StaticOrder& S, const Epi& E) {
;     ...
;       PG8_BAR; PG8_WAIT_L(0); PG8_MMA(1, 0, At, B0); PG8_BAR; PG8_SCHED;
;       PG8_STAGE(PG8_SB(1, 1), b3 + hstepB, voffB);
;       PG8_WAIT_V(6); PG8_BAR; PG8_MMA(1, 1, At, B1); PG8_BAR;
	s_waitcnt lgkmcnt(0)
	s_waitcnt lgkmcnt(0)
	v_mfma_f32_16x16x32_bf16 v[38:41], v[152:155], v[176:179], v[38:41]
	v_mfma_f32_16x16x32_bf16 v[34:37], v[168:171], v[176:179], v[34:37]
	v_mfma_f32_16x16x32_bf16 v[30:33], v[152:155], v[184:187], v[30:33]
	v_mfma_f32_16x16x32_bf16 v[26:29], v[168:171], v[184:187], v[26:29]
	v_mfma_f32_16x16x32_bf16 v[14:17], v[152:155], v[192:195], v[14:17]
	v_mfma_f32_16x16x32_bf16 v[10:13], v[168:171], v[192:195], v[10:13]
	v_mfma_f32_16x16x32_bf16 v[6:9], v[152:155], v[222:225], v[6:9]
	v_mfma_f32_16x16x32_bf16 v[2:5], v[168:171], v[222:225], v[2:5]
	v_mfma_f32_16x16x32_bf16 v[38:41], v[164:167], v[180:183], v[38:41]
	v_mfma_f32_16x16x32_bf16 v[34:37], v[172:175], v[180:183], v[34:37]
	v_mfma_f32_16x16x32_bf16 v[30:33], v[164:167], v[188:191], v[30:33]
	v_mfma_f32_16x16x32_bf16 v[26:29], v[172:175], v[188:191], v[26:29]
	v_mfma_f32_16x16x32_bf16 v[14:17], v[164:167], v[196:199], v[14:17]
	v_mfma_f32_16x16x32_bf16 v[10:13], v[172:175], v[196:199], v[10:13]
	v_mfma_f32_16x16x32_bf16 v[6:9], v[164:167], v[226:229], v[6:9]
	v_mfma_f32_16x16x32_bf16 v[2:5], v[172:175], v[226:229], v[2:5]
	s_barrier
	s_add_u32 s52, s52, 0x40080
	s_addc_u32 s53, s53, 0
	s_add_i32 s54, s54, s57
	v_lshl_add_u64 v[152:153], s[52:53], 0, v[0:1]
	s_mov_b32 m0, s54
	s_nop 0
	global_load_lds_dwordx4 v[152:153], off
	v_lshl_add_u64 v[152:153], s[52:53], 0, v[130:131]
	s_add_i32 m0, s54, 0x2000
	s_nop 0
	global_load_lds_dwordx4 v[152:153], off
	s_waitcnt vmcnt(6)
	s_barrier
	v_mfma_f32_16x16x32_bf16 v[94:97], v[230:233], v[176:179], v[94:97]
	v_mfma_f32_16x16x32_bf16 v[90:93], v[238:241], v[176:179], v[90:93]
	v_mfma_f32_16x16x32_bf16 v[86:89], v[230:233], v[184:187], v[86:89]
	v_mfma_f32_16x16x32_bf16 v[82:85], v[238:241], v[184:187], v[82:85]
	v_mfma_f32_16x16x32_bf16 v[78:81], v[230:233], v[192:195], v[78:81]
	v_mfma_f32_16x16x32_bf16 v[74:77], v[238:241], v[192:195], v[74:77]
	v_mfma_f32_16x16x32_bf16 v[22:25], v[230:233], v[222:225], v[22:25]
	v_mfma_f32_16x16x32_bf16 v[18:21], v[238:241], v[222:225], v[18:21]
	v_mfma_f32_16x16x32_bf16 v[94:97], v[234:237], v[180:183], v[94:97]
	v_mfma_f32_16x16x32_bf16 v[90:93], v[242:245], v[180:183], v[90:93]
	v_mfma_f32_16x16x32_bf16 v[86:89], v[234:237], v[188:191], v[86:89]
	v_mfma_f32_16x16x32_bf16 v[82:85], v[242:245], v[188:191], v[82:85]
	v_mfma_f32_16x16x32_bf16 v[78:81], v[234:237], v[196:199], v[78:81]
	v_mfma_f32_16x16x32_bf16 v[74:77], v[242:245], v[196:199], v[74:77]
	v_mfma_f32_16x16x32_bf16 v[22:25], v[234:237], v[226:229], v[22:25]
	v_mfma_f32_16x16x32_bf16 v[18:21], v[242:245], v[226:229], v[18:21]
	s_add_i32 s70, s70, 2
	s_add_u32 s30, s30, 0x100
	s_addc_u32 s31, s31, 0
	s_add_u32 s68, s68, 0x100
	s_addc_u32 s69, s69, 0
	s_cmp_gt_u32 s70, 13
	s_barrier
	s_cbranch_scc0 .LBB0_1175
	s_lshl_b32 s28, s28, 10
	s_add_i32 s28, s63, s28
	s_cmp_eq_u32 s37, 20
	v_readlane_b32 s4, v252, 63
	s_cselect_b64 s[30:31], -1, 0
	v_readlane_b32 s5, v253, 0
	s_and_b64 s[30:31], s[4:5], s[30:31]
	v_lshl_add_u32 v152, s65, 8, v159
	s_andn2_b64 vcc, exec, s[30:31]
	s_mov_b64 s[30:31], -1
	s_cbranch_vccz .LBB0_1178
	v_lshl_add_u32 v153, v158, 2, s28
	ds_read2_b32 v[168:169], v153 offset1:16
	v_readlane_b32 s4, v253, 16
	v_lshl_or_b32 v156, s37, 8, v161
	v_readlane_b32 s18, v253, 30
	v_readlane_b32 s19, v253, 31
	v_ashrrev_i32_e32 v157, 31, v156
	v_lshlrev_b64 v[156:157], 1, v[156:157]
	v_mov_b64_e32 v[154:155], s[18:19]
	v_mad_i64_i32 v[164:165], s[30:31], v152, s96, v[154:155]
	v_lshl_add_u64 v[170:171], v[164:165], 0, v[156:157]
	s_waitcnt lgkmcnt(0)
	v_pk_mul_f32 v[166:167], v[72:73], v[168:169] op_sel_hi:[1,0]
	v_pk_mul_f32 v[164:165], v[70:71], v[168:169] op_sel_hi:[1,0]
	v_pk_mul_f32 v[172:173], v[68:69], v[168:169] op_sel_hi:[1,0]
	v_pk_mul_f32 v[174:175], v[66:67], v[168:169] op_sel_hi:[1,0]
	v_cvt_pk_bf16_f32 v164, v164, v165
	v_cvt_pk_bf16_f32 v165, v166, v167
	v_cvt_pk_bf16_f32 v166, v174, v175
	v_cvt_pk_bf16_f32 v167, v172, v173
	global_store_dwordx4 v[170:171], v[164:167], off
	v_pk_mul_f32 v[128:129], v[128:129], v[168:169] op_sel_hi:[1,0]
	v_pk_mul_f32 v[126:127], v[126:127], v[168:169] op_sel_hi:[1,0]
	v_pk_mul_f32 v[164:165], v[124:125], v[168:169] op_sel_hi:[1,0]
	v_pk_mul_f32 v[124:125], v[122:123], v[168:169] op_sel_hi:[1,0]
	v_cvt_pk_bf16_f32 v122, v126, v127
	v_cvt_pk_bf16_f32 v123, v128, v129
	v_cvt_pk_bf16_f32 v124, v124, v125
	v_cvt_pk_bf16_f32 v125, v164, v165
	global_store_dwordx4 v[170:171], v[122:125], off offset:256
	v_mov_b32_e32 v128, v169
	v_pk_mul_f32 v[164:165], v[60:61], v[128:129] op_sel_hi:[1,0]
	v_or_b32_e32 v122, 16, v152
	v_mad_i64_i32 v[122:123], s[30:31], v122, s96, v[154:155]
	v_lshl_add_u64 v[126:127], v[122:123], 0, v[156:157]
	v_pk_mul_f32 v[124:125], v[64:65], v[128:129] op_sel_hi:[1,0]
	v_pk_mul_f32 v[122:123], v[62:63], v[128:129] op_sel_hi:[1,0]
	v_pk_mul_f32 v[166:167], v[58:59], v[128:129] op_sel_hi:[1,0]
	v_cvt_pk_bf16_f32 v122, v122, v123
	v_cvt_pk_bf16_f32 v123, v124, v125
	v_cvt_pk_bf16_f32 v124, v166, v167
	v_cvt_pk_bf16_f32 v125, v164, v165
	v_pk_mul_f32 v[118:119], v[118:119], v[128:129] op_sel_hi:[1,0]
	global_store_dwordx4 v[126:127], v[122:125], off
	v_pk_mul_f32 v[120:121], v[120:121], v[128:129] op_sel_hi:[1,0]
	v_readlane_b32 s5, v253, 17
	v_pk_mul_f32 v[122:123], v[116:117], v[128:129] op_sel_hi:[1,0]
	v_pk_mul_f32 v[116:117], v[114:115], v[128:129] op_sel_hi:[1,0]
	v_cvt_pk_bf16_f32 v114, v118, v119
	ds_read2_b32 v[118:119], v153 offset0:32 offset1:48
	v_cvt_pk_bf16_f32 v115, v120, v121
	v_cvt_pk_bf16_f32 v116, v116, v117
	v_cvt_pk_bf16_f32 v117, v122, v123
	global_store_dwordx4 v[126:127], v[114:117], off offset:256
	s_waitcnt lgkmcnt(0)
; DI unsigned pk2(float lo, float hi) { f32x2 v = {lo, hi}; bf2_t r = __builtin_convertvector(v, bf2_t); return __builtin_bit_cast(unsigned, r); }
;   DI void operator()(const f32x4 (&acc)[2][2][4][2], const Unit& u, int wr, int wc, int fr, int fq, const PG8_LAS float* sR) const {
;     ...
;     const int col0 = u.pn * BM + wc * 32 + 8 * fq;
; #pragma unroll
;     for (int ai = 0; ai < 2; ++ai)
; #pragma unroll
;       for (int m = 0; m < 4; ++m) {
;         bf16_t* rowp = C + (size_t)(row0 + ai * HALF + m * 16) * ldc + col0;
;         const float rs = sR[ai * 128 + m * 16 + fr];
; #pragma unroll
;         for (int bj = 0; bj < 2; ++bj) {
;           const f32x4 v0 = acc[ai][bj][m][0] * rs, v1 = acc[ai][bj][m][1] * rs;
;           u32x4 w; w[0] = pk2(v0[0], v0[1]); w[1] = pk2(v0[2], v0[3]); w[2] = pk2(v1[0], v1[1]); w[3] = pk2(v1[2], v1[3]);
;           *(u32x4*)(rowp + bj * HALF) = w;
;         }
;       }
	v_pk_mul_f32 v[122:123], v[52:53], v[118:119] op_sel_hi:[1,0]
	v_pk_mul_f32 v[124:125], v[50:51], v[118:119] op_sel_hi:[1,0]
	v_or_b32_e32 v114, 32, v152
	v_mad_i64_i32 v[114:115], s[30:31], v114, s96, v[154:155]
	v_lshl_add_u64 v[120:121], v[114:115], 0, v[156:157]
	v_pk_mul_f32 v[116:117], v[56:57], v[118:119] op_sel_hi:[1,0]
	v_pk_mul_f32 v[114:115], v[54:55], v[118:119] op_sel_hi:[1,0]
	v_pk_mul_f32 v[112:113], v[112:113], v[118:119] op_sel_hi:[1,0]
	v_cvt_pk_bf16_f32 v114, v114, v115
	v_cvt_pk_bf16_f32 v115, v116, v117
	v_cvt_pk_bf16_f32 v116, v124, v125
	v_cvt_pk_bf16_f32 v117, v122, v123
	global_store_dwordx4 v[120:121], v[114:117], off
	v_pk_mul_f32 v[110:111], v[110:111], v[118:119] op_sel_hi:[1,0]
	v_readlane_b32 s6, v253, 18
	v_pk_mul_f32 v[114:115], v[108:109], v[118:119] op_sel_hi:[1,0]
	v_pk_mul_f32 v[108:109], v[106:107], v[118:119] op_sel_hi:[1,0]
	v_cvt_pk_bf16_f32 v106, v110, v111
	v_cvt_pk_bf16_f32 v107, v112, v113
	v_cvt_pk_bf16_f32 v108, v108, v109
	v_cvt_pk_bf16_f32 v109, v114, v115
	global_store_dwordx4 v[120:121], v[106:109], off offset:256
	v_mov_b32_e32 v112, v119
	v_pk_mul_f32 v[114:115], v[44:45], v[112:113] op_sel_hi:[1,0]
	v_or_b32_e32 v106, 48, v152
	v_mad_i64_i32 v[106:107], s[30:31], v106, s96, v[154:155]
	v_lshl_add_u64 v[110:111], v[106:107], 0, v[156:157]
	v_pk_mul_f32 v[108:109], v[48:49], v[112:113] op_sel_hi:[1,0]
	v_pk_mul_f32 v[106:107], v[46:47], v[112:113] op_sel_hi:[1,0]
	v_pk_mul_f32 v[116:117], v[42:43], v[112:113] op_sel_hi:[1,0]
	v_cvt_pk_bf16_f32 v106, v106, v107
	v_cvt_pk_bf16_f32 v107, v108, v109
	v_cvt_pk_bf16_f32 v108, v116, v117
	v_cvt_pk_bf16_f32 v109, v114, v115
	v_pk_mul_f32 v[102:103], v[102:103], v[112:113] op_sel_hi:[1,0]
	global_store_dwordx4 v[110:111], v[106:109], off
	v_pk_mul_f32 v[104:105], v[104:105], v[112:113] op_sel_hi:[1,0]
	v_readlane_b32 s7, v253, 19
	v_pk_mul_f32 v[106:107], v[100:101], v[112:113] op_sel_hi:[1,0]
	v_pk_mul_f32 v[100:101], v[98:99], v[112:113] op_sel_hi:[1,0]
	v_cvt_pk_bf16_f32 v98, v102, v103
	ds_read2_b32 v[102:103], v153 offset0:128 offset1:144
	v_cvt_pk_bf16_f32 v99, v104, v105
	v_cvt_pk_bf16_f32 v100, v100, v101
	v_cvt_pk_bf16_f32 v101, v106, v107
	global_store_dwordx4 v[110:111], v[98:101], off offset:256
	s_waitcnt lgkmcnt(0)
	v_pk_mul_f32 v[106:107], v[36:37], v[102:103] op_sel_hi:[1,0]
	v_pk_mul_f32 v[108:109], v[34:35], v[102:103] op_sel_hi:[1,0]
	v_add_u32_e32 v98, 0x80, v152
	v_mad_i64_i32 v[98:99], s[30:31], v98, s96, v[154:155]
	v_lshl_add_u64 v[104:105], v[98:99], 0, v[156:157]
	v_pk_mul_f32 v[100:101], v[40:41], v[102:103] op_sel_hi:[1,0]
	v_pk_mul_f32 v[98:99], v[38:39], v[102:103] op_sel_hi:[1,0]
	v_pk_mul_f32 v[96:97], v[96:97], v[102:103] op_sel_hi:[1,0]
	v_cvt_pk_bf16_f32 v98, v98, v99
	v_cvt_pk_bf16_f32 v99, v100, v101
	v_cvt_pk_bf16_f32 v100, v108, v109
	v_cvt_pk_bf16_f32 v101, v106, v107
	global_store_dwordx4 v[104:105], v[98:101], off
	v_pk_mul_f32 v[94:95], v[94:95], v[102:103] op_sel_hi:[1,0]
	v_readlane_b32 s8, v253, 20
	v_pk_mul_f32 v[98:99], v[92:93], v[102:103] op_sel_hi:[1,0]
	v_pk_mul_f32 v[92:93], v[90:91], v[102:103] op_sel_hi:[1,0]
	v_cvt_pk_bf16_f32 v90, v94, v95
	v_cvt_pk_bf16_f32 v91, v96, v97
	v_cvt_pk_bf16_f32 v92, v92, v93
	v_cvt_pk_bf16_f32 v93, v98, v99
	global_store_dwordx4 v[104:105], v[90:93], off offset:256
	v_mov_b32_e32 v96, v103
	v_pk_mul_f32 v[98:99], v[28:29], v[96:97] op_sel_hi:[1,0]
	v_add_u32_e32 v90, 0x90, v152
	v_mad_i64_i32 v[90:91], s[30:31], v90, s96, v[154:155]
	v_lshl_add_u64 v[94:95], v[90:91], 0, v[156:157]
	v_pk_mul_f32 v[92:93], v[32:33], v[96:97] op_sel_hi:[1,0]
	v_pk_mul_f32 v[90:91], v[30:31], v[96:97] op_sel_hi:[1,0]
	v_pk_mul_f32 v[100:101], v[26:27], v[96:97] op_sel_hi:[1,0]
	v_cvt_pk_bf16_f32 v90, v90, v91
	v_cvt_pk_bf16_f32 v91, v92, v93
	v_cvt_pk_bf16_f32 v92, v100, v101
	v_cvt_pk_bf16_f32 v93, v98, v99
	v_pk_mul_f32 v[86:87], v[86:87], v[96:97] op_sel_hi:[1,0]
	global_store_dwordx4 v[94:95], v[90:93], off
	v_pk_mul_f32 v[88:89], v[88:89], v[96:97] op_sel_hi:[1,0]
	v_readlane_b32 s9, v253, 21
	v_pk_mul_f32 v[90:91], v[84:85], v[96:97] op_sel_hi:[1,0]
	v_pk_mul_f32 v[84:85], v[82:83], v[96:97] op_sel_hi:[1,0]
	v_cvt_pk_bf16_f32 v82, v86, v87
	ds_read2_b32 v[86:87], v153 offset0:160 offset1:176
	v_cvt_pk_bf16_f32 v83, v88, v89
	v_cvt_pk_bf16_f32 v84, v84, v85
	v_cvt_pk_bf16_f32 v85, v90, v91
	global_store_dwordx4 v[94:95], v[82:85], off offset:256
	s_waitcnt lgkmcnt(0)
	v_pk_mul_f32 v[90:91], v[12:13], v[86:87] op_sel_hi:[1,0]
	v_pk_mul_f32 v[92:93], v[10:11], v[86:87] op_sel_hi:[1,0]
	v_add_u32_e32 v82, 0xa0, v152
	v_mad_i64_i32 v[82:83], s[30:31], v82, s96, v[154:155]
	v_lshl_add_u64 v[88:89], v[82:83], 0, v[156:157]
	v_pk_mul_f32 v[84:85], v[16:17], v[86:87] op_sel_hi:[1,0]
	v_pk_mul_f32 v[82:83], v[14:15], v[86:87] op_sel_hi:[1,0]
	v_pk_mul_f32 v[80:81], v[80:81], v[86:87] op_sel_hi:[1,0]
	v_cvt_pk_bf16_f32 v82, v82, v83
	v_cvt_pk_bf16_f32 v83, v84, v85
	v_cvt_pk_bf16_f32 v84, v92, v93
	v_cvt_pk_bf16_f32 v85, v90, v91
	global_store_dwordx4 v[88:89], v[82:85], off
	v_pk_mul_f32 v[78:79], v[78:79], v[86:87] op_sel_hi:[1,0]
	v_readlane_b32 s10, v253, 22
	v_pk_mul_f32 v[82:83], v[76:77], v[86:87] op_sel_hi:[1,0]
	v_pk_mul_f32 v[76:77], v[74:75], v[86:87] op_sel_hi:[1,0]
	v_cvt_pk_bf16_f32 v74, v78, v79
	v_cvt_pk_bf16_f32 v75, v80, v81
	v_cvt_pk_bf16_f32 v76, v76, v77
	v_cvt_pk_bf16_f32 v77, v82, v83
	global_store_dwordx4 v[88:89], v[74:77], off offset:256
	v_mov_b32_e32 v80, v87
	v_pk_mul_f32 v[82:83], v[4:5], v[80:81] op_sel_hi:[1,0]
	v_add_u32_e32 v74, 0xb0, v152
	v_mad_i64_i32 v[74:75], s[30:31], v74, s96, v[154:155]
	v_lshl_add_u64 v[78:79], v[74:75], 0, v[156:157]
	v_pk_mul_f32 v[76:77], v[8:9], v[80:81] op_sel_hi:[1,0]
	v_pk_mul_f32 v[74:75], v[6:7], v[80:81] op_sel_hi:[1,0]
	v_pk_mul_f32 v[84:85], v[2:3], v[80:81] op_sel_hi:[1,0]
	v_cvt_pk_bf16_f32 v74, v74, v75
	v_cvt_pk_bf16_f32 v75, v76, v77
	v_cvt_pk_bf16_f32 v76, v84, v85
	v_cvt_pk_bf16_f32 v77, v82, v83
	global_store_dwordx4 v[78:79], v[74:77], off
	v_pk_mul_f32 v[24:25], v[24:25], v[80:81] op_sel_hi:[1,0]
	v_pk_mul_f32 v[22:23], v[22:23], v[80:81] op_sel_hi:[1,0]
	v_pk_mul_f32 v[74:75], v[20:21], v[80:81] op_sel_hi:[1,0]
	v_pk_mul_f32 v[20:21], v[18:19], v[80:81] op_sel_hi:[1,0]
	v_cvt_pk_bf16_f32 v18, v22, v23
	v_cvt_pk_bf16_f32 v19, v24, v25
	v_cvt_pk_bf16_f32 v20, v20, v21
	v_cvt_pk_bf16_f32 v21, v74, v75
	v_readlane_b32 s11, v253, 23
	v_readlane_b32 s12, v253, 24
	v_readlane_b32 s13, v253, 25
	v_readlane_b32 s14, v253, 26
	v_readlane_b32 s15, v253, 27
	v_readlane_b32 s16, v253, 28
	v_readlane_b32 s17, v253, 29
	global_store_dwordx4 v[78:79], v[18:21], off offset:256
	s_mov_b64 s[30:31], 0

; DI int otid() { int t = threadIdx.x; asm volatile("" : "+v"(t)); return t; }
; #define PG8_STAGE(bufoff, gbase, voff) do { _Pragma("unroll") for (int _i = 0; _i < 2; ++_i) \
;     __builtin_amdgcn_global_load_lds((const unsigned*)((const char*)(gbase) + (voff)[_i]), (PG8_LAS unsigned*)(lds + (bufoff) + ldsw + _i * 8192), 16, 0, 0); } while (0)
; #define PG8_WAIT_V(n) asm volatile("s_waitcnt vmcnt(" #n ")" ::: "memory")
; #define PG8_BAR __builtin_amdgcn_s_barrier()
; template <class Epi>
; DI void gemm_phase(PG8_LAS unsigned char* lds, const Gemm g, const StaticOrder& S, const Epi& E) {
;   const int tid = otid(), wid = __builtin_amdgcn_readfirstlane(tid >> 6), lane = tid & 63, wr = wid >> 2, wc = wid & 3, fr = lane & 15, fq = lane >> 4;
;   const int K = g.K, nt = K / BK;
;   unsigned voffA[2], voffB[2];
; #pragma unroll
;   for (int i = 0; i < 2; ++i) { int R, C; stage_rc(tid * 16 + i * 8192, R, C); const int Rb = Epi::PERM ? ((R & ~31) + perm32(R & 31)) : R;
;     voffA[i] = (unsigned)(R * g.lda + C) * 2u; voffB[i] = (unsigned)(Rb * K + C) * 2u; }
;   const size_t kstep = (size_t)(BK * 2);
;   const size_t hstepA = (size_t)HALF * g.lda * 2, hstepB = (size_t)HALF * K * 2;
;   const size_t tstepA = 2 * hstepA, tstepB = 2 * hstepB;
;   const unsigned ldsw = (unsigned)wid * 1024u;
;   const int aoff = lds_byte(wr * 64 + fr, fq * 8), boff = lds_byte(wc * 32 + fr, fq * 8);
;     ...
;   Unit cur, nxt; int ui = 0;
;   if (!S.next(0, cur)) return;
;   f32x4 acc[2][2][4][2];
; #pragma unroll
;   for (int a = 0; a < 2; ++a)
; #pragma unroll
;     for (int b = 0; b < 2; ++b)
; #pragma unroll
;       for (int m = 0; m < 4; ++m)
; #pragma unroll
;         for (int n = 0; n < 2; ++n) acc[a][b][m][n] = (f32x4){0.f, 0.f, 0.f, 0.f};
;   bf16x8 At[4][2], B0[2][2], B1[2][2];
;   const char* cA = (const char*)g.A + (size_t)cur.pm * tstepA; const char* cB = (const char*)g.Bt + (size_t)cur.pn * tstepB;
;   PG8_STAGE(PG8_SB(0, 0), cB, voffB); PG8_STAGE(PG8_SA(0, 0), cA, voffA); PG8_STAGE(PG8_SB(0, 1), cB + hstepB, voffB); PG8_STAGE(PG8_SA(0, 1), cA + hstepA, voffA);
;   if (wr == 1) PG8_BAR;
;   PG8_WAIT_V(4); PG8_BAR;
;   PG8_STAGE(PG8_SB(1, 0), cB + kstep, voffB); PG8_STAGE(PG8_SA(1, 0), cA + kstep, voffA); PG8_STAGE(PG8_SB(1, 1), cB + hstepB + kstep, voffB);
;   PG8_WAIT_V(6); PG8_BAR;
.LBB0_1190:
	s_or_b64 exec, exec, s[30:31]
	v_readlane_b32 s4, v253, 1
	v_mov_b32_e32 v4, v200
	v_readlane_b32 s5, v253, 2
	s_waitcnt lgkmcnt(0)
	s_barrier
	s_andn2_b64 vcc, exec, s[4:5]
	v_readfirstlane_b32 s28, v4
	s_cbranch_vccnz .LBB0_1202
	v_lshlrev_b32_e32 v0, 4, v4
	v_add_u32_e32 v3, 0x2000, v0
	v_ashrrev_i32_e32 v2, 31, v3
	v_lshrrev_b32_e32 v2, 22, v2
	v_add_u32_e32 v2, v3, v2
	v_ashrrev_i32_e32 v2, 10, v2
	v_mul_i32_i24_e32 v5, 0x400, v2
	v_sub_u32_e32 v3, v3, v5
	v_lshrrev_b32_e32 v5, 4, v3
	v_bitop3_b32 v5, v5, v3, 32 bitop3:0x6c
	v_ashrrev_i32_e32 v3, 31, v5
	v_lshrrev_b32_e32 v3, 26, v3
	v_add_u32_e32 v6, v5, v3
	v_lshlrev_b32_e32 v7, 3, v2
	v_ashrrev_i32_e32 v3, 6, v6
	v_and_b32_e32 v7, -16, v7
	v_add_u32_e32 v7, v3, v7
	v_and_b32_e32 v8, 3, v3
	s_mov_b32 s4, 0x1fffe0
	v_lshrrev_b32_e32 v9, 2, v7
	v_lshlrev_b32_e32 v10, 1, v7
	v_and_b32_e32 v6, 0xc0, v6
	v_and_or_b32 v8, v7, s4, v8
	v_and_b32_e32 v9, 4, v9
	v_and_b32_e32 v10, 24, v10
	v_sub_u32_e32 v5, v5, v6
	v_or3_b32 v8, v8, v9, v10
	v_lshlrev_b32_e32 v9, 5, v2
	v_ashrrev_i16_sdwa v5, v202, sext(v5) dst_sel:DWORD dst_unused:UNUSED_PAD src0_sel:DWORD src1_sel:BYTE_0
	v_and_b32_e32 v9, 32, v9
	v_bfe_i32 v5, v5, 0, 16
	v_add_lshl_u32 v6, v9, v5, 1
	v_lshl_add_u32 v130, v8, 11, v6
	v_lshl_add_u32 v132, v7, 11, v6
	v_bfe_i32 v6, v4, 27, 1
	v_lshrrev_b32_e32 v6, 22, v6
	v_add_u32_e32 v6, v0, v6
	v_and_b32_e32 v6, 0xfffffc00, v6
	v_sub_u32_e32 v0, v0, v6
	v_lshrrev_b32_e32 v6, 4, v0
	v_bitop3_b32 v8, v6, v0, 32 bitop3:0x6c
	v_ashrrev_i32_e32 v0, 31, v0
	v_lshrrev_b32_e32 v0, 26, v0
	v_add_u32_e32 v0, v8, v0
	v_ashrrev_i32_e32 v6, 6, v0
	v_ashrrev_i32_e32 v0, 31, v4
	v_lshrrev_b32_e32 v0, 26, v0
	v_add_u32_e32 v0, v4, v0
	v_ashrrev_i32_e32 v7, 6, v0
	v_lshlrev_b32_e32 v0, 3, v7
	v_and_b32_e32 v0, -16, v0
	v_add_u32_e32 v9, v6, v0
	v_and_b32_e32 v0, 3, v6
	v_lshrrev_b32_e32 v10, 2, v9
	v_lshlrev_b32_e32 v11, 1, v9
	v_and_or_b32 v0, v9, s4, v0
	v_and_b32_e32 v10, 4, v10
	v_and_b32_e32 v11, 24, v11
	v_or3_b32 v0, v0, v10, v11
	v_mul_i32_i24_e32 v11, 64, v6
	v_sub_u32_e32 v8, v8, v11
	s_ashr_i32 s30, s28, 6
	v_lshlrev_b32_e32 v10, 5, v7
	v_ashrrev_i16_sdwa v8, v202, sext(v8) dst_sel:DWORD dst_unused:UNUSED_PAD src0_sel:DWORD src1_sel:BYTE_0
	s_lshl_b32 s34, s30, 10
	v_and_b32_e32 v10, 32, v10
	v_bfe_i32 v8, v8, 0, 16
	v_add_lshl_u32 v10, v10, v8, 1
	s_add_i32 s37, s34, 0
	v_readlane_b32 s4, v253, 12
	v_lshl_add_u32 v0, v0, 11, v10
	s_add_i32 m0, s37, 0x10000
	v_readlane_b32 s5, v253, 13
	v_lshl_add_u32 v142, v9, 11, v10
	s_add_i32 s54, s37, 0x2000
	s_add_i32 s55, s37, 0x4000
	s_add_i32 s56, s37, 0x6000
	s_ashr_i32 s31, s28, 8
	global_load_lds_dwordx4 v0, s[4:5]
	s_add_i32 m0, s37, 0x12000
	s_nop 0
	global_load_lds_dwordx4 v130, s[4:5]
	v_readlane_b32 s4, v253, 8
	s_mov_b32 m0, s37
	v_readlane_b32 s5, v253, 9
	s_nop 4
	global_load_lds_dwordx4 v142, s[4:5]
	s_mov_b32 m0, s54
	s_nop 0
	global_load_lds_dwordx4 v132, s[4:5]
	v_readlane_b32 s4, v253, 6
	s_add_i32 m0, s37, 0x14000
	v_readlane_b32 s5, v253, 7
	s_nop 4
	global_load_lds_dwordx4 v0, s[4:5]
	s_add_i32 m0, s37, 0x16000
	s_cmp_lg_u32 s31, 1
	global_load_lds_dwordx4 v130, s[4:5]
	v_readlane_b32 s4, v253, 10
	s_mov_b32 m0, s55
	v_readlane_b32 s5, v253, 11
	s_nop 4
	global_load_lds_dwordx4 v142, s[4:5]
	s_mov_b32 m0, s56
	s_nop 0
	global_load_lds_dwordx4 v132, s[4:5]
	s_cbranch_scc1 .LBB0_1193
	s_barrier
	s_setprio 1

; #define PG8_STAGE(bufoff, gbase, voff) do { _Pragma("unroll") for (int _i = 0; _i < 2; ++_i) \
;     __builtin_amdgcn_global_load_lds((const unsigned*)((const char*)(gbase) + (voff)[_i]), (PG8_LAS unsigned*)(lds + (bufoff) + ldsw + _i * 8192), 16, 0, 0); } while (0)
; #define PG8_LDA(dst, b, h) do { _Pragma("unroll") for (int m = 0; m < 4; ++m) _Pragma("unroll") for (int k = 0; k < 2; ++k) dst[m][k] = *(const PG8_LAS bf16x8*)(lds + PG8_SA(b, h) + aoff + m * 2048 + k * 1024); } while (0)
; #define PG8_LDB(dst, b, h) do { _Pragma("unroll") for (int n = 0; n < 2; ++n) _Pragma("unroll") for (int k = 0; k < 2; ++k) dst[n][k] = *(const PG8_LAS bf16x8*)(lds + PG8_SB(b, h) + boff + n * 2048 + k * 1024); } while (0)
; #define PG8_MMA(ai, bj, At, Bt) do { __builtin_amdgcn_s_setprio(1); _Pragma("unroll") for (int m = 0; m < 4; ++m) _Pragma("unroll") for (int n = 0; n < 2; ++n) _Pragma("unroll") for (int k = 0; k < 2; ++k) \
;     acc[ai][bj][m][n] = __builtin_amdgcn_mfma_f32_16x16x32_bf16(Bt[n][k], At[m][k], acc[ai][bj][m][n], 0, 0, 0); __builtin_amdgcn_s_setprio(0); } while (0)
; #define PG8_WAIT_L(n) asm volatile("s_waitcnt lgkmcnt(" #n ")" ::: "memory")
; #define PG8_BAR __builtin_amdgcn_s_barrier()
; #define PG8_SCHED __builtin_amdgcn_sched_barrier(0)
; template <class Epi>
; DI void gemm_phase(PG8_LAS unsigned char* lds, const Gemm g, const StaticOrder& S, const Epi& E) {
;     ...
;     for (int t = 0; t < nt; t += 2) {
;       const bool last = (t == nt - 2);
;       const char* a1 = cA + (size_t)(t + 1) * kstep;
;       const char* a2 = last ? nA : cA + (size_t)(t + 2) * kstep; const char* b2 = last ? nB : cB + (size_t)(t + 2) * kstep;
;       const char* a3 = a2 + kstep; const char* b3 = b2 + kstep;
;       PG8_LDB(B0, 0, 0); PG8_SCHED; PG8_LDA(At, 0, 0); PG8_STAGE(PG8_SA(1, 1), a1 + hstepA, voffA);
;       PG8_WAIT_L(8); PG8_BAR; PG8_WAIT_L(0); PG8_MMA(0, 0, At, B0); PG8_BAR; PG8_SCHED;
;       PG8_LDB(B1, 0, 1); PG8_STAGE(PG8_SB(0, 0), b2, voffB);
;       PG8_BAR; PG8_WAIT_L(0); PG8_MMA(0, 1, At, B1); PG8_BAR;
;       PG8_LDA(At, 0, 1); PG8_STAGE(PG8_SA(0, 0), a2, voffA);
;       PG8_BAR; PG8_WAIT_L(0); PG8_MMA(1, 0, At, B0); PG8_BAR; PG8_SCHED;
.LBB0_1197:
	s_add_u32 s50, s48, 0xfffc0080
	s_addc_u32 s51, s49, -1
	s_add_i32 s68, 0, 0x10000
	v_add_u32_e32 v157, s68, v153
	ds_read_b128 v[148:151], v157
	ds_read_b128 v[158:161], v157 offset:1024
	ds_read_b128 v[162:165], v157 offset:2048
	ds_read_b128 v[166:169], v157 offset:3072
	s_cmp_eq_u32 s67, 12
	s_cselect_b32 s53, s43, s51
	s_cselect_b32 s52, s63, s50
	s_cselect_b32 s51, s31, s66
	s_cselect_b32 s50, s64, s65
	v_lshl_add_u64 v[198:199], s[48:49], 0, v[144:145]
	s_add_i32 m0, s37, 0xc000
	ds_read_b128 v[170:173], v156
	ds_read_b128 v[174:177], v156 offset:1024
	ds_read_b128 v[178:181], v156 offset:2048
	ds_read_b128 v[182:185], v156 offset:3072
	ds_read_b128 v[186:189], v156 offset:4096
	ds_read_b128 v[190:193], v156 offset:5120
	ds_read_b128 v[194:197], v156 offset:6144
	ds_read_b128 v[222:225], v156 offset:7168
	global_load_lds_dwordx4 v[198:199], off
	v_lshl_add_u64 v[198:199], s[48:49], 0, v[146:147]
	s_add_i32 m0, s37, 0xe000
	s_nop 0
	global_load_lds_dwordx4 v[198:199], off
	s_waitcnt lgkmcnt(8)
	s_barrier
	s_waitcnt lgkmcnt(0)
	s_waitcnt lgkmcnt(0)
	v_mfma_f32_16x16x32_bf16 v[126:129], v[148:151], v[170:173], v[126:129]
	v_mfma_f32_16x16x32_bf16 v[122:125], v[162:165], v[170:173], v[122:125]
	v_mfma_f32_16x16x32_bf16 v[118:121], v[148:151], v[178:181], v[118:121]
	v_mfma_f32_16x16x32_bf16 v[110:113], v[162:165], v[178:181], v[110:113]
	v_mfma_f32_16x16x32_bf16 v[94:97], v[148:151], v[186:189], v[94:97]
	v_mfma_f32_16x16x32_bf16 v[90:93], v[162:165], v[186:189], v[90:93]
	v_mfma_f32_16x16x32_bf16 v[86:89], v[148:151], v[194:197], v[86:89]
	v_mfma_f32_16x16x32_bf16 v[78:81], v[162:165], v[194:197], v[78:81]
	v_mfma_f32_16x16x32_bf16 v[126:129], v[158:161], v[174:177], v[126:129]
	v_mfma_f32_16x16x32_bf16 v[122:125], v[166:169], v[174:177], v[122:125]
	v_mfma_f32_16x16x32_bf16 v[118:121], v[158:161], v[182:185], v[118:121]
	v_mfma_f32_16x16x32_bf16 v[110:113], v[166:169], v[182:185], v[110:113]
	v_mfma_f32_16x16x32_bf16 v[94:97], v[158:161], v[190:193], v[94:97]
	v_mfma_f32_16x16x32_bf16 v[90:93], v[166:169], v[190:193], v[90:93]
	v_mfma_f32_16x16x32_bf16 v[86:89], v[158:161], v[222:225], v[86:89]
	v_mfma_f32_16x16x32_bf16 v[78:81], v[166:169], v[222:225], v[78:81]
	s_barrier
	s_add_i32 s70, 0, 0x14000
	s_add_i32 s68, s68, s34
	v_add_u32_e32 v157, s70, v153
	v_lshl_add_u64 v[198:199], s[50:51], 0, v[0:1]
	s_mov_b32 m0, s68
	ds_read_b128 v[226:229], v157
	ds_read_b128 v[230:233], v157 offset:1024
	ds_read_b128 v[234:237], v157 offset:2048
	ds_read_b128 v[238:241], v157 offset:3072
	global_load_lds_dwordx4 v[198:199], off
	v_lshl_add_u64 v[242:243], s[50:51], 0, v[130:131]
	s_add_i32 m0, s68, 0x2000
	s_nop 0
	global_load_lds_dwordx4 v[242:243], off
	s_barrier
	s_waitcnt lgkmcnt(0)
	s_waitcnt lgkmcnt(0)
	v_mfma_f32_16x16x32_bf16 v[114:117], v[226:229], v[170:173], v[114:117]
	v_mfma_f32_16x16x32_bf16 v[106:109], v[234:237], v[170:173], v[106:109]
	v_mfma_f32_16x16x32_bf16 v[102:105], v[226:229], v[178:181], v[102:105]
	v_mfma_f32_16x16x32_bf16 v[98:101], v[234:237], v[178:181], v[98:101]
	v_mfma_f32_16x16x32_bf16 v[82:85], v[226:229], v[186:189], v[82:85]
	v_mfma_f32_16x16x32_bf16 v[74:77], v[234:237], v[186:189], v[74:77]
	v_mfma_f32_16x16x32_bf16 v[70:73], v[226:229], v[194:197], v[70:73]
	v_mfma_f32_16x16x32_bf16 v[66:69], v[234:237], v[194:197], v[66:69]
	v_mfma_f32_16x16x32_bf16 v[114:117], v[230:233], v[174:177], v[114:117]
	v_mfma_f32_16x16x32_bf16 v[106:109], v[238:241], v[174:177], v[106:109]
	v_mfma_f32_16x16x32_bf16 v[102:105], v[230:233], v[182:185], v[102:105]
	v_mfma_f32_16x16x32_bf16 v[98:101], v[238:241], v[182:185], v[98:101]
	v_mfma_f32_16x16x32_bf16 v[82:85], v[230:233], v[190:193], v[82:85]
	v_mfma_f32_16x16x32_bf16 v[74:77], v[238:241], v[190:193], v[74:77]
	v_mfma_f32_16x16x32_bf16 v[70:73], v[230:233], v[222:225], v[70:73]
	v_mfma_f32_16x16x32_bf16 v[66:69], v[238:241], v[222:225], v[66:69]
	s_mov_b32 m0, s37
	v_lshl_add_u64 v[244:245], s[52:53], 0, v[142:143]
	s_barrier
	ds_read_b128 v[170:173], v156 offset:16384
	ds_read_b128 v[174:177], v156 offset:17408
	ds_read_b128 v[178:181], v156 offset:18432
	ds_read_b128 v[182:185], v156 offset:19456
	ds_read_b128 v[186:189], v156 offset:20480
	ds_read_b128 v[190:193], v156 offset:21504
	ds_read_b128 v[194:197], v156 offset:22528
	ds_read_b128 v[222:225], v156 offset:23552
	global_load_lds_dwordx4 v[244:245], off
	v_lshl_add_u64 v[246:247], s[52:53], 0, v[132:133]
	s_mov_b32 m0, s54
	s_nop 0
	global_load_lds_dwordx4 v[246:247], off
	s_barrier
	s_waitcnt lgkmcnt(0)
	s_waitcnt lgkmcnt(0)
	v_mfma_f32_16x16x32_bf16 v[62:65], v[148:151], v[170:173], v[62:65]
	v_mfma_f32_16x16x32_bf16 v[58:61], v[162:165], v[170:173], v[58:61]
	v_mfma_f32_16x16x32_bf16 v[54:57], v[148:151], v[178:181], v[54:57]
	v_mfma_f32_16x16x32_bf16 v[46:49], v[162:165], v[178:181], v[46:49]
	v_mfma_f32_16x16x32_bf16 v[30:33], v[148:151], v[186:189], v[30:33]
	v_mfma_f32_16x16x32_bf16 v[26:29], v[162:165], v[186:189], v[26:29]
	v_mfma_f32_16x16x32_bf16 v[22:25], v[148:151], v[194:197], v[22:25]
	v_mfma_f32_16x16x32_bf16 v[14:17], v[162:165], v[194:197], v[14:17]
	v_mfma_f32_16x16x32_bf16 v[62:65], v[158:161], v[174:177], v[62:65]
	v_mfma_f32_16x16x32_bf16 v[58:61], v[166:169], v[174:177], v[58:61]
	v_mfma_f32_16x16x32_bf16 v[54:57], v[158:161], v[182:185], v[54:57]
	v_mfma_f32_16x16x32_bf16 v[46:49], v[166:169], v[182:185], v[46:49]
	v_mfma_f32_16x16x32_bf16 v[30:33], v[158:161], v[190:193], v[30:33]
	v_mfma_f32_16x16x32_bf16 v[26:29], v[166:169], v[190:193], v[26:29]
	v_mfma_f32_16x16x32_bf16 v[22:25], v[158:161], v[222:225], v[22:25]
	v_mfma_f32_16x16x32_bf16 v[14:17], v[166:169], v[222:225], v[14:17]
	s_barrier
; #define PG8_STAGE(bufoff, gbase, voff) do { _Pragma("unroll") for (int _i = 0; _i < 2; ++_i) \
;     __builtin_amdgcn_global_load_lds((const unsigned*)((const char*)(gbase) + (voff)[_i]), (PG8_LAS unsigned*)(lds + (bufoff) + ldsw + _i * 8192), 16, 0, 0); } while (0)
; #define PG8_LDA(dst, b, h) do { _Pragma("unroll") for (int m = 0; m < 4; ++m) _Pragma("unroll") for (int k = 0; k < 2; ++k) dst[m][k] = *(const PG8_LAS bf16x8*)(lds + PG8_SA(b, h) + aoff + m * 2048 + k * 1024); } while (0)
; #define PG8_LDB(dst, b, h) do { _Pragma("unroll") for (int n = 0; n < 2; ++n) _Pragma("unroll") for (int k = 0; k < 2; ++k) dst[n][k] = *(const PG8_LAS bf16x8*)(lds + PG8_SB(b, h) + boff + n * 2048 + k * 1024); } while (0)
; #define PG8_MMA(ai, bj, At, Bt) do { __builtin_amdgcn_s_setprio(1); _Pragma("unroll") for (int m = 0; m < 4; ++m) _Pragma("unroll") for (int n = 0; n < 2; ++n) _Pragma("unroll") for (int k = 0; k < 2; ++k) \
;     acc[ai][bj][m][n] = __builtin_amdgcn_mfma_f32_16x16x32_bf16(Bt[n][k], At[m][k], acc[ai][bj][m][n], 0, 0, 0); __builtin_amdgcn_s_setprio(0); } while (0)
; #define PG8_WAIT_V(n) asm volatile("s_waitcnt vmcnt(" #n ")" ::: "memory")
; #define PG8_WAIT_L(n) asm volatile("s_waitcnt lgkmcnt(" #n ")" ::: "memory")
; #define PG8_BAR __builtin_amdgcn_s_barrier()
; #define PG8_SCHED __builtin_amdgcn_sched_barrier(0)
; template <class Epi>
; DI void gemm_phase(PG8_LAS unsigned char* lds, const Gemm g, const StaticOrder& S, const Epi& E) {
;     ...
;       PG8_STAGE(PG8_SB(0, 1), b2 + hstepB, voffB);
;       PG8_WAIT_V(6); PG8_BAR; PG8_MMA(1, 1, At, B1); PG8_BAR;
;       PG8_LDB(B0, 1, 0); PG8_SCHED; PG8_LDA(At, 1, 0); PG8_STAGE(PG8_SA(0, 1), a2 + hstepA, voffA);
;       PG8_WAIT_L(8); PG8_BAR; PG8_WAIT_L(0); PG8_MMA(0, 0, At, B0); PG8_BAR; PG8_SCHED;
;       PG8_LDB(B1, 1, 1); PG8_STAGE(PG8_SB(1, 0), b3, voffB);
;       PG8_BAR; PG8_WAIT_L(0); PG8_MMA(0, 1, At, B1); PG8_BAR;
;       PG8_LDA(At, 1, 1); PG8_STAGE(PG8_SA(1, 0), a3, voffA);
	s_add_u32 s68, s50, 0x40000
	s_addc_u32 s69, s51, 0
	s_add_i32 s70, s70, s34
	v_lshl_add_u64 v[148:149], s[68:69], 0, v[0:1]
	s_mov_b32 m0, s70
	s_nop 0
	global_load_lds_dwordx4 v[148:149], off
	v_lshl_add_u64 v[148:149], s[68:69], 0, v[130:131]
	s_add_i32 m0, s70, 0x2000
	s_nop 0
	global_load_lds_dwordx4 v[148:149], off
	s_waitcnt vmcnt(6)
	s_barrier
	v_mfma_f32_16x16x32_bf16 v[50:53], v[226:229], v[170:173], v[50:53]
	v_mfma_f32_16x16x32_bf16 v[42:45], v[234:237], v[170:173], v[42:45]
	v_mfma_f32_16x16x32_bf16 v[38:41], v[226:229], v[178:181], v[38:41]
	v_mfma_f32_16x16x32_bf16 v[34:37], v[234:237], v[178:181], v[34:37]
	v_mfma_f32_16x16x32_bf16 v[18:21], v[226:229], v[186:189], v[18:21]
	v_mfma_f32_16x16x32_bf16 v[10:13], v[234:237], v[186:189], v[10:13]
	v_mfma_f32_16x16x32_bf16 v[6:9], v[226:229], v[194:197], v[6:9]
	v_mfma_f32_16x16x32_bf16 v[2:5], v[234:237], v[194:197], v[2:5]
	v_mfma_f32_16x16x32_bf16 v[50:53], v[230:233], v[174:177], v[50:53]
	v_mfma_f32_16x16x32_bf16 v[42:45], v[238:241], v[174:177], v[42:45]
	v_mfma_f32_16x16x32_bf16 v[38:41], v[230:233], v[182:185], v[38:41]
	v_mfma_f32_16x16x32_bf16 v[34:37], v[238:241], v[182:185], v[34:37]
	v_mfma_f32_16x16x32_bf16 v[18:21], v[230:233], v[190:193], v[18:21]
	v_mfma_f32_16x16x32_bf16 v[10:13], v[238:241], v[190:193], v[10:13]
	v_mfma_f32_16x16x32_bf16 v[6:9], v[230:233], v[222:225], v[6:9]
	v_mfma_f32_16x16x32_bf16 v[2:5], v[238:241], v[222:225], v[2:5]
	s_add_i32 s68, 0, 0x18000
	v_add_u32_e32 v157, s68, v153
	s_barrier
	ds_read_b128 v[148:151], v157
	ds_read_b128 v[158:161], v157 offset:1024
	ds_read_b128 v[162:165], v157 offset:2048
	ds_read_b128 v[166:169], v157 offset:3072
	s_add_u32 s52, s52, 0x40000
	s_addc_u32 s53, s53, 0
	s_mov_b32 m0, s55
	v_lshl_add_u64 v[226:227], s[52:53], 0, v[142:143]
	ds_read_b128 v[170:173], v156 offset:32768
	ds_read_b128 v[174:177], v156 offset:33792
	ds_read_b128 v[178:181], v156 offset:34816
	ds_read_b128 v[182:185], v156 offset:35840
	ds_read_b128 v[186:189], v156 offset:36864
	ds_read_b128 v[190:193], v156 offset:37888
	ds_read_b128 v[194:197], v156 offset:38912
	ds_read_b128 v[222:225], v156 offset:39936
	global_load_lds_dwordx4 v[226:227], off
	v_lshl_add_u64 v[226:227], s[52:53], 0, v[132:133]
	s_mov_b32 m0, s56
	s_nop 0
	global_load_lds_dwordx4 v[226:227], off
	s_waitcnt lgkmcnt(8)
	s_barrier
	s_waitcnt lgkmcnt(0)
	s_waitcnt lgkmcnt(0)
	v_mfma_f32_16x16x32_bf16 v[126:129], v[148:151], v[170:173], v[126:129]
	v_mfma_f32_16x16x32_bf16 v[122:125], v[162:165], v[170:173], v[122:125]
	v_mfma_f32_16x16x32_bf16 v[118:121], v[148:151], v[178:181], v[118:121]
	v_mfma_f32_16x16x32_bf16 v[110:113], v[162:165], v[178:181], v[110:113]
	v_mfma_f32_16x16x32_bf16 v[94:97], v[148:151], v[186:189], v[94:97]
	v_mfma_f32_16x16x32_bf16 v[90:93], v[162:165], v[186:189], v[90:93]
	v_mfma_f32_16x16x32_bf16 v[86:89], v[148:151], v[194:197], v[86:89]
	v_mfma_f32_16x16x32_bf16 v[78:81], v[162:165], v[194:197], v[78:81]
	v_mfma_f32_16x16x32_bf16 v[126:129], v[158:161], v[174:177], v[126:129]
	v_mfma_f32_16x16x32_bf16 v[122:125], v[166:169], v[174:177], v[122:125]
	v_mfma_f32_16x16x32_bf16 v[118:121], v[158:161], v[182:185], v[118:121]
	v_mfma_f32_16x16x32_bf16 v[110:113], v[166:169], v[182:185], v[110:113]
	v_mfma_f32_16x16x32_bf16 v[94:97], v[158:161], v[190:193], v[94:97]
	v_mfma_f32_16x16x32_bf16 v[90:93], v[166:169], v[190:193], v[90:93]
	v_mfma_f32_16x16x32_bf16 v[86:89], v[158:161], v[222:225], v[86:89]
	v_mfma_f32_16x16x32_bf16 v[78:81], v[166:169], v[222:225], v[78:81]
	s_barrier
	s_add_i32 s52, 0, 0x1c000
	s_add_i32 s53, s68, s34
	v_add_u32_e32 v157, s52, v153
	v_lshl_add_u64 v[198:199], v[198:199], 0, s[86:87]
	s_mov_b32 m0, s53
	ds_read_b128 v[226:229], v157
	ds_read_b128 v[230:233], v157 offset:1024
	ds_read_b128 v[234:237], v157 offset:2048
	ds_read_b128 v[238:241], v157 offset:3072
	global_load_lds_dwordx4 v[198:199], off
	v_lshl_add_u64 v[198:199], v[242:243], 0, s[86:87]
	s_add_i32 m0, s53, 0x2000
	s_nop 0
	global_load_lds_dwordx4 v[198:199], off
	s_barrier
	s_waitcnt lgkmcnt(0)
	s_waitcnt lgkmcnt(0)
	v_mfma_f32_16x16x32_bf16 v[114:117], v[226:229], v[170:173], v[114:117]
	v_mfma_f32_16x16x32_bf16 v[106:109], v[234:237], v[170:173], v[106:109]
	v_mfma_f32_16x16x32_bf16 v[102:105], v[226:229], v[178:181], v[102:105]
	v_mfma_f32_16x16x32_bf16 v[98:101], v[234:237], v[178:181], v[98:101]
	v_mfma_f32_16x16x32_bf16 v[82:85], v[226:229], v[186:189], v[82:85]
	v_mfma_f32_16x16x32_bf16 v[74:77], v[234:237], v[186:189], v[74:77]
	v_mfma_f32_16x16x32_bf16 v[70:73], v[226:229], v[194:197], v[70:73]
	v_mfma_f32_16x16x32_bf16 v[66:69], v[234:237], v[194:197], v[66:69]
	v_mfma_f32_16x16x32_bf16 v[114:117], v[230:233], v[174:177], v[114:117]
	v_mfma_f32_16x16x32_bf16 v[106:109], v[238:241], v[174:177], v[106:109]
	v_mfma_f32_16x16x32_bf16 v[102:105], v[230:233], v[182:185], v[102:105]
	v_mfma_f32_16x16x32_bf16 v[98:101], v[238:241], v[182:185], v[98:101]
	v_mfma_f32_16x16x32_bf16 v[82:85], v[230:233], v[190:193], v[82:85]
	v_mfma_f32_16x16x32_bf16 v[74:77], v[238:241], v[190:193], v[74:77]
	v_mfma_f32_16x16x32_bf16 v[70:73], v[230:233], v[222:225], v[70:73]
	v_mfma_f32_16x16x32_bf16 v[66:69], v[238:241], v[222:225], v[66:69]
	s_mov_b32 m0, s57
	v_lshl_add_u64 v[198:199], v[244:245], 0, s[86:87]
	s_barrier
	ds_read_b128 v[170:173], v156 offset:49152
	ds_read_b128 v[174:177], v156 offset:50176
	ds_read_b128 v[178:181], v156 offset:51200
	ds_read_b128 v[182:185], v156 offset:52224
	ds_read_b128 v[186:189], v156 offset:53248
	ds_read_b128 v[190:193], v156 offset:54272
	ds_read_b128 v[194:197], v156 offset:55296
	ds_read_b128 v[222:225], v156 offset:56320
	global_load_lds_dwordx4 v[198:199], off
	v_lshl_add_u64 v[198:199], v[246:247], 0, s[86:87]
	s_mov_b32 m0, s58
	s_nop 0
	global_load_lds_dwordx4 v[198:199], off
	s_barrier
; DI unsigned pk2(float lo, float hi) { f32x2 v = {lo, hi}; bf2_t r = __builtin_convertvector(v, bf2_t); return __builtin_bit_cast(unsigned, r); }
; #define PG8_STAGE(bufoff, gbase, voff) do { _Pragma("unroll") for (int _i = 0; _i < 2; ++_i) \
;     __builtin_amdgcn_global_load_lds((const unsigned*)((const char*)(gbase) + (voff)[_i]), (PG8_LAS unsigned*)(lds + (bufoff) + ldsw + _i * 8192), 16, 0, 0); } while (0)
; #define PG8_MMA(ai, bj, At, Bt) do { __builtin_amdgcn_s_setprio(1); _Pragma("unroll") for (int m = 0; m < 4; ++m) _Pragma("unroll") for (int n = 0; n < 2; ++n) _Pragma("unroll") for (int k = 0; k < 2; ++k) \
;     acc[ai][bj][m][n] = __builtin_amdgcn_mfma_f32_16x16x32_bf16(Bt[n][k], At[m][k], acc[ai][bj][m][n], 0, 0, 0); __builtin_amdgcn_s_setprio(0); } while (0)
; #define PG8_WAIT_V(n) asm volatile("s_waitcnt vmcnt(" #n ")" ::: "memory")
; #define PG8_WAIT_L(n) asm volatile("s_waitcnt lgkmcnt(" #n ")" ::: "memory")
; #define PG8_BAR __builtin_amdgcn_s_barrier()
; #define PG8_SCHED __builtin_amdgcn_sched_barrier(0)
;   DI void operator()(const f32x4 (&acc)[2][2][4][2], const Unit& u, int wr, int wc, int fr, int fq, const PG8_LAS float* sR) const {
;     ...
;     const int col0 = u.pn * BM + wc * 32 + 8 * fq;
; #pragma unroll
;     for (int ai = 0; ai < 2; ++ai)
; #pragma unroll
;       for (int m = 0; m < 4; ++m) {
;         bf16_t* rowp = C + (size_t)(row0 + ai * HALF + m * 16) * ldc + col0;
;         const float rs = sR[ai * 128 + m * 16 + fr];
; #pragma unroll
;         for (int bj = 0; bj < 2; ++bj) {
;           const f32x4 v0 = acc[ai][bj][m][0] * rs, v1 = acc[ai][bj][m][1] * rs;
;           u32x4 w; w[0] = pk2(v0[0], v0[1]); w[1] = pk2(v0[2], v0[3]); w[2] = pk2(v1[0], v1[1]); w[3] = pk2(v1[2], v1[3]);
;           *(u32x4*)(rowp + bj * HALF) = w;
;         }
;       }
; template <class Epi>
; DI void gemm_phase(PG8_LAS unsigned char* lds, const Gemm g, const StaticOrder& S, const Epi& E) {
;     ...
;       PG8_BAR; PG8_WAIT_L(0); PG8_MMA(1, 0, At, B0); PG8_BAR; PG8_SCHED;
;       PG8_STAGE(PG8_SB(1, 1), b3 + hstepB, voffB);
;       PG8_WAIT_V(6); PG8_BAR; PG8_MMA(1, 1, At, B1); PG8_BAR;
	s_waitcnt lgkmcnt(0)
	s_waitcnt lgkmcnt(0)
	v_mfma_f32_16x16x32_bf16 v[62:65], v[148:151], v[170:173], v[62:65]
	v_mfma_f32_16x16x32_bf16 v[58:61], v[162:165], v[170:173], v[58:61]
	v_mfma_f32_16x16x32_bf16 v[54:57], v[148:151], v[178:181], v[54:57]
	v_mfma_f32_16x16x32_bf16 v[46:49], v[162:165], v[178:181], v[46:49]
	v_mfma_f32_16x16x32_bf16 v[30:33], v[148:151], v[186:189], v[30:33]
	v_mfma_f32_16x16x32_bf16 v[26:29], v[162:165], v[186:189], v[26:29]
	v_mfma_f32_16x16x32_bf16 v[22:25], v[148:151], v[194:197], v[22:25]
	v_mfma_f32_16x16x32_bf16 v[14:17], v[162:165], v[194:197], v[14:17]
	v_mfma_f32_16x16x32_bf16 v[62:65], v[158:161], v[174:177], v[62:65]
	v_mfma_f32_16x16x32_bf16 v[58:61], v[166:169], v[174:177], v[58:61]
	v_mfma_f32_16x16x32_bf16 v[54:57], v[158:161], v[182:185], v[54:57]
	v_mfma_f32_16x16x32_bf16 v[46:49], v[166:169], v[182:185], v[46:49]
	v_mfma_f32_16x16x32_bf16 v[30:33], v[158:161], v[190:193], v[30:33]
	v_mfma_f32_16x16x32_bf16 v[26:29], v[166:169], v[190:193], v[26:29]
	v_mfma_f32_16x16x32_bf16 v[22:25], v[158:161], v[222:225], v[22:25]
	v_mfma_f32_16x16x32_bf16 v[14:17], v[166:169], v[222:225], v[14:17]
	s_barrier
	s_add_u32 s50, s50, 0x40080
	s_addc_u32 s51, s51, 0
	s_add_i32 s52, s52, s34
	v_lshl_add_u64 v[148:149], s[50:51], 0, v[0:1]
	s_mov_b32 m0, s52
	s_nop 0
	global_load_lds_dwordx4 v[148:149], off
	v_lshl_add_u64 v[148:149], s[50:51], 0, v[130:131]
	s_add_i32 m0, s52, 0x2000
	s_nop 0
	global_load_lds_dwordx4 v[148:149], off
	s_waitcnt vmcnt(6)
	s_barrier
	v_mfma_f32_16x16x32_bf16 v[50:53], v[226:229], v[170:173], v[50:53]
	v_mfma_f32_16x16x32_bf16 v[42:45], v[234:237], v[170:173], v[42:45]
	v_mfma_f32_16x16x32_bf16 v[38:41], v[226:229], v[178:181], v[38:41]
	v_mfma_f32_16x16x32_bf16 v[34:37], v[234:237], v[178:181], v[34:37]
	v_mfma_f32_16x16x32_bf16 v[18:21], v[226:229], v[186:189], v[18:21]
	v_mfma_f32_16x16x32_bf16 v[10:13], v[234:237], v[186:189], v[10:13]
	v_mfma_f32_16x16x32_bf16 v[6:9], v[226:229], v[194:197], v[6:9]
	v_mfma_f32_16x16x32_bf16 v[2:5], v[234:237], v[194:197], v[2:5]
	v_mfma_f32_16x16x32_bf16 v[50:53], v[230:233], v[174:177], v[50:53]
	v_mfma_f32_16x16x32_bf16 v[42:45], v[238:241], v[174:177], v[42:45]
	v_mfma_f32_16x16x32_bf16 v[38:41], v[230:233], v[182:185], v[38:41]
	v_mfma_f32_16x16x32_bf16 v[34:37], v[238:241], v[182:185], v[34:37]
	v_mfma_f32_16x16x32_bf16 v[18:21], v[230:233], v[190:193], v[18:21]
	v_mfma_f32_16x16x32_bf16 v[10:13], v[238:241], v[190:193], v[10:13]
	v_mfma_f32_16x16x32_bf16 v[6:9], v[230:233], v[222:225], v[6:9]
	v_mfma_f32_16x16x32_bf16 v[2:5], v[238:241], v[222:225], v[2:5]
	s_add_i32 s67, s67, 2
	s_add_u32 s48, s48, 0x100
	s_addc_u32 s49, s49, 0
	s_add_u32 s65, s65, 0x100
	s_addc_u32 s66, s66, 0
	s_cmp_gt_u32 s67, 13
	s_barrier
	s_cbranch_scc0 .LBB0_1197
	v_lshl_add_u32 v164, s61, 10, v154
	ds_read2_b32 v[160:161], v164 offset1:16
	v_readlane_b32 s4, v253, 16
	v_lshl_or_b32 v150, s60, 8, v155
	v_readlane_b32 s18, v253, 30
	v_readlane_b32 s19, v253, 31
	v_lshl_add_u32 v157, s62, 8, v152
	v_ashrrev_i32_e32 v151, 31, v150
	v_mov_b64_e32 v[148:149], s[18:19]
	v_mad_i64_i32 v[158:159], s[48:49], v157, s36, v[148:149]
	v_lshlrev_b64 v[150:151], 1, v[150:151]
	s_waitcnt lgkmcnt(0)
	v_pk_mul_f32 v[128:129], v[128:129], v[160:161] op_sel_hi:[1,0]
	v_pk_mul_f32 v[126:127], v[126:127], v[160:161] op_sel_hi:[1,0]
	v_pk_mul_f32 v[162:163], v[124:125], v[160:161] op_sel_hi:[1,0]
	v_pk_mul_f32 v[124:125], v[122:123], v[160:161] op_sel_hi:[1,0]
	v_lshl_add_u64 v[158:159], v[158:159], 0, v[150:151]
	v_cvt_pk_bf16_f32 v122, v126, v127
	v_cvt_pk_bf16_f32 v123, v128, v129
	v_cvt_pk_bf16_f32 v124, v124, v125
	v_cvt_pk_bf16_f32 v125, v162, v163
	global_store_dwordx4 v[158:159], v[122:125], off
	v_pk_mul_f32 v[116:117], v[116:117], v[160:161] op_sel_hi:[1,0]
	v_pk_mul_f32 v[114:115], v[114:115], v[160:161] op_sel_hi:[1,0]
	v_pk_mul_f32 v[122:123], v[108:109], v[160:161] op_sel_hi:[1,0]
	v_pk_mul_f32 v[108:109], v[106:107], v[160:161] op_sel_hi:[1,0]
	v_cvt_pk_bf16_f32 v106, v114, v115
	v_cvt_pk_bf16_f32 v107, v116, v117
	v_cvt_pk_bf16_f32 v108, v108, v109
	v_cvt_pk_bf16_f32 v109, v122, v123
	global_store_dwordx4 v[158:159], v[106:109], off offset:256
	v_mov_b32_e32 v116, v161
	v_pk_mul_f32 v[112:113], v[112:113], v[116:117] op_sel_hi:[1,0]
	v_or_b32_e32 v106, 16, v157
	v_mad_i64_i32 v[106:107], s[48:49], v106, s36, v[148:149]
	v_lshl_add_u64 v[114:115], v[106:107], 0, v[150:151]
	v_pk_mul_f32 v[108:109], v[120:121], v[116:117] op_sel_hi:[1,0]
	v_pk_mul_f32 v[106:107], v[118:119], v[116:117] op_sel_hi:[1,0]
	v_pk_mul_f32 v[110:111], v[110:111], v[116:117] op_sel_hi:[1,0]
	v_cvt_pk_bf16_f32 v106, v106, v107
	v_cvt_pk_bf16_f32 v107, v108, v109
	v_cvt_pk_bf16_f32 v108, v110, v111
	v_cvt_pk_bf16_f32 v109, v112, v113
	global_store_dwordx4 v[114:115], v[106:109], off
	v_pk_mul_f32 v[104:105], v[104:105], v[116:117] op_sel_hi:[1,0]
	v_pk_mul_f32 v[102:103], v[102:103], v[116:117] op_sel_hi:[1,0]
	v_pk_mul_f32 v[106:107], v[100:101], v[116:117] op_sel_hi:[1,0]
	v_pk_mul_f32 v[100:101], v[98:99], v[116:117] op_sel_hi:[1,0]
	v_cvt_pk_bf16_f32 v98, v102, v103
	v_cvt_pk_bf16_f32 v99, v104, v105
	v_cvt_pk_bf16_f32 v100, v100, v101
	v_cvt_pk_bf16_f32 v101, v106, v107
	global_store_dwordx4 v[114:115], v[98:101], off offset:256
	ds_read2_b32 v[100:101], v164 offset0:32 offset1:48
	s_and_b64 vcc, exec, s[40:41]
	v_or_b32_e32 v98, 32, v157
	v_mad_i64_i32 v[98:99], s[48:49], v98, s36, v[148:149]
	s_waitcnt lgkmcnt(0)
; DI unsigned pk2(float lo, float hi) { f32x2 v = {lo, hi}; bf2_t r = __builtin_convertvector(v, bf2_t); return __builtin_bit_cast(unsigned, r); }
; #define PG8_WAIT_V(n) asm volatile("s_waitcnt vmcnt(" #n ")" ::: "memory")
; #define PG8_BAR __builtin_amdgcn_s_barrier()
;   DI void operator()(const f32x4 (&acc)[2][2][4][2], const Unit& u, int wr, int wc, int fr, int fq, const PG8_LAS float* sR) const {
;     ...
;     const int col0 = u.pn * BM + wc * 32 + 8 * fq;
; #pragma unroll
;     for (int ai = 0; ai < 2; ++ai)
; #pragma unroll
;       for (int m = 0; m < 4; ++m) {
;         bf16_t* rowp = C + (size_t)(row0 + ai * HALF + m * 16) * ldc + col0;
;         const float rs = sR[ai * 128 + m * 16 + fr];
; #pragma unroll
;         for (int bj = 0; bj < 2; ++bj) {
;           const f32x4 v0 = acc[ai][bj][m][0] * rs, v1 = acc[ai][bj][m][1] * rs;
;           u32x4 w; w[0] = pk2(v0[0], v0[1]); w[1] = pk2(v0[2], v0[3]); w[2] = pk2(v1[0], v1[1]); w[3] = pk2(v1[2], v1[3]);
;           *(u32x4*)(rowp + bj * HALF) = w;
;         }
;       }
; template <class Epi>
; DI void gemm_phase(PG8_LAS unsigned char* lds, const Gemm g, const StaticOrder& S, const Epi& E) {
;     ...
;     if (!has_next) break;
; #pragma unroll
;     for (int a = 0; a < 2; ++a)
; #pragma unroll
;       for (int b = 0; b < 2; ++b)
; #pragma unroll
;         for (int m = 0; m < 4; ++m)
; #pragma unroll
;           for (int n = 0; n < 2; ++n) acc[a][b][m][n] = (f32x4){0.f, 0.f, 0.f, 0.f};
;     cur = nxt; cA = nA; cB = nB; ++ui;
;   }
;   PG8_WAIT_V(0);
;   if (wr == 0) PG8_BAR;
;   PG8_BAR;
	v_pk_mul_f32 v[96:97], v[96:97], v[100:101] op_sel_hi:[1,0]
	v_pk_mul_f32 v[94:95], v[94:95], v[100:101] op_sel_hi:[1,0]
	v_pk_mul_f32 v[102:103], v[92:93], v[100:101] op_sel_hi:[1,0]
	v_pk_mul_f32 v[92:93], v[90:91], v[100:101] op_sel_hi:[1,0]
	v_lshl_add_u64 v[98:99], v[98:99], 0, v[150:151]
	v_cvt_pk_bf16_f32 v90, v94, v95
	v_cvt_pk_bf16_f32 v91, v96, v97
	v_cvt_pk_bf16_f32 v92, v92, v93
	v_cvt_pk_bf16_f32 v93, v102, v103
	global_store_dwordx4 v[98:99], v[90:93], off
	v_pk_mul_f32 v[84:85], v[84:85], v[100:101] op_sel_hi:[1,0]
	v_pk_mul_f32 v[82:83], v[82:83], v[100:101] op_sel_hi:[1,0]
	v_pk_mul_f32 v[90:91], v[76:77], v[100:101] op_sel_hi:[1,0]
	v_pk_mul_f32 v[76:77], v[74:75], v[100:101] op_sel_hi:[1,0]
	v_cvt_pk_bf16_f32 v74, v82, v83
	v_cvt_pk_bf16_f32 v75, v84, v85
	v_cvt_pk_bf16_f32 v76, v76, v77
	v_cvt_pk_bf16_f32 v77, v90, v91
	global_store_dwordx4 v[98:99], v[74:77], off offset:256
	v_mov_b32_e32 v84, v101
	v_pk_mul_f32 v[80:81], v[80:81], v[84:85] op_sel_hi:[1,0]
	v_or_b32_e32 v74, 48, v157
	v_mad_i64_i32 v[74:75], s[48:49], v74, s36, v[148:149]
	v_lshl_add_u64 v[82:83], v[74:75], 0, v[150:151]
	v_pk_mul_f32 v[76:77], v[88:89], v[84:85] op_sel_hi:[1,0]
	v_pk_mul_f32 v[74:75], v[86:87], v[84:85] op_sel_hi:[1,0]
	v_pk_mul_f32 v[78:79], v[78:79], v[84:85] op_sel_hi:[1,0]
	v_cvt_pk_bf16_f32 v74, v74, v75
	v_cvt_pk_bf16_f32 v75, v76, v77
	v_cvt_pk_bf16_f32 v76, v78, v79
	v_cvt_pk_bf16_f32 v77, v80, v81
	global_store_dwordx4 v[82:83], v[74:77], off
	v_pk_mul_f32 v[72:73], v[72:73], v[84:85] op_sel_hi:[1,0]
	v_pk_mul_f32 v[70:71], v[70:71], v[84:85] op_sel_hi:[1,0]
	v_pk_mul_f32 v[74:75], v[68:69], v[84:85] op_sel_hi:[1,0]
	v_pk_mul_f32 v[68:69], v[66:67], v[84:85] op_sel_hi:[1,0]
	v_cvt_pk_bf16_f32 v66, v70, v71
	v_cvt_pk_bf16_f32 v67, v72, v73
	v_cvt_pk_bf16_f32 v68, v68, v69
	v_cvt_pk_bf16_f32 v69, v74, v75
	global_store_dwordx4 v[82:83], v[66:69], off offset:256
	ds_read2_b32 v[68:69], v164 offset0:128 offset1:144
	s_mov_b32 s60, s30
	v_add_u32_e32 v66, 0x80, v157
	v_mad_i64_i32 v[66:67], s[48:49], v66, s36, v[148:149]
	s_waitcnt lgkmcnt(0)
	v_pk_mul_f32 v[64:65], v[64:65], v[68:69] op_sel_hi:[1,0]
	v_pk_mul_f32 v[62:63], v[62:63], v[68:69] op_sel_hi:[1,0]
	v_pk_mul_f32 v[70:71], v[60:61], v[68:69] op_sel_hi:[1,0]
	v_pk_mul_f32 v[60:61], v[58:59], v[68:69] op_sel_hi:[1,0]
	v_lshl_add_u64 v[66:67], v[66:67], 0, v[150:151]
	v_cvt_pk_bf16_f32 v58, v62, v63
	v_cvt_pk_bf16_f32 v59, v64, v65
	v_cvt_pk_bf16_f32 v60, v60, v61
	v_cvt_pk_bf16_f32 v61, v70, v71
	global_store_dwordx4 v[66:67], v[58:61], off
	v_pk_mul_f32 v[52:53], v[52:53], v[68:69] op_sel_hi:[1,0]
	v_pk_mul_f32 v[50:51], v[50:51], v[68:69] op_sel_hi:[1,0]
	v_pk_mul_f32 v[58:59], v[44:45], v[68:69] op_sel_hi:[1,0]
	v_pk_mul_f32 v[44:45], v[42:43], v[68:69] op_sel_hi:[1,0]
	v_cvt_pk_bf16_f32 v42, v50, v51
	v_cvt_pk_bf16_f32 v43, v52, v53
	v_cvt_pk_bf16_f32 v44, v44, v45
	v_cvt_pk_bf16_f32 v45, v58, v59
	global_store_dwordx4 v[66:67], v[42:45], off offset:256
	v_mov_b32_e32 v52, v69
	v_pk_mul_f32 v[48:49], v[48:49], v[52:53] op_sel_hi:[1,0]
	v_add_u32_e32 v42, 0x90, v157
	v_mad_i64_i32 v[42:43], s[48:49], v42, s36, v[148:149]
	v_lshl_add_u64 v[50:51], v[42:43], 0, v[150:151]
	v_pk_mul_f32 v[44:45], v[56:57], v[52:53] op_sel_hi:[1,0]
	v_pk_mul_f32 v[42:43], v[54:55], v[52:53] op_sel_hi:[1,0]
	v_pk_mul_f32 v[46:47], v[46:47], v[52:53] op_sel_hi:[1,0]
	v_cvt_pk_bf16_f32 v42, v42, v43
	v_cvt_pk_bf16_f32 v43, v44, v45
	v_cvt_pk_bf16_f32 v44, v46, v47
	v_cvt_pk_bf16_f32 v45, v48, v49
	global_store_dwordx4 v[50:51], v[42:45], off
	v_pk_mul_f32 v[40:41], v[40:41], v[52:53] op_sel_hi:[1,0]
	v_pk_mul_f32 v[38:39], v[38:39], v[52:53] op_sel_hi:[1,0]
	v_pk_mul_f32 v[42:43], v[36:37], v[52:53] op_sel_hi:[1,0]
	v_pk_mul_f32 v[36:37], v[34:35], v[52:53] op_sel_hi:[1,0]
	v_cvt_pk_bf16_f32 v34, v38, v39
	v_cvt_pk_bf16_f32 v35, v40, v41
	v_cvt_pk_bf16_f32 v36, v36, v37
	v_cvt_pk_bf16_f32 v37, v42, v43
	global_store_dwordx4 v[50:51], v[34:37], off offset:256
	ds_read2_b32 v[36:37], v164 offset0:160 offset1:176
	s_mov_b32 s62, s42
	v_add_u32_e32 v34, 0xa0, v157
	v_mad_i64_i32 v[34:35], s[48:49], v34, s36, v[148:149]
	s_waitcnt lgkmcnt(0)
	v_pk_mul_f32 v[32:33], v[32:33], v[36:37] op_sel_hi:[1,0]
	v_pk_mul_f32 v[30:31], v[30:31], v[36:37] op_sel_hi:[1,0]
	v_pk_mul_f32 v[38:39], v[28:29], v[36:37] op_sel_hi:[1,0]
	v_pk_mul_f32 v[28:29], v[26:27], v[36:37] op_sel_hi:[1,0]
	v_lshl_add_u64 v[34:35], v[34:35], 0, v[150:151]
	v_cvt_pk_bf16_f32 v26, v30, v31
	v_cvt_pk_bf16_f32 v27, v32, v33
	v_cvt_pk_bf16_f32 v28, v28, v29
	v_cvt_pk_bf16_f32 v29, v38, v39
	global_store_dwordx4 v[34:35], v[26:29], off
	v_pk_mul_f32 v[20:21], v[20:21], v[36:37] op_sel_hi:[1,0]
	v_pk_mul_f32 v[18:19], v[18:19], v[36:37] op_sel_hi:[1,0]
	v_pk_mul_f32 v[26:27], v[12:13], v[36:37] op_sel_hi:[1,0]
	v_pk_mul_f32 v[12:13], v[10:11], v[36:37] op_sel_hi:[1,0]
	v_cvt_pk_bf16_f32 v10, v18, v19
	v_cvt_pk_bf16_f32 v11, v20, v21
	v_cvt_pk_bf16_f32 v12, v12, v13
	v_cvt_pk_bf16_f32 v13, v26, v27
	global_store_dwordx4 v[34:35], v[10:13], off offset:256
	v_mov_b32_e32 v20, v37
	v_pk_mul_f32 v[16:17], v[16:17], v[20:21] op_sel_hi:[1,0]
	v_add_u32_e32 v10, 0xb0, v157
	v_mad_i64_i32 v[10:11], s[48:49], v10, s36, v[148:149]
	v_lshl_add_u64 v[18:19], v[10:11], 0, v[150:151]
	v_pk_mul_f32 v[12:13], v[24:25], v[20:21] op_sel_hi:[1,0]
	v_pk_mul_f32 v[10:11], v[22:23], v[20:21] op_sel_hi:[1,0]
	v_pk_mul_f32 v[14:15], v[14:15], v[20:21] op_sel_hi:[1,0]
	v_cvt_pk_bf16_f32 v10, v10, v11
	v_cvt_pk_bf16_f32 v11, v12, v13
	v_cvt_pk_bf16_f32 v12, v14, v15
	v_cvt_pk_bf16_f32 v13, v16, v17
	global_store_dwordx4 v[18:19], v[10:13], off
	v_pk_mul_f32 v[8:9], v[8:9], v[20:21] op_sel_hi:[1,0]
	v_pk_mul_f32 v[6:7], v[6:7], v[20:21] op_sel_hi:[1,0]
	v_pk_mul_f32 v[10:11], v[4:5], v[20:21] op_sel_hi:[1,0]
	v_pk_mul_f32 v[4:5], v[2:3], v[20:21] op_sel_hi:[1,0]
	v_cvt_pk_bf16_f32 v2, v6, v7
	v_cvt_pk_bf16_f32 v3, v8, v9
	v_cvt_pk_bf16_f32 v4, v4, v5
	v_cvt_pk_bf16_f32 v5, v10, v11
	s_mov_b64 s[50:51], s[46:47]
	s_mov_b64 s[48:49], s[44:45]
	s_mov_b32 s61, s59
	v_readlane_b32 s5, v253, 17
	v_readlane_b32 s6, v253, 18
	v_readlane_b32 s7, v253, 19
	v_readlane_b32 s8, v253, 20
	v_readlane_b32 s9, v253, 21
	v_readlane_b32 s10, v253, 22
	v_readlane_b32 s11, v253, 23
	v_readlane_b32 s12, v253, 24
	v_readlane_b32 s13, v253, 25
	v_readlane_b32 s14, v253, 26
	v_readlane_b32 s15, v253, 27
	v_readlane_b32 s16, v253, 28
	v_readlane_b32 s17, v253, 29
	global_store_dwordx4 v[18:19], v[2:5], off offset:256
	s_cbranch_vccz .LBB0_1194
	s_waitcnt vmcnt(0)
	s_cmpk_gt_u32 s28, 0xff
	s_cbranch_scc1 .LBB0_1201
	s_barrier
